# weight conversion: tile order permuted so that each workgroup's consecutive tiles are adjacent along the source rows (contiguous reads per row), same tiles overall
# baseline (speedup 1.0000x reference)
;     ...
;     const int first = ((int)blockIdx.x + rot) % (int)gridDim.x;
;     for (int t_ = first; t_ < ntile * ((REP & 1) + 1); t_ += gridDim.x) { const int t = t_ % ntile;
;         const int r0 = (t / nkt) * 64, k0 = (t % nkt) * 64;
;         __syncthreads();
; #pragma unroll
;         for (int i = 0; i < 8; ++i) { const int kk = i * 8 + w; tile[kk * 65 + lane] = src(k0 + kk, r0 + lane); }
; __device__ void convert_phase(unsigned char* smem, const Params& p, int l) {
;     ...
;       conv_tiles(tile, wt + W_UP1, 5632, 1024, 0, [=](int k, int r) { const int col = (r >> 5) * 16 + (r & 15); return gn[k] * (((r >> 4) & 1) ? wu[(size_t)k * DFF + col] : wg[(size_t)k * DFF + col]); }); }
.LBB0_307:
	s_mov_b32 s98, s11
	s_lshr_b32 s99, s98, 8
	s_and_b32 s100, s98, 0xff
	s_mul_i32 s101, s100, 6
	s_sub_i32 s98, s100, 128
	s_mul_i32 s98, s98, 5
	s_add_i32 s98, s98, 768
	s_cmp_lt_u32 s100, 128
	s_cselect_b32 s98, s101, s98
	s_add_i32 s98, s98, s99
	s_mul_hi_u32 s99, s98, 0x2e8ba2f
	s_mul_i32 s100, s99, 88
	s_sub_i32 s98, s98, s100
	s_mul_i32 s98, s98, 16
	s_add_i32 s98, s98, s99
	s_mul_hi_i32 s8, s98, 0x2e8ba2e9
	s_lshr_b32 s9, s8, 31
	s_ashr_i32 s8, s8, 8
	s_add_i32 s8, s8, s9
	s_mulk_i32 s8, 0x580
	s_sub_i32 s8, s98, s8
	s_sext_i32_i16 s9, s8
	s_bfe_u32 s9, s9, 0x4001b
	s_add_i32 s9, s8, s9
	s_sext_i32_i16 s16, s9
	s_and_b32 s9, s9, 0xfff0
	s_lshl_b32 s16, s16, 2
	s_sub_i32 s8, s8, s9
	s_and_b32 s9, s16, 0xffffffc0
	v_or_b32_e32 v16, s9, v4
	s_sext_i32_i16 s8, s8
	v_ashrrev_i32_e32 v17, 1, v16
	s_lshl_b32 s8, s8, 6
	v_and_or_b32 v18, v17, -16, v6
	v_add_u32_e32 v16, s8, v5
	v_ashrrev_i32_e32 v19, 31, v18
	v_ashrrev_i32_e32 v17, 31, v16
	v_lshl_add_u64 v[18:19], v[18:19], 2, v[0:1]
	v_add_u32_e32 v22, s8, v8
	v_add_u32_e32 v23, s8, v9
	v_add_u32_e32 v24, s8, v10
	v_add_u32_e32 v26, s8, v11
	v_add_u32_e32 v28, s8, v12
	v_add_u32_e32 v30, s8, v13
	v_add_u32_e32 v32, s8, v14
	v_lshl_add_u64 v[20:21], v[16:17], 2, s[6:7]
	v_mad_i64_i32 v[16:17], s[16:17], v16, s33, v[18:19]
	global_load_dword v34, v[20:21], off
	global_load_dword v35, v[20:21], off offset:32
	global_load_dword v36, v[20:21], off offset:64
	global_load_dword v37, v[20:21], off offset:96
	global_load_dword v38, v[20:21], off offset:128
	global_load_dword v39, v[20:21], off offset:160
	global_load_dword v40, v[20:21], off offset:192
	global_load_dword v41, v[20:21], off offset:224
	v_mad_i64_i32 v[20:21], s[16:17], v22, s33, v[18:19]
	v_mad_i64_i32 v[22:23], s[16:17], v23, s33, v[18:19]
	v_mad_i64_i32 v[24:25], s[16:17], v24, s33, v[18:19]
	v_mad_i64_i32 v[26:27], s[16:17], v26, s33, v[18:19]
	v_mad_i64_i32 v[28:29], s[16:17], v28, s33, v[18:19]
	v_mad_i64_i32 v[30:31], s[16:17], v30, s33, v[18:19]
	v_mad_i64_i32 v[18:19], s[16:17], v32, s33, v[18:19]
	global_load_dword v42, v[16:17], off
	global_load_dword v43, v[20:21], off
	global_load_dword v44, v[22:23], off
	global_load_dword v45, v[24:25], off
	global_load_dword v46, v[26:27], off
	global_load_dword v47, v[28:29], off
	global_load_dword v48, v[30:31], off
	global_load_dword v49, v[18:19], off
	v_add_u32_e32 v16, s9, v5
	v_add_u32_e32 v18, s9, v8
	v_add_u32_e32 v20, s9, v9
	v_add_u32_e32 v22, s9, v10
	v_add_u32_e32 v24, s9, v11
	v_add_u32_e32 v26, s9, v12
	v_add_u32_e32 v28, s9, v13
	v_add_u32_e32 v30, s9, v14
	s_ashr_i32 s9, s8, 31
	v_ashrrev_i32_e32 v17, 31, v16
	v_ashrrev_i32_e32 v19, 31, v18
	v_ashrrev_i32_e32 v21, 31, v20
	v_ashrrev_i32_e32 v23, 31, v22
	v_ashrrev_i32_e32 v25, 31, v24
	v_ashrrev_i32_e32 v27, 31, v26
	v_ashrrev_i32_e32 v29, 31, v28
	v_ashrrev_i32_e32 v31, 31, v30
	v_lshl_add_u64 v[32:33], s[8:9], 1, v[2:3]
	v_lshlrev_b64 v[16:17], 11, v[16:17]
	v_lshlrev_b64 v[18:19], 11, v[18:19]
	v_lshlrev_b64 v[20:21], 11, v[20:21]
	v_lshlrev_b64 v[22:23], 11, v[22:23]
	v_lshlrev_b64 v[24:25], 11, v[24:25]
	v_lshlrev_b64 v[26:27], 11, v[26:27]
	v_lshlrev_b64 v[28:29], 11, v[28:29]
	v_lshlrev_b64 v[30:31], 11, v[30:31]
	v_lshl_add_u64 v[16:17], v[32:33], 0, v[16:17]
	v_lshl_add_u64 v[18:19], v[32:33], 0, v[18:19]
	v_lshl_add_u64 v[20:21], v[32:33], 0, v[20:21]
	v_lshl_add_u64 v[22:23], v[32:33], 0, v[22:23]
	v_lshl_add_u64 v[24:25], v[32:33], 0, v[24:25]
	v_lshl_add_u64 v[26:27], v[32:33], 0, v[26:27]
	v_lshl_add_u64 v[28:29], v[32:33], 0, v[28:29]
	v_lshl_add_u64 v[30:31], v[32:33], 0, v[30:31]
	s_add_i32 s98, s11, s5
	s_cmp_lt_i32 s98, 0x580
	s_cbranch_scc0 .Lcv307_p1skip
;     ...
;     for (int t_ = first; t_ < ntile * ((REP & 1) + 1); t_ += gridDim.x) { const int t = t_ % ntile;
;         const int r0 = (t / nkt) * 64, k0 = (t % nkt) * 64;
;         __syncthreads();
; #pragma unroll
;         for (int i = 0; i < 8; ++i) { const int kk = i * 8 + w; tile[kk * 65 + lane] = src(k0 + kk, r0 + lane); }
; __device__ void convert_phase(unsigned char* smem, const Params& p, int l) {
;     ...
;       conv_tiles(tile, wt + W_UP1, 5632, 1024, 0, [=](int k, int r) { const int col = (r >> 5) * 16 + (r & 15); return gn[k] * (((r >> 4) & 1) ? wu[(size_t)k * DFF + col] : wg[(size_t)k * DFF + col]); }); }
	s_lshr_b32 s99, s98, 8
	s_and_b32 s100, s98, 0xff
	s_mul_i32 s101, s100, 6
	s_sub_i32 s98, s100, 128
	s_mul_i32 s98, s98, 5
	s_add_i32 s98, s98, 768
	s_cmp_lt_u32 s100, 128
	s_cselect_b32 s98, s101, s98
	s_add_i32 s98, s98, s99
	s_mul_hi_u32 s99, s98, 0x2e8ba2f
	s_mul_i32 s100, s99, 88
	s_sub_i32 s98, s98, s100
	s_mul_i32 s98, s98, 16
	s_add_i32 s98, s98, s99
	s_mul_hi_i32 s8, s98, 0x2e8ba2e9
	s_lshr_b32 s9, s8, 31
	s_ashr_i32 s8, s8, 8
	s_add_i32 s8, s8, s9
	s_mulk_i32 s8, 0x580
	s_sub_i32 s8, s98, s8
	s_sext_i32_i16 s9, s8
	s_bfe_u32 s9, s9, 0x4001b
	s_add_i32 s9, s8, s9
	s_sext_i32_i16 s16, s9
	s_and_b32 s9, s9, 0xfff0
	s_lshl_b32 s16, s16, 2
	s_sub_i32 s8, s8, s9
	s_and_b32 s9, s16, 0xffffffc0
	v_or_b32_e32 v56, s9, v4
	s_sext_i32_i16 s8, s8
	v_ashrrev_i32_e32 v57, 1, v56
	s_lshl_b32 s8, s8, 6
	v_and_or_b32 v58, v57, -16, v6
	v_add_u32_e32 v56, s8, v5
	v_ashrrev_i32_e32 v59, 31, v58
	v_ashrrev_i32_e32 v57, 31, v56
	v_lshl_add_u64 v[58:59], v[58:59], 2, v[0:1]
	v_add_u32_e32 v62, s8, v8
	v_add_u32_e32 v63, s8, v9
	v_add_u32_e32 v64, s8, v10
	v_add_u32_e32 v66, s8, v11
	v_add_u32_e32 v68, s8, v12
	v_add_u32_e32 v70, s8, v13
	v_add_u32_e32 v72, s8, v14
	v_lshl_add_u64 v[60:61], v[56:57], 2, s[6:7]
	v_mad_i64_i32 v[56:57], s[16:17], v56, s33, v[58:59]
	global_load_dword v74, v[60:61], off
	global_load_dword v75, v[60:61], off offset:32
	global_load_dword v76, v[60:61], off offset:64
	global_load_dword v77, v[60:61], off offset:96
	global_load_dword v78, v[60:61], off offset:128
	global_load_dword v79, v[60:61], off offset:160
	global_load_dword v80, v[60:61], off offset:192
	global_load_dword v81, v[60:61], off offset:224
	v_mad_i64_i32 v[60:61], s[16:17], v62, s33, v[58:59]
	v_mad_i64_i32 v[62:63], s[16:17], v63, s33, v[58:59]
	v_mad_i64_i32 v[64:65], s[16:17], v64, s33, v[58:59]
	v_mad_i64_i32 v[66:67], s[16:17], v66, s33, v[58:59]
	v_mad_i64_i32 v[68:69], s[16:17], v68, s33, v[58:59]
	v_mad_i64_i32 v[70:71], s[16:17], v70, s33, v[58:59]
	v_mad_i64_i32 v[58:59], s[16:17], v72, s33, v[58:59]
	global_load_dword v82, v[56:57], off
	global_load_dword v83, v[60:61], off
	global_load_dword v84, v[62:63], off
	global_load_dword v85, v[64:65], off
	global_load_dword v86, v[66:67], off
	global_load_dword v87, v[68:69], off
	global_load_dword v88, v[70:71], off
	global_load_dword v89, v[58:59], off
	v_add_u32_e32 v56, s9, v5
	v_add_u32_e32 v58, s9, v8
	v_add_u32_e32 v60, s9, v9
	v_add_u32_e32 v62, s9, v10
	v_add_u32_e32 v64, s9, v11
	v_add_u32_e32 v66, s9, v12
	v_add_u32_e32 v68, s9, v13
	v_add_u32_e32 v70, s9, v14
	s_ashr_i32 s9, s8, 31
	v_ashrrev_i32_e32 v57, 31, v56
	v_ashrrev_i32_e32 v59, 31, v58
	v_ashrrev_i32_e32 v61, 31, v60
	v_ashrrev_i32_e32 v63, 31, v62
	v_ashrrev_i32_e32 v65, 31, v64
	v_ashrrev_i32_e32 v67, 31, v66
	v_ashrrev_i32_e32 v69, 31, v68
	v_ashrrev_i32_e32 v71, 31, v70
	v_lshl_add_u64 v[72:73], s[8:9], 1, v[2:3]
	v_lshlrev_b64 v[56:57], 11, v[56:57]
	v_lshlrev_b64 v[58:59], 11, v[58:59]
	v_lshlrev_b64 v[60:61], 11, v[60:61]
	v_lshlrev_b64 v[62:63], 11, v[62:63]
	v_lshlrev_b64 v[64:65], 11, v[64:65]
	v_lshlrev_b64 v[66:67], 11, v[66:67]
	v_lshlrev_b64 v[68:69], 11, v[68:69]
	v_lshlrev_b64 v[70:71], 11, v[70:71]
	v_lshl_add_u64 v[56:57], v[72:73], 0, v[56:57]
	v_lshl_add_u64 v[58:59], v[72:73], 0, v[58:59]
	v_lshl_add_u64 v[60:61], v[72:73], 0, v[60:61]
	v_lshl_add_u64 v[62:63], v[72:73], 0, v[62:63]
	v_lshl_add_u64 v[64:65], v[72:73], 0, v[64:65]
	v_lshl_add_u64 v[66:67], v[72:73], 0, v[66:67]
	v_lshl_add_u64 v[68:69], v[72:73], 0, v[68:69]
	v_lshl_add_u64 v[70:71], v[72:73], 0, v[70:71]
	s_waitcnt vmcnt(16)
	s_branch .Lcv307_pj

; __device__ __forceinline__ bf16_t f2bf(float f) { unsigned u = __float_as_uint(f); u += 0x7FFFu + ((u >> 16) & 1u); return (bf16_t)(u >> 16); }
;     ...
;     for (int t_ = first; t_ < ntile * ((REP & 1) + 1); t_ += gridDim.x) { const int t = t_ % ntile;
;         const int r0 = (t / nkt) * 64, k0 = (t % nkt) * 64;
;         __syncthreads();
; #pragma unroll
;         for (int i = 0; i < 8; ++i) { const int kk = i * 8 + w; tile[kk * 65 + lane] = src(k0 + kk, r0 + lane); }
;         __syncthreads();
; #pragma unroll
;         for (int i = 0; i < 8; ++i) { const int j = i * 8 + w; Bt[(size_t)(r0 + j) * ld + k0 + lane] = f2bf(tile[lane * 65 + j]); }
;     }
; __device__ void convert_phase(unsigned char* smem, const Params& p, int l) {
;     ...
;       conv_tiles(tile, wt + W_UP1, 5632, 1024, 0, [=](int k, int r) { const int col = (r >> 5) * 16 + (r & 15); return gn[k] * (((r >> 4) & 1) ? wu[(size_t)k * DFF + col] : wg[(size_t)k * DFF + col]); }); }
.Lcv307_top:
	s_waitcnt vmcnt(31)
	v_mul_f32_e32 v32, v34, v42
	s_waitcnt vmcnt(30)
	v_mul_f32_e32 v33, v35, v43
	s_waitcnt vmcnt(29)
	v_mul_f32_e32 v34, v36, v44
	s_waitcnt vmcnt(28)
	v_mul_f32_e32 v35, v37, v45
	s_waitcnt vmcnt(27)
	v_mul_f32_e32 v36, v38, v46
	s_waitcnt vmcnt(26)
	v_mul_f32_e32 v37, v39, v47
	s_waitcnt vmcnt(25)
	v_mul_f32_e32 v38, v40, v48
	s_waitcnt vmcnt(24)
	v_mul_f32_e32 v39, v41, v49
	ds_write_b32 v15, v32
	ds_write_b32 v15, v33 offset:2080
	ds_write_b32 v15, v34 offset:4160
	ds_write_b32 v15, v35 offset:6240
	ds_write_b32 v15, v36 offset:8320
	ds_write_b32 v15, v37 offset:10400
	ds_write_b32 v15, v38 offset:12480
	ds_write_b32 v15, v39 offset:14560
	s_waitcnt lgkmcnt(0)
	s_barrier
	ds_read2_b32 v[32:33], v7 offset1:8
	ds_read2_b32 v[34:35], v7 offset0:16 offset1:24
	ds_read2_b32 v[36:37], v7 offset0:32 offset1:40
	ds_read2_b32 v[38:39], v7 offset0:48 offset1:56
	s_waitcnt lgkmcnt(3)
	v_bfe_u32 v40, v32, 16, 1
	v_bfe_u32 v41, v33, 16, 1
	s_waitcnt lgkmcnt(2)
	v_bfe_u32 v42, v34, 16, 1
	v_bfe_u32 v43, v35, 16, 1
	s_waitcnt lgkmcnt(1)
	v_bfe_u32 v44, v36, 16, 1
	v_bfe_u32 v45, v37, 16, 1
	s_waitcnt lgkmcnt(0)
	v_bfe_u32 v46, v38, 16, 1
	v_bfe_u32 v47, v39, 16, 1
	v_add3_u32 v32, v32, v40, s88
	v_add3_u32 v33, v33, v41, s88
	v_add3_u32 v34, v34, v42, s88
	v_add3_u32 v35, v35, v43, s88
	v_add3_u32 v36, v36, v44, s88
	v_add3_u32 v37, v37, v45, s88
	v_add3_u32 v38, v38, v46, s88
	v_add3_u32 v39, v39, v47, s88
	global_store_short_d16_hi v[16:17], v32, off
	global_store_short_d16_hi v[18:19], v33, off
	global_store_short_d16_hi v[20:21], v34, off
	global_store_short_d16_hi v[22:23], v35, off
	global_store_short_d16_hi v[24:25], v36, off
	global_store_short_d16_hi v[26:27], v37, off
	global_store_short_d16_hi v[28:29], v38, off
	global_store_short_d16_hi v[30:31], v39, off
	s_lshl_b32 s98, s5, 1
	s_add_i32 s98, s98, s11
	s_cmp_lt_i32 s98, 0x580
	s_cbranch_scc0 .Lcv307_s0
	s_lshr_b32 s99, s98, 8
	s_and_b32 s100, s98, 0xff
	s_mul_i32 s101, s100, 6
	s_sub_i32 s98, s100, 128
	s_mul_i32 s98, s98, 5
	s_add_i32 s98, s98, 768
	s_cmp_lt_u32 s100, 128
	s_cselect_b32 s98, s101, s98
	s_add_i32 s98, s98, s99
	s_mul_hi_u32 s99, s98, 0x2e8ba2f
	s_mul_i32 s100, s99, 88
	s_sub_i32 s98, s98, s100
	s_mul_i32 s98, s98, 16
	s_add_i32 s98, s98, s99
	s_mul_hi_i32 s8, s98, 0x2e8ba2e9
	s_lshr_b32 s9, s8, 31
	s_ashr_i32 s8, s8, 8
	s_add_i32 s8, s8, s9
	s_mulk_i32 s8, 0x580
	s_sub_i32 s8, s98, s8
	s_sext_i32_i16 s9, s8
	s_bfe_u32 s9, s9, 0x4001b
	s_add_i32 s9, s8, s9
	s_sext_i32_i16 s16, s9
	s_and_b32 s9, s9, 0xfff0
	s_lshl_b32 s16, s16, 2
	s_sub_i32 s8, s8, s9
	s_and_b32 s9, s16, 0xffffffc0
	v_or_b32_e32 v16, s9, v4
	s_sext_i32_i16 s8, s8
	v_ashrrev_i32_e32 v17, 1, v16
	s_lshl_b32 s8, s8, 6
	v_and_or_b32 v18, v17, -16, v6
	v_add_u32_e32 v16, s8, v5
	v_ashrrev_i32_e32 v19, 31, v18
	v_ashrrev_i32_e32 v17, 31, v16
	v_lshl_add_u64 v[18:19], v[18:19], 2, v[0:1]
	v_add_u32_e32 v22, s8, v8
	v_add_u32_e32 v23, s8, v9
	v_add_u32_e32 v24, s8, v10
	v_add_u32_e32 v26, s8, v11
	v_add_u32_e32 v28, s8, v12
	v_add_u32_e32 v30, s8, v13
	v_add_u32_e32 v32, s8, v14
	v_lshl_add_u64 v[20:21], v[16:17], 2, s[6:7]
	v_mad_i64_i32 v[16:17], s[16:17], v16, s33, v[18:19]
	global_load_dword v34, v[20:21], off
	global_load_dword v35, v[20:21], off offset:32
	global_load_dword v36, v[20:21], off offset:64
	global_load_dword v37, v[20:21], off offset:96
	global_load_dword v38, v[20:21], off offset:128
	global_load_dword v39, v[20:21], off offset:160
	global_load_dword v40, v[20:21], off offset:192
	global_load_dword v41, v[20:21], off offset:224
	v_mad_i64_i32 v[20:21], s[16:17], v22, s33, v[18:19]
	v_mad_i64_i32 v[22:23], s[16:17], v23, s33, v[18:19]
	v_mad_i64_i32 v[24:25], s[16:17], v24, s33, v[18:19]
	v_mad_i64_i32 v[26:27], s[16:17], v26, s33, v[18:19]
	v_mad_i64_i32 v[28:29], s[16:17], v28, s33, v[18:19]
	v_mad_i64_i32 v[30:31], s[16:17], v30, s33, v[18:19]
	v_mad_i64_i32 v[18:19], s[16:17], v32, s33, v[18:19]
	global_load_dword v42, v[16:17], off
	global_load_dword v43, v[20:21], off
	global_load_dword v44, v[22:23], off
	global_load_dword v45, v[24:25], off
	global_load_dword v46, v[26:27], off
	global_load_dword v47, v[28:29], off
	global_load_dword v48, v[30:31], off
	global_load_dword v49, v[18:19], off
	v_add_u32_e32 v16, s9, v5
	v_add_u32_e32 v18, s9, v8
	v_add_u32_e32 v20, s9, v9
	v_add_u32_e32 v22, s9, v10
	v_add_u32_e32 v24, s9, v11
	v_add_u32_e32 v26, s9, v12
	v_add_u32_e32 v28, s9, v13
	v_add_u32_e32 v30, s9, v14
	s_ashr_i32 s9, s8, 31
	v_ashrrev_i32_e32 v17, 31, v16
	v_ashrrev_i32_e32 v19, 31, v18
	v_ashrrev_i32_e32 v21, 31, v20
	v_ashrrev_i32_e32 v23, 31, v22
	v_ashrrev_i32_e32 v25, 31, v24
	v_ashrrev_i32_e32 v27, 31, v26
	v_ashrrev_i32_e32 v29, 31, v28
	v_ashrrev_i32_e32 v31, 31, v30
	v_lshl_add_u64 v[32:33], s[8:9], 1, v[2:3]
	v_lshlrev_b64 v[16:17], 11, v[16:17]
	v_lshlrev_b64 v[18:19], 11, v[18:19]
	v_lshlrev_b64 v[20:21], 11, v[20:21]
	v_lshlrev_b64 v[22:23], 11, v[22:23]
	v_lshlrev_b64 v[24:25], 11, v[24:25]
	v_lshlrev_b64 v[26:27], 11, v[26:27]
	v_lshlrev_b64 v[28:29], 11, v[28:29]
	v_lshlrev_b64 v[30:31], 11, v[30:31]
	v_lshl_add_u64 v[16:17], v[32:33], 0, v[16:17]
	v_lshl_add_u64 v[18:19], v[32:33], 0, v[18:19]
	v_lshl_add_u64 v[20:21], v[32:33], 0, v[20:21]
	v_lshl_add_u64 v[22:23], v[32:33], 0, v[22:23]
	v_lshl_add_u64 v[24:25], v[32:33], 0, v[24:25]
	v_lshl_add_u64 v[26:27], v[32:33], 0, v[26:27]
	v_lshl_add_u64 v[28:29], v[32:33], 0, v[28:29]
	v_lshl_add_u64 v[30:31], v[32:33], 0, v[30:31]
	s_branch .Lcv307_n0

; __device__ __forceinline__ bf16_t f2bf(float f) { unsigned u = __float_as_uint(f); u += 0x7FFFu + ((u >> 16) & 1u); return (bf16_t)(u >> 16); }
;     ...
;     for (int t_ = first; t_ < ntile * ((REP & 1) + 1); t_ += gridDim.x) { const int t = t_ % ntile;
;         const int r0 = (t / nkt) * 64, k0 = (t % nkt) * 64;
;         __syncthreads();
; #pragma unroll
;         for (int i = 0; i < 8; ++i) { const int kk = i * 8 + w; tile[kk * 65 + lane] = src(k0 + kk, r0 + lane); }
;         __syncthreads();
; #pragma unroll
;         for (int i = 0; i < 8; ++i) { const int j = i * 8 + w; Bt[(size_t)(r0 + j) * ld + k0 + lane] = f2bf(tile[lane * 65 + j]); }
;     }
; __device__ void convert_phase(unsigned char* smem, const Params& p, int l) {
;     ...
;       conv_tiles(tile, wt + W_UP1, 5632, 1024, 0, [=](int k, int r) { const int col = (r >> 5) * 16 + (r & 15); return gn[k] * (((r >> 4) & 1) ? wu[(size_t)k * DFF + col] : wg[(size_t)k * DFF + col]); }); }
.Lcv307_n0:
	s_add_i32 s11, s11, s5
	s_cmp_lt_i32 s11, 0x580
	s_cbranch_scc0 .LBB0_308
	s_waitcnt vmcnt(31)
	v_mul_f32_e32 v72, v74, v82
	s_waitcnt vmcnt(30)
	v_mul_f32_e32 v73, v75, v83
	s_waitcnt vmcnt(29)
	v_mul_f32_e32 v74, v76, v84
	s_waitcnt vmcnt(28)
	v_mul_f32_e32 v75, v77, v85
	s_waitcnt vmcnt(27)
	v_mul_f32_e32 v76, v78, v86
	s_waitcnt vmcnt(26)
	v_mul_f32_e32 v77, v79, v87
	s_waitcnt vmcnt(25)
	v_mul_f32_e32 v78, v80, v88
	s_waitcnt vmcnt(24)
	v_mul_f32_e32 v79, v81, v89
	ds_write_b32 v15, v72 offset:17408
	ds_write_b32 v15, v73 offset:19488
	ds_write_b32 v15, v74 offset:21568
	ds_write_b32 v15, v75 offset:23648
	ds_write_b32 v15, v76 offset:25728
	ds_write_b32 v15, v77 offset:27808
	ds_write_b32 v15, v78 offset:29888
	ds_write_b32 v15, v79 offset:31968
	s_waitcnt lgkmcnt(0)
	s_barrier
	ds_read2_b32 v[72:73], v95 offset1:8
	ds_read2_b32 v[74:75], v95 offset0:16 offset1:24
	ds_read2_b32 v[76:77], v95 offset0:32 offset1:40
	ds_read2_b32 v[78:79], v95 offset0:48 offset1:56
	s_waitcnt lgkmcnt(3)
	v_bfe_u32 v80, v72, 16, 1
	v_bfe_u32 v81, v73, 16, 1
	s_waitcnt lgkmcnt(2)
	v_bfe_u32 v82, v74, 16, 1
	v_bfe_u32 v83, v75, 16, 1
	s_waitcnt lgkmcnt(1)
	v_bfe_u32 v84, v76, 16, 1
	v_bfe_u32 v85, v77, 16, 1
	s_waitcnt lgkmcnt(0)
	v_bfe_u32 v86, v78, 16, 1
	v_bfe_u32 v87, v79, 16, 1
	v_add3_u32 v72, v72, v80, s88
	v_add3_u32 v73, v73, v81, s88
	v_add3_u32 v74, v74, v82, s88
	v_add3_u32 v75, v75, v83, s88
	v_add3_u32 v76, v76, v84, s88
	v_add3_u32 v77, v77, v85, s88
	v_add3_u32 v78, v78, v86, s88
	v_add3_u32 v79, v79, v87, s88
	global_store_short_d16_hi v[56:57], v72, off
	global_store_short_d16_hi v[58:59], v73, off
	global_store_short_d16_hi v[60:61], v74, off
	global_store_short_d16_hi v[62:63], v75, off
	global_store_short_d16_hi v[64:65], v76, off
	global_store_short_d16_hi v[66:67], v77, off
	global_store_short_d16_hi v[68:69], v78, off
	global_store_short_d16_hi v[70:71], v79, off
	s_lshl_b32 s98, s5, 1
	s_add_i32 s98, s98, s11
	s_cmp_lt_i32 s98, 0x580
	s_cbranch_scc0 .Lcv307_s1
	s_lshr_b32 s99, s98, 8
	s_and_b32 s100, s98, 0xff
	s_mul_i32 s101, s100, 6
	s_sub_i32 s98, s100, 128
	s_mul_i32 s98, s98, 5
	s_add_i32 s98, s98, 768
	s_cmp_lt_u32 s100, 128
	s_cselect_b32 s98, s101, s98
	s_add_i32 s98, s98, s99
	s_mul_hi_u32 s99, s98, 0x2e8ba2f
	s_mul_i32 s100, s99, 88
	s_sub_i32 s98, s98, s100
	s_mul_i32 s98, s98, 16
	s_add_i32 s98, s98, s99
	s_mul_hi_i32 s8, s98, 0x2e8ba2e9
	s_lshr_b32 s9, s8, 31
	s_ashr_i32 s8, s8, 8
	s_add_i32 s8, s8, s9
	s_mulk_i32 s8, 0x580
	s_sub_i32 s8, s98, s8
	s_sext_i32_i16 s9, s8
	s_bfe_u32 s9, s9, 0x4001b
	s_add_i32 s9, s8, s9
	s_sext_i32_i16 s16, s9
	s_and_b32 s9, s9, 0xfff0
	s_lshl_b32 s16, s16, 2
	s_sub_i32 s8, s8, s9
	s_and_b32 s9, s16, 0xffffffc0
	v_or_b32_e32 v56, s9, v4
	s_sext_i32_i16 s8, s8
	v_ashrrev_i32_e32 v57, 1, v56
	s_lshl_b32 s8, s8, 6
	v_and_or_b32 v58, v57, -16, v6
	v_add_u32_e32 v56, s8, v5
	v_ashrrev_i32_e32 v59, 31, v58
	v_ashrrev_i32_e32 v57, 31, v56
	v_lshl_add_u64 v[58:59], v[58:59], 2, v[0:1]
	v_add_u32_e32 v62, s8, v8
	v_add_u32_e32 v63, s8, v9
	v_add_u32_e32 v64, s8, v10
	v_add_u32_e32 v66, s8, v11
	v_add_u32_e32 v68, s8, v12
	v_add_u32_e32 v70, s8, v13
	v_add_u32_e32 v72, s8, v14
	v_lshl_add_u64 v[60:61], v[56:57], 2, s[6:7]
	v_mad_i64_i32 v[56:57], s[16:17], v56, s33, v[58:59]
	global_load_dword v74, v[60:61], off
	global_load_dword v75, v[60:61], off offset:32
	global_load_dword v76, v[60:61], off offset:64
	global_load_dword v77, v[60:61], off offset:96
	global_load_dword v78, v[60:61], off offset:128
	global_load_dword v79, v[60:61], off offset:160
	global_load_dword v80, v[60:61], off offset:192
	global_load_dword v81, v[60:61], off offset:224
	v_mad_i64_i32 v[60:61], s[16:17], v62, s33, v[58:59]
	v_mad_i64_i32 v[62:63], s[16:17], v63, s33, v[58:59]
	v_mad_i64_i32 v[64:65], s[16:17], v64, s33, v[58:59]
	v_mad_i64_i32 v[66:67], s[16:17], v66, s33, v[58:59]
	v_mad_i64_i32 v[68:69], s[16:17], v68, s33, v[58:59]
	v_mad_i64_i32 v[70:71], s[16:17], v70, s33, v[58:59]
	v_mad_i64_i32 v[58:59], s[16:17], v72, s33, v[58:59]
	global_load_dword v82, v[56:57], off
	global_load_dword v83, v[60:61], off
	global_load_dword v84, v[62:63], off
	global_load_dword v85, v[64:65], off
	global_load_dword v86, v[66:67], off
	global_load_dword v87, v[68:69], off
	global_load_dword v88, v[70:71], off
	global_load_dword v89, v[58:59], off
	v_add_u32_e32 v56, s9, v5
	v_add_u32_e32 v58, s9, v8
	v_add_u32_e32 v60, s9, v9
	v_add_u32_e32 v62, s9, v10
	v_add_u32_e32 v64, s9, v11
	v_add_u32_e32 v66, s9, v12
	v_add_u32_e32 v68, s9, v13
	v_add_u32_e32 v70, s9, v14
	s_ashr_i32 s9, s8, 31
	v_ashrrev_i32_e32 v57, 31, v56
	v_ashrrev_i32_e32 v59, 31, v58
	v_ashrrev_i32_e32 v61, 31, v60
	v_ashrrev_i32_e32 v63, 31, v62
	v_ashrrev_i32_e32 v65, 31, v64
	v_ashrrev_i32_e32 v67, 31, v66
	v_ashrrev_i32_e32 v69, 31, v68
	v_ashrrev_i32_e32 v71, 31, v70
	v_lshl_add_u64 v[72:73], s[8:9], 1, v[2:3]
	v_lshlrev_b64 v[56:57], 11, v[56:57]
	v_lshlrev_b64 v[58:59], 11, v[58:59]
	v_lshlrev_b64 v[60:61], 11, v[60:61]
	v_lshlrev_b64 v[62:63], 11, v[62:63]
	v_lshlrev_b64 v[64:65], 11, v[64:65]
	v_lshlrev_b64 v[66:67], 11, v[66:67]
	v_lshlrev_b64 v[68:69], 11, v[68:69]
	v_lshlrev_b64 v[70:71], 11, v[70:71]
	v_lshl_add_u64 v[56:57], v[72:73], 0, v[56:57]
	v_lshl_add_u64 v[58:59], v[72:73], 0, v[58:59]
	v_lshl_add_u64 v[60:61], v[72:73], 0, v[60:61]
	v_lshl_add_u64 v[62:63], v[72:73], 0, v[62:63]
	v_lshl_add_u64 v[64:65], v[72:73], 0, v[64:65]
	v_lshl_add_u64 v[66:67], v[72:73], 0, v[66:67]
	v_lshl_add_u64 v[68:69], v[72:73], 0, v[68:69]
	v_lshl_add_u64 v[70:71], v[72:73], 0, v[70:71]
	s_branch .Lcv307_n1

; __device__ __forceinline__ bf16_t f2bf(float f) { unsigned u = __float_as_uint(f); u += 0x7FFFu + ((u >> 16) & 1u); return (bf16_t)(u >> 16); }
;     ...
;     for (int t_ = first; t_ < ntile * ((REP & 1) + 1); t_ += gridDim.x) { const int t = t_ % ntile;
;         const int r0 = (t / nkt) * 64, k0 = (t % nkt) * 64;
;         __syncthreads();
; #pragma unroll
;         for (int i = 0; i < 8; ++i) { const int kk = i * 8 + w; tile[kk * 65 + lane] = src(k0 + kk, r0 + lane); }
;         __syncthreads();
; #pragma unroll
;         for (int i = 0; i < 8; ++i) { const int j = i * 8 + w; Bt[(size_t)(r0 + j) * ld + k0 + lane] = f2bf(tile[lane * 65 + j]); }
;     }
; __device__ void convert_phase(unsigned char* smem, const Params& p, int l) {
;     ...
;     { const float* wd = ((const float*)ldp(4)) + uo; conv_tiles(tile, wt + W_DN1, 1024, 2816, 37, [=](int k, int r) { return wd[(size_t)k * DM + r]; }); }
.LBB0_310:
	s_mov_b32 s98, s11
	s_lshr_b32 s99, s98, 8
	s_and_b32 s100, s98, 0xff
	s_mul_i32 s101, s100, 3
	s_sub_i32 s98, s100, 192
	s_mul_i32 s98, s98, 2
	s_add_i32 s98, s98, 576
	s_cmp_lt_u32 s100, 192
	s_cselect_b32 s98, s101, s98
	s_add_i32 s98, s98, s99
	s_mul_hi_u32 s99, s98, 0x10000001
	s_mul_i32 s100, s99, 16
	s_sub_i32 s98, s98, s100
	s_mul_i32 s98, s98, 44
	s_add_i32 s98, s98, s99
	s_mul_hi_i32 s8, s98, 0x2e8ba2e9
	s_lshr_b32 s9, s8, 31
	s_ashr_i32 s8, s8, 7
	s_add_i32 s8, s8, s9
	s_mulk_i32 s8, 0x2c0
	s_sub_i32 s8, s98, s8
	s_sext_i32_i16 s9, s8
	s_mulk_i32 s9, 0xba3
	s_lshr_b32 s16, s9, 31
	s_ashr_i32 s9, s9, 17
	s_add_i32 s9, s9, s16
	s_sext_i32_i16 s16, s9
	s_mul_i32 s9, s9, 44
	s_sub_i32 s8, s8, s9
	s_sext_i32_i16 s8, s8
	s_lshl_b32 s16, s16, 6
	s_lshl_b32 s8, s8, 6
	v_or_b32_e32 v14, s16, v2
	v_add_u32_e32 v16, s8, v3
	v_ashrrev_i32_e32 v15, 31, v14
	v_add_u32_e32 v18, s8, v5
	v_add_u32_e32 v20, s8, v6
	v_add_u32_e32 v22, s8, v7
	v_add_u32_e32 v24, s8, v8
	v_add_u32_e32 v26, s8, v9
	v_add_u32_e32 v28, s8, v10
	v_add_u32_e32 v30, s8, v11
	v_ashrrev_i32_e32 v17, 31, v16
	v_lshl_add_u64 v[14:15], v[14:15], 2, s[6:7]
	v_ashrrev_i32_e32 v19, 31, v18
	v_ashrrev_i32_e32 v21, 31, v20
	v_ashrrev_i32_e32 v23, 31, v22
	v_ashrrev_i32_e32 v25, 31, v24
	v_ashrrev_i32_e32 v27, 31, v26
	v_ashrrev_i32_e32 v29, 31, v28
	v_ashrrev_i32_e32 v31, 31, v30
	v_lshlrev_b64 v[16:17], 12, v[16:17]
	v_lshlrev_b64 v[18:19], 12, v[18:19]
	v_lshlrev_b64 v[20:21], 12, v[20:21]
	v_lshlrev_b64 v[22:23], 12, v[22:23]
	v_lshlrev_b64 v[24:25], 12, v[24:25]
	v_lshlrev_b64 v[26:27], 12, v[26:27]
	v_lshlrev_b64 v[28:29], 12, v[28:29]
	v_lshlrev_b64 v[30:31], 12, v[30:31]
	v_lshl_add_u64 v[16:17], v[14:15], 0, v[16:17]
	v_lshl_add_u64 v[18:19], v[14:15], 0, v[18:19]
	v_lshl_add_u64 v[20:21], v[14:15], 0, v[20:21]
	v_lshl_add_u64 v[22:23], v[14:15], 0, v[22:23]
	v_lshl_add_u64 v[24:25], v[14:15], 0, v[24:25]
	v_lshl_add_u64 v[26:27], v[14:15], 0, v[26:27]
	v_lshl_add_u64 v[28:29], v[14:15], 0, v[28:29]
	v_lshl_add_u64 v[14:15], v[14:15], 0, v[30:31]
	global_load_dword v13, v[16:17], off
	global_load_dword v30, v[18:19], off
	global_load_dword v31, v[20:21], off
	global_load_dword v32, v[22:23], off
	global_load_dword v33, v[24:25], off
	global_load_dword v34, v[26:27], off
	global_load_dword v35, v[28:29], off
	global_load_dword v36, v[14:15], off
	s_ashr_i32 s9, s8, 31
	v_add_u32_e32 v16, s16, v3
	v_add_u32_e32 v18, s16, v5
	v_add_u32_e32 v20, s16, v6
	v_add_u32_e32 v22, s16, v7
	v_add_u32_e32 v24, s16, v8
	v_add_u32_e32 v26, s16, v9
	v_add_u32_e32 v28, s16, v10
	v_add_u32_e32 v37, s16, v11
	v_lshl_add_u64 v[14:15], s[8:9], 1, v[0:1]
	v_mad_i64_i32 v[16:17], s[8:9], v16, s54, v[14:15]
	v_mad_i64_i32 v[18:19], s[8:9], v18, s54, v[14:15]
	v_mad_i64_i32 v[20:21], s[8:9], v20, s54, v[14:15]
	v_mad_i64_i32 v[22:23], s[8:9], v22, s54, v[14:15]
	v_mad_i64_i32 v[24:25], s[8:9], v24, s54, v[14:15]
	v_mad_i64_i32 v[26:27], s[8:9], v26, s54, v[14:15]
	v_mad_i64_i32 v[28:29], s[8:9], v28, s54, v[14:15]
	v_mad_i64_i32 v[14:15], s[8:9], v37, s54, v[14:15]
	s_add_i32 s98, s11, s5
	s_cmp_lt_i32 s98, 0x2c0
	s_cbranch_scc0 .Lcv310_p1skip
	s_lshr_b32 s99, s98, 8
	s_and_b32 s100, s98, 0xff
	s_mul_i32 s101, s100, 3
	s_sub_i32 s98, s100, 192
	s_mul_i32 s98, s98, 2
	s_add_i32 s98, s98, 576
	s_cmp_lt_u32 s100, 192
	s_cselect_b32 s98, s101, s98
	s_add_i32 s98, s98, s99
	s_mul_hi_u32 s99, s98, 0x10000001
	s_mul_i32 s100, s99, 16
	s_sub_i32 s98, s98, s100
	s_mul_i32 s98, s98, 44
	s_add_i32 s98, s98, s99
	s_mul_hi_i32 s8, s98, 0x2e8ba2e9
	s_lshr_b32 s9, s8, 31
	s_ashr_i32 s8, s8, 7
	s_add_i32 s8, s8, s9
	s_mulk_i32 s8, 0x2c0
	s_sub_i32 s8, s98, s8
	s_sext_i32_i16 s9, s8
	s_mulk_i32 s9, 0xba3
	s_lshr_b32 s16, s9, 31
	s_ashr_i32 s9, s9, 17
	s_add_i32 s9, s9, s16
	s_sext_i32_i16 s16, s9
	s_mul_i32 s9, s9, 44
	s_sub_i32 s8, s8, s9
	s_sext_i32_i16 s8, s8
	s_lshl_b32 s16, s16, 6
	s_lshl_b32 s8, s8, 6
	v_or_b32_e32 v54, s16, v2
	v_add_u32_e32 v56, s8, v3
	v_ashrrev_i32_e32 v55, 31, v54
	v_add_u32_e32 v58, s8, v5
	v_add_u32_e32 v60, s8, v6
	v_add_u32_e32 v62, s8, v7
	v_add_u32_e32 v64, s8, v8
	v_add_u32_e32 v66, s8, v9
	v_add_u32_e32 v68, s8, v10
	v_add_u32_e32 v70, s8, v11
	v_ashrrev_i32_e32 v57, 31, v56
	v_lshl_add_u64 v[54:55], v[54:55], 2, s[6:7]
	v_ashrrev_i32_e32 v59, 31, v58
	v_ashrrev_i32_e32 v61, 31, v60
	v_ashrrev_i32_e32 v63, 31, v62
	v_ashrrev_i32_e32 v65, 31, v64
	v_ashrrev_i32_e32 v67, 31, v66
	v_ashrrev_i32_e32 v69, 31, v68
	v_ashrrev_i32_e32 v71, 31, v70
	v_lshlrev_b64 v[56:57], 12, v[56:57]
	v_lshlrev_b64 v[58:59], 12, v[58:59]
	v_lshlrev_b64 v[60:61], 12, v[60:61]
	v_lshlrev_b64 v[62:63], 12, v[62:63]
	v_lshlrev_b64 v[64:65], 12, v[64:65]
	v_lshlrev_b64 v[66:67], 12, v[66:67]
	v_lshlrev_b64 v[68:69], 12, v[68:69]
	v_lshlrev_b64 v[70:71], 12, v[70:71]
	v_lshl_add_u64 v[56:57], v[54:55], 0, v[56:57]
	v_lshl_add_u64 v[58:59], v[54:55], 0, v[58:59]
	v_lshl_add_u64 v[60:61], v[54:55], 0, v[60:61]
	v_lshl_add_u64 v[62:63], v[54:55], 0, v[62:63]
	v_lshl_add_u64 v[64:65], v[54:55], 0, v[64:65]
	v_lshl_add_u64 v[66:67], v[54:55], 0, v[66:67]
	v_lshl_add_u64 v[68:69], v[54:55], 0, v[68:69]
	v_lshl_add_u64 v[54:55], v[54:55], 0, v[70:71]
	global_load_dword v53, v[56:57], off
	global_load_dword v70, v[58:59], off
	global_load_dword v71, v[60:61], off
	global_load_dword v72, v[62:63], off
	global_load_dword v73, v[64:65], off
	global_load_dword v74, v[66:67], off
	global_load_dword v75, v[68:69], off
	global_load_dword v76, v[54:55], off
	s_ashr_i32 s9, s8, 31
	v_add_u32_e32 v56, s16, v3
	v_add_u32_e32 v58, s16, v5
	v_add_u32_e32 v60, s16, v6
	v_add_u32_e32 v62, s16, v7
	v_add_u32_e32 v64, s16, v8
	v_add_u32_e32 v66, s16, v9
	v_add_u32_e32 v68, s16, v10
	v_add_u32_e32 v77, s16, v11
	v_lshl_add_u64 v[54:55], s[8:9], 1, v[0:1]
	v_mad_i64_i32 v[56:57], s[8:9], v56, s54, v[54:55]
	v_mad_i64_i32 v[58:59], s[8:9], v58, s54, v[54:55]
	v_mad_i64_i32 v[60:61], s[8:9], v60, s54, v[54:55]
	v_mad_i64_i32 v[62:63], s[8:9], v62, s54, v[54:55]
	v_mad_i64_i32 v[64:65], s[8:9], v64, s54, v[54:55]
	v_mad_i64_i32 v[66:67], s[8:9], v66, s54, v[54:55]
	v_mad_i64_i32 v[68:69], s[8:9], v68, s54, v[54:55]
	v_mad_i64_i32 v[54:55], s[8:9], v77, s54, v[54:55]
	s_waitcnt vmcnt(8)
	s_branch .Lcv310_pj

; __device__ __forceinline__ bf16_t f2bf(float f) { unsigned u = __float_as_uint(f); u += 0x7FFFu + ((u >> 16) & 1u); return (bf16_t)(u >> 16); }
;     ...
;     for (int t_ = first; t_ < ntile * ((REP & 1) + 1); t_ += gridDim.x) { const int t = t_ % ntile;
;         const int r0 = (t / nkt) * 64, k0 = (t % nkt) * 64;
;         __syncthreads();
; #pragma unroll
;         for (int i = 0; i < 8; ++i) { const int kk = i * 8 + w; tile[kk * 65 + lane] = src(k0 + kk, r0 + lane); }
;         __syncthreads();
; #pragma unroll
;         for (int i = 0; i < 8; ++i) { const int j = i * 8 + w; Bt[(size_t)(r0 + j) * ld + k0 + lane] = f2bf(tile[lane * 65 + j]); }
;     }
; __device__ void convert_phase(unsigned char* smem, const Params& p, int l) {
;     ...
;     { const float* wd = ((const float*)ldp(4)) + uo; conv_tiles(tile, wt + W_DN1, 1024, 2816, 37, [=](int k, int r) { return wd[(size_t)k * DM + r]; }); }
.Lcv310_top:
	s_waitcnt vmcnt(23)
	ds_write_b32 v12, v13
	s_waitcnt vmcnt(22)
	ds_write_b32 v12, v30 offset:2080
	s_waitcnt vmcnt(21)
	ds_write_b32 v12, v31 offset:4160
	s_waitcnt vmcnt(20)
	ds_write_b32 v12, v32 offset:6240
	s_waitcnt vmcnt(19)
	ds_write_b32 v12, v33 offset:8320
	s_waitcnt vmcnt(18)
	ds_write_b32 v12, v34 offset:10400
	s_waitcnt vmcnt(17)
	ds_write_b32 v12, v35 offset:12480
	s_waitcnt vmcnt(16)
	ds_write_b32 v12, v36 offset:14560
	s_waitcnt lgkmcnt(0)
	s_barrier
	ds_read2_b32 v[30:31], v4 offset1:8
	ds_read2_b32 v[32:33], v4 offset0:16 offset1:24
	ds_read2_b32 v[34:35], v4 offset0:32 offset1:40
	ds_read2_b32 v[36:37], v4 offset0:48 offset1:56
	s_waitcnt lgkmcnt(3)
	v_bfe_u32 v13, v30, 16, 1
	v_bfe_u32 v38, v31, 16, 1
	s_waitcnt lgkmcnt(2)
	v_bfe_u32 v39, v32, 16, 1
	v_bfe_u32 v40, v33, 16, 1
	s_waitcnt lgkmcnt(1)
	v_bfe_u32 v41, v34, 16, 1
	v_bfe_u32 v42, v35, 16, 1
	s_waitcnt lgkmcnt(0)
	v_bfe_u32 v43, v36, 16, 1
	v_bfe_u32 v44, v37, 16, 1
	v_add3_u32 v13, v30, v13, s88
	v_add3_u32 v30, v31, v38, s88
	v_add3_u32 v31, v32, v39, s88
	v_add3_u32 v32, v33, v40, s88
	v_add3_u32 v33, v34, v41, s88
	v_add3_u32 v34, v35, v42, s88
	v_add3_u32 v35, v36, v43, s88
	v_add3_u32 v36, v37, v44, s88
	global_store_short_d16_hi v[16:17], v13, off
	global_store_short_d16_hi v[18:19], v30, off
	global_store_short_d16_hi v[20:21], v31, off
	global_store_short_d16_hi v[22:23], v32, off
	global_store_short_d16_hi v[24:25], v33, off
	global_store_short_d16_hi v[26:27], v34, off
	global_store_short_d16_hi v[28:29], v35, off
	global_store_short_d16_hi v[14:15], v36, off
	s_lshl_b32 s98, s5, 1
	s_add_i32 s98, s98, s11
	s_cmp_lt_i32 s98, 0x2c0
	s_cbranch_scc0 .Lcv310_s0
	s_lshr_b32 s99, s98, 8
	s_and_b32 s100, s98, 0xff
	s_mul_i32 s101, s100, 3
	s_sub_i32 s98, s100, 192
	s_mul_i32 s98, s98, 2
	s_add_i32 s98, s98, 576
	s_cmp_lt_u32 s100, 192
	s_cselect_b32 s98, s101, s98
	s_add_i32 s98, s98, s99
	s_mul_hi_u32 s99, s98, 0x10000001
	s_mul_i32 s100, s99, 16
	s_sub_i32 s98, s98, s100
	s_mul_i32 s98, s98, 44
	s_add_i32 s98, s98, s99
	s_mul_hi_i32 s8, s98, 0x2e8ba2e9
	s_lshr_b32 s9, s8, 31
	s_ashr_i32 s8, s8, 7
	s_add_i32 s8, s8, s9
	s_mulk_i32 s8, 0x2c0
	s_sub_i32 s8, s98, s8
	s_sext_i32_i16 s9, s8
	s_mulk_i32 s9, 0xba3
	s_lshr_b32 s16, s9, 31
	s_ashr_i32 s9, s9, 17
	s_add_i32 s9, s9, s16
	s_sext_i32_i16 s16, s9
	s_mul_i32 s9, s9, 44
	s_sub_i32 s8, s8, s9
	s_sext_i32_i16 s8, s8
	s_lshl_b32 s16, s16, 6
	s_lshl_b32 s8, s8, 6
	v_or_b32_e32 v14, s16, v2
	v_add_u32_e32 v16, s8, v3
	v_ashrrev_i32_e32 v15, 31, v14
	v_add_u32_e32 v18, s8, v5
	v_add_u32_e32 v20, s8, v6
	v_add_u32_e32 v22, s8, v7
	v_add_u32_e32 v24, s8, v8
	v_add_u32_e32 v26, s8, v9
	v_add_u32_e32 v28, s8, v10
	v_add_u32_e32 v30, s8, v11
	v_ashrrev_i32_e32 v17, 31, v16
	v_lshl_add_u64 v[14:15], v[14:15], 2, s[6:7]
	v_ashrrev_i32_e32 v19, 31, v18
	v_ashrrev_i32_e32 v21, 31, v20
	v_ashrrev_i32_e32 v23, 31, v22
	v_ashrrev_i32_e32 v25, 31, v24
	v_ashrrev_i32_e32 v27, 31, v26
	v_ashrrev_i32_e32 v29, 31, v28
	v_ashrrev_i32_e32 v31, 31, v30
	v_lshlrev_b64 v[16:17], 12, v[16:17]
	v_lshlrev_b64 v[18:19], 12, v[18:19]
	v_lshlrev_b64 v[20:21], 12, v[20:21]
	v_lshlrev_b64 v[22:23], 12, v[22:23]
	v_lshlrev_b64 v[24:25], 12, v[24:25]
	v_lshlrev_b64 v[26:27], 12, v[26:27]
	v_lshlrev_b64 v[28:29], 12, v[28:29]
	v_lshlrev_b64 v[30:31], 12, v[30:31]
	v_lshl_add_u64 v[16:17], v[14:15], 0, v[16:17]
	v_lshl_add_u64 v[18:19], v[14:15], 0, v[18:19]
	v_lshl_add_u64 v[20:21], v[14:15], 0, v[20:21]
	v_lshl_add_u64 v[22:23], v[14:15], 0, v[22:23]
	v_lshl_add_u64 v[24:25], v[14:15], 0, v[24:25]
	v_lshl_add_u64 v[26:27], v[14:15], 0, v[26:27]
	v_lshl_add_u64 v[28:29], v[14:15], 0, v[28:29]
	v_lshl_add_u64 v[14:15], v[14:15], 0, v[30:31]
	global_load_dword v13, v[16:17], off
	global_load_dword v30, v[18:19], off
	global_load_dword v31, v[20:21], off
	global_load_dword v32, v[22:23], off
	global_load_dword v33, v[24:25], off
	global_load_dword v34, v[26:27], off
	global_load_dword v35, v[28:29], off
	global_load_dword v36, v[14:15], off
	s_ashr_i32 s9, s8, 31
	v_add_u32_e32 v16, s16, v3
	v_add_u32_e32 v18, s16, v5
	v_add_u32_e32 v20, s16, v6
	v_add_u32_e32 v22, s16, v7
	v_add_u32_e32 v24, s16, v8
	v_add_u32_e32 v26, s16, v9
	v_add_u32_e32 v28, s16, v10
	v_add_u32_e32 v37, s16, v11
	v_lshl_add_u64 v[14:15], s[8:9], 1, v[0:1]
	v_mad_i64_i32 v[16:17], s[8:9], v16, s54, v[14:15]
	v_mad_i64_i32 v[18:19], s[8:9], v18, s54, v[14:15]
	v_mad_i64_i32 v[20:21], s[8:9], v20, s54, v[14:15]
	v_mad_i64_i32 v[22:23], s[8:9], v22, s54, v[14:15]
	v_mad_i64_i32 v[24:25], s[8:9], v24, s54, v[14:15]
	v_mad_i64_i32 v[26:27], s[8:9], v26, s54, v[14:15]
	v_mad_i64_i32 v[28:29], s[8:9], v28, s54, v[14:15]
	v_mad_i64_i32 v[14:15], s[8:9], v37, s54, v[14:15]
	s_branch .Lcv310_n0

; __device__ __forceinline__ bf16_t f2bf(float f) { unsigned u = __float_as_uint(f); u += 0x7FFFu + ((u >> 16) & 1u); return (bf16_t)(u >> 16); }
;     ...
;     for (int t_ = first; t_ < ntile * ((REP & 1) + 1); t_ += gridDim.x) { const int t = t_ % ntile;
;         const int r0 = (t / nkt) * 64, k0 = (t % nkt) * 64;
;         __syncthreads();
; #pragma unroll
;         for (int i = 0; i < 8; ++i) { const int kk = i * 8 + w; tile[kk * 65 + lane] = src(k0 + kk, r0 + lane); }
;         __syncthreads();
; #pragma unroll
;         for (int i = 0; i < 8; ++i) { const int j = i * 8 + w; Bt[(size_t)(r0 + j) * ld + k0 + lane] = f2bf(tile[lane * 65 + j]); }
;     }
; __device__ void convert_phase(unsigned char* smem, const Params& p, int l) {
;     ...
;     { const float* wd = ((const float*)ldp(4)) + uo; conv_tiles(tile, wt + W_DN1, 1024, 2816, 37, [=](int k, int r) { return wd[(size_t)k * DM + r]; }); }
.Lcv310_n0:
	s_add_i32 s11, s11, s5
	s_cmp_lt_i32 s11, 0x2c0
	s_cbranch_scc0 .LBB0_311
	s_waitcnt vmcnt(23)
	ds_write_b32 v12, v53 offset:17408
	s_waitcnt vmcnt(22)
	ds_write_b32 v12, v70 offset:19488
	s_waitcnt vmcnt(21)
	ds_write_b32 v12, v71 offset:21568
	s_waitcnt vmcnt(20)
	ds_write_b32 v12, v72 offset:23648
	s_waitcnt vmcnt(19)
	ds_write_b32 v12, v73 offset:25728
	s_waitcnt vmcnt(18)
	ds_write_b32 v12, v74 offset:27808
	s_waitcnt vmcnt(17)
	ds_write_b32 v12, v75 offset:29888
	s_waitcnt vmcnt(16)
	ds_write_b32 v12, v76 offset:31968
	s_waitcnt lgkmcnt(0)
	s_barrier
	ds_read2_b32 v[70:71], v95 offset1:8
	ds_read2_b32 v[72:73], v95 offset0:16 offset1:24
	ds_read2_b32 v[74:75], v95 offset0:32 offset1:40
	ds_read2_b32 v[76:77], v95 offset0:48 offset1:56
	s_waitcnt lgkmcnt(3)
	v_bfe_u32 v53, v70, 16, 1
	v_bfe_u32 v78, v71, 16, 1
	s_waitcnt lgkmcnt(2)
	v_bfe_u32 v79, v72, 16, 1
	v_bfe_u32 v80, v73, 16, 1
	s_waitcnt lgkmcnt(1)
	v_bfe_u32 v81, v74, 16, 1
	v_bfe_u32 v82, v75, 16, 1
	s_waitcnt lgkmcnt(0)
	v_bfe_u32 v83, v76, 16, 1
	v_bfe_u32 v84, v77, 16, 1
	v_add3_u32 v53, v70, v53, s88
	v_add3_u32 v70, v71, v78, s88
	v_add3_u32 v71, v72, v79, s88
	v_add3_u32 v72, v73, v80, s88
	v_add3_u32 v73, v74, v81, s88
	v_add3_u32 v74, v75, v82, s88
	v_add3_u32 v75, v76, v83, s88
	v_add3_u32 v76, v77, v84, s88
	global_store_short_d16_hi v[56:57], v53, off
	global_store_short_d16_hi v[58:59], v70, off
	global_store_short_d16_hi v[60:61], v71, off
	global_store_short_d16_hi v[62:63], v72, off
	global_store_short_d16_hi v[64:65], v73, off
	global_store_short_d16_hi v[66:67], v74, off
	global_store_short_d16_hi v[68:69], v75, off
	global_store_short_d16_hi v[54:55], v76, off
	s_lshl_b32 s98, s5, 1
	s_add_i32 s98, s98, s11
	s_cmp_lt_i32 s98, 0x2c0
	s_cbranch_scc0 .Lcv310_s1
	s_lshr_b32 s99, s98, 8
	s_and_b32 s100, s98, 0xff
	s_mul_i32 s101, s100, 3
	s_sub_i32 s98, s100, 192
	s_mul_i32 s98, s98, 2
	s_add_i32 s98, s98, 576
	s_cmp_lt_u32 s100, 192
	s_cselect_b32 s98, s101, s98
	s_add_i32 s98, s98, s99
	s_mul_hi_u32 s99, s98, 0x10000001
	s_mul_i32 s100, s99, 16
	s_sub_i32 s98, s98, s100
	s_mul_i32 s98, s98, 44
	s_add_i32 s98, s98, s99
	s_mul_hi_i32 s8, s98, 0x2e8ba2e9
	s_lshr_b32 s9, s8, 31
	s_ashr_i32 s8, s8, 7
	s_add_i32 s8, s8, s9
	s_mulk_i32 s8, 0x2c0
	s_sub_i32 s8, s98, s8
	s_sext_i32_i16 s9, s8
	s_mulk_i32 s9, 0xba3
	s_lshr_b32 s16, s9, 31
	s_ashr_i32 s9, s9, 17
	s_add_i32 s9, s9, s16
	s_sext_i32_i16 s16, s9
	s_mul_i32 s9, s9, 44
	s_sub_i32 s8, s8, s9
	s_sext_i32_i16 s8, s8
	s_lshl_b32 s16, s16, 6
	s_lshl_b32 s8, s8, 6
	v_or_b32_e32 v54, s16, v2
	v_add_u32_e32 v56, s8, v3
	v_ashrrev_i32_e32 v55, 31, v54
	v_add_u32_e32 v58, s8, v5
	v_add_u32_e32 v60, s8, v6
	v_add_u32_e32 v62, s8, v7
	v_add_u32_e32 v64, s8, v8
	v_add_u32_e32 v66, s8, v9
	v_add_u32_e32 v68, s8, v10
	v_add_u32_e32 v70, s8, v11
	v_ashrrev_i32_e32 v57, 31, v56
	v_lshl_add_u64 v[54:55], v[54:55], 2, s[6:7]
	v_ashrrev_i32_e32 v59, 31, v58
	v_ashrrev_i32_e32 v61, 31, v60
	v_ashrrev_i32_e32 v63, 31, v62
	v_ashrrev_i32_e32 v65, 31, v64
	v_ashrrev_i32_e32 v67, 31, v66
	v_ashrrev_i32_e32 v69, 31, v68
	v_ashrrev_i32_e32 v71, 31, v70
	v_lshlrev_b64 v[56:57], 12, v[56:57]
	v_lshlrev_b64 v[58:59], 12, v[58:59]
	v_lshlrev_b64 v[60:61], 12, v[60:61]
	v_lshlrev_b64 v[62:63], 12, v[62:63]
	v_lshlrev_b64 v[64:65], 12, v[64:65]
	v_lshlrev_b64 v[66:67], 12, v[66:67]
	v_lshlrev_b64 v[68:69], 12, v[68:69]
	v_lshlrev_b64 v[70:71], 12, v[70:71]
	v_lshl_add_u64 v[56:57], v[54:55], 0, v[56:57]
	v_lshl_add_u64 v[58:59], v[54:55], 0, v[58:59]
	v_lshl_add_u64 v[60:61], v[54:55], 0, v[60:61]
	v_lshl_add_u64 v[62:63], v[54:55], 0, v[62:63]
	v_lshl_add_u64 v[64:65], v[54:55], 0, v[64:65]
	v_lshl_add_u64 v[66:67], v[54:55], 0, v[66:67]
	v_lshl_add_u64 v[68:69], v[54:55], 0, v[68:69]
	v_lshl_add_u64 v[54:55], v[54:55], 0, v[70:71]
	global_load_dword v53, v[56:57], off
	global_load_dword v70, v[58:59], off
	global_load_dword v71, v[60:61], off
	global_load_dword v72, v[62:63], off
	global_load_dword v73, v[64:65], off
	global_load_dword v74, v[66:67], off
	global_load_dword v75, v[68:69], off
	global_load_dword v76, v[54:55], off
	s_ashr_i32 s9, s8, 31
	v_add_u32_e32 v56, s16, v3
	v_add_u32_e32 v58, s16, v5
	v_add_u32_e32 v60, s16, v6
	v_add_u32_e32 v62, s16, v7
	v_add_u32_e32 v64, s16, v8
	v_add_u32_e32 v66, s16, v9
	v_add_u32_e32 v68, s16, v10
	v_add_u32_e32 v77, s16, v11
	v_lshl_add_u64 v[54:55], s[8:9], 1, v[0:1]
	v_mad_i64_i32 v[56:57], s[8:9], v56, s54, v[54:55]
	v_mad_i64_i32 v[58:59], s[8:9], v58, s54, v[54:55]
	v_mad_i64_i32 v[60:61], s[8:9], v60, s54, v[54:55]
	v_mad_i64_i32 v[62:63], s[8:9], v62, s54, v[54:55]
	v_mad_i64_i32 v[64:65], s[8:9], v64, s54, v[54:55]
	v_mad_i64_i32 v[66:67], s[8:9], v66, s54, v[54:55]
	v_mad_i64_i32 v[68:69], s[8:9], v68, s54, v[54:55]
	v_mad_i64_i32 v[54:55], s[8:9], v77, s54, v[54:55]
	s_branch .Lcv310_n1

; __device__ __forceinline__ bf16_t f2bf(float f) { unsigned u = __float_as_uint(f); u += 0x7FFFu + ((u >> 16) & 1u); return (bf16_t)(u >> 16); }
;     ...
;     for (int t_ = first; t_ < ntile * ((REP & 1) + 1); t_ += gridDim.x) { const int t = t_ % ntile;
;         const int r0 = (t / nkt) * 64, k0 = (t % nkt) * 64;
;         __syncthreads();
; #pragma unroll
;         for (int i = 0; i < 8; ++i) { const int kk = i * 8 + w; tile[kk * 65 + lane] = src(k0 + kk, r0 + lane); }
;         __syncthreads();
; #pragma unroll
;         for (int i = 0; i < 8; ++i) { const int j = i * 8 + w; Bt[(size_t)(r0 + j) * ld + k0 + lane] = f2bf(tile[lane * 65 + j]); }
;     }
; __device__ void convert_phase(unsigned char* smem, const Params& p, int l) {
;     ...
;       conv_tiles(tile, wt + W_HYRG, 2560, 1024, 71, [=](int k, int r) { const int col = r < HYC ? r : r + QKVC; return gn[k] * wi[(size_t)k * INC + col]; });
.LBB0_313:
	s_mov_b32 s98, s18
	s_lshr_b32 s99, s98, 8
	s_and_b32 s100, s98, 0xff
	s_mul_i32 s101, s100, 3
	s_sub_i32 s98, s100, 128
	s_mul_i32 s98, s98, 2
	s_add_i32 s98, s98, 384
	s_cmp_lt_u32 s100, 128
	s_cselect_b32 s98, s101, s98
	s_add_i32 s98, s98, s99
	s_mul_hi_u32 s99, s98, 0x6666667
	s_mul_i32 s100, s99, 40
	s_sub_i32 s98, s98, s100
	s_mul_i32 s98, s98, 16
	s_add_i32 s98, s98, s99
	s_mul_hi_i32 s10, s98, 0x66666667
	s_lshr_b32 s19, s10, 31
	s_ashr_i32 s10, s10, 8
	s_add_i32 s10, s10, s19
	s_mulk_i32 s10, 0x280
	s_sub_i32 s10, s98, s10
	s_sext_i32_i16 s19, s10
	s_bfe_u32 s19, s19, 0x4001b
	s_add_i32 s19, s10, s19
	s_sext_i32_i16 s20, s19
	s_and_b32 s19, s19, 0xfff0
	s_lshl_b32 s20, s20, 2
	s_sub_i32 s10, s10, s19
	s_and_b32 s19, s20, 0xffffffc0
	s_movk_i32 s11, 0x600
	v_or_b32_e32 v13, s19, v2
	s_sext_i32_i16 s10, s10
	v_add_u32_e32 v15, 0x1200, v13
	v_cmp_gt_i32_e32 vcc, s11, v13
	s_lshl_b32 s10, s10, 6
	v_add_u32_e32 v14, s10, v3
	v_cndmask_b32_e32 v16, v15, v13, vcc
	v_ashrrev_i32_e32 v17, 31, v16
	v_ashrrev_i32_e32 v15, 31, v14
	v_lshl_add_u64 v[16:17], v[16:17], 2, s[6:7]
	v_add_u32_e32 v20, s10, v5
	v_add_u32_e32 v21, s10, v6
	v_add_u32_e32 v22, s10, v7
	v_add_u32_e32 v24, s10, v8
	v_add_u32_e32 v26, s10, v9
	v_add_u32_e32 v28, s10, v10
	v_add_u32_e32 v30, s10, v11
	v_lshl_add_u64 v[18:19], v[14:15], 2, s[8:9]
	v_mad_i64_i32 v[14:15], s[20:21], v14, s94, v[16:17]
	global_load_dword v13, v[18:19], off
	global_load_dword v32, v[18:19], off offset:32
	global_load_dword v33, v[18:19], off offset:64
	global_load_dword v34, v[18:19], off offset:96
	global_load_dword v35, v[18:19], off offset:128
	global_load_dword v36, v[18:19], off offset:160
	global_load_dword v37, v[18:19], off offset:192
	global_load_dword v38, v[18:19], off offset:224
	v_mad_i64_i32 v[18:19], s[20:21], v20, s94, v[16:17]
	v_mad_i64_i32 v[20:21], s[20:21], v21, s94, v[16:17]
	v_mad_i64_i32 v[22:23], s[20:21], v22, s94, v[16:17]
	v_mad_i64_i32 v[24:25], s[20:21], v24, s94, v[16:17]
	v_mad_i64_i32 v[26:27], s[20:21], v26, s94, v[16:17]
	v_mad_i64_i32 v[28:29], s[20:21], v28, s94, v[16:17]
	v_mad_i64_i32 v[16:17], s[20:21], v30, s94, v[16:17]
	global_load_dword v39, v[14:15], off
	global_load_dword v40, v[18:19], off
	global_load_dword v41, v[20:21], off
	global_load_dword v42, v[22:23], off
	global_load_dword v43, v[24:25], off
	global_load_dword v44, v[26:27], off
	global_load_dword v45, v[28:29], off
	global_load_dword v46, v[16:17], off
	v_add_u32_e32 v14, s19, v3
	v_add_u32_e32 v16, s19, v5
	v_add_u32_e32 v18, s19, v6
	v_add_u32_e32 v20, s19, v7
	v_add_u32_e32 v22, s19, v8
	v_add_u32_e32 v24, s19, v9
	v_add_u32_e32 v26, s19, v10
	v_add_u32_e32 v28, s19, v11
	s_ashr_i32 s11, s10, 31
	v_ashrrev_i32_e32 v15, 31, v14
	v_ashrrev_i32_e32 v17, 31, v16
	v_ashrrev_i32_e32 v19, 31, v18
	v_ashrrev_i32_e32 v21, 31, v20
	v_ashrrev_i32_e32 v23, 31, v22
	v_ashrrev_i32_e32 v25, 31, v24
	v_ashrrev_i32_e32 v27, 31, v26
	v_ashrrev_i32_e32 v29, 31, v28
	v_lshl_add_u64 v[30:31], s[10:11], 1, v[0:1]
	v_lshlrev_b64 v[14:15], 11, v[14:15]
	v_lshlrev_b64 v[16:17], 11, v[16:17]
	v_lshlrev_b64 v[18:19], 11, v[18:19]
	v_lshlrev_b64 v[20:21], 11, v[20:21]
	v_lshlrev_b64 v[22:23], 11, v[22:23]
	v_lshlrev_b64 v[24:25], 11, v[24:25]
	v_lshlrev_b64 v[26:27], 11, v[26:27]
	v_lshlrev_b64 v[28:29], 11, v[28:29]
	v_lshl_add_u64 v[14:15], v[30:31], 0, v[14:15]
	v_lshl_add_u64 v[16:17], v[30:31], 0, v[16:17]
	v_lshl_add_u64 v[18:19], v[30:31], 0, v[18:19]
	v_lshl_add_u64 v[20:21], v[30:31], 0, v[20:21]
	v_lshl_add_u64 v[22:23], v[30:31], 0, v[22:23]
	v_lshl_add_u64 v[24:25], v[30:31], 0, v[24:25]
	v_lshl_add_u64 v[26:27], v[30:31], 0, v[26:27]
	v_lshl_add_u64 v[28:29], v[30:31], 0, v[28:29]
	s_add_i32 s98, s18, s5
	s_cmp_lt_i32 s98, 0x280
	s_cbranch_scc0 .Lcv313_p1skip
; __device__ __forceinline__ bf16_t f2bf(float f) { unsigned u = __float_as_uint(f); u += 0x7FFFu + ((u >> 16) & 1u); return (bf16_t)(u >> 16); }
;     ...
;     for (int t_ = first; t_ < ntile * ((REP & 1) + 1); t_ += gridDim.x) { const int t = t_ % ntile;
;         const int r0 = (t / nkt) * 64, k0 = (t % nkt) * 64;
;         __syncthreads();
; #pragma unroll
;         for (int i = 0; i < 8; ++i) { const int kk = i * 8 + w; tile[kk * 65 + lane] = src(k0 + kk, r0 + lane); }
;         __syncthreads();
; #pragma unroll
;         for (int i = 0; i < 8; ++i) { const int j = i * 8 + w; Bt[(size_t)(r0 + j) * ld + k0 + lane] = f2bf(tile[lane * 65 + j]); }
;     }
; __device__ void convert_phase(unsigned char* smem, const Params& p, int l) {
;     ...
;       conv_tiles(tile, wt + W_HYRG, 2560, 1024, 71, [=](int k, int r) { const int col = r < HYC ? r : r + QKVC; return gn[k] * wi[(size_t)k * INC + col]; });
	s_lshr_b32 s99, s98, 8
	s_and_b32 s100, s98, 0xff
	s_mul_i32 s101, s100, 3
	s_sub_i32 s98, s100, 128
	s_mul_i32 s98, s98, 2
	s_add_i32 s98, s98, 384
	s_cmp_lt_u32 s100, 128
	s_cselect_b32 s98, s101, s98
	s_add_i32 s98, s98, s99
	s_mul_hi_u32 s99, s98, 0x6666667
	s_mul_i32 s100, s99, 40
	s_sub_i32 s98, s98, s100
	s_mul_i32 s98, s98, 16
	s_add_i32 s98, s98, s99
	s_mul_hi_i32 s10, s98, 0x66666667
	s_lshr_b32 s19, s10, 31
	s_ashr_i32 s10, s10, 8
	s_add_i32 s10, s10, s19
	s_mulk_i32 s10, 0x280
	s_sub_i32 s10, s98, s10
	s_sext_i32_i16 s19, s10
	s_bfe_u32 s19, s19, 0x4001b
	s_add_i32 s19, s10, s19
	s_sext_i32_i16 s20, s19
	s_and_b32 s19, s19, 0xfff0
	s_lshl_b32 s20, s20, 2
	s_sub_i32 s10, s10, s19
	s_and_b32 s19, s20, 0xffffffc0
	s_movk_i32 s11, 0x600
	v_or_b32_e32 v53, s19, v2
	s_sext_i32_i16 s10, s10
	v_add_u32_e32 v55, 0x1200, v53
	v_cmp_gt_i32_e32 vcc, s11, v53
	s_lshl_b32 s10, s10, 6
	v_add_u32_e32 v54, s10, v3
	v_cndmask_b32_e32 v56, v55, v53, vcc
	v_ashrrev_i32_e32 v57, 31, v56
	v_ashrrev_i32_e32 v55, 31, v54
	v_lshl_add_u64 v[56:57], v[56:57], 2, s[6:7]
	v_add_u32_e32 v60, s10, v5
	v_add_u32_e32 v61, s10, v6
	v_add_u32_e32 v62, s10, v7
	v_add_u32_e32 v64, s10, v8
	v_add_u32_e32 v66, s10, v9
	v_add_u32_e32 v68, s10, v10
	v_add_u32_e32 v70, s10, v11
	v_lshl_add_u64 v[58:59], v[54:55], 2, s[8:9]
	v_mad_i64_i32 v[54:55], s[20:21], v54, s94, v[56:57]
	global_load_dword v53, v[58:59], off
	global_load_dword v72, v[58:59], off offset:32
	global_load_dword v73, v[58:59], off offset:64
	global_load_dword v74, v[58:59], off offset:96
	global_load_dword v75, v[58:59], off offset:128
	global_load_dword v76, v[58:59], off offset:160
	global_load_dword v77, v[58:59], off offset:192
	global_load_dword v78, v[58:59], off offset:224
	v_mad_i64_i32 v[58:59], s[20:21], v60, s94, v[56:57]
	v_mad_i64_i32 v[60:61], s[20:21], v61, s94, v[56:57]
	v_mad_i64_i32 v[62:63], s[20:21], v62, s94, v[56:57]
	v_mad_i64_i32 v[64:65], s[20:21], v64, s94, v[56:57]
	v_mad_i64_i32 v[66:67], s[20:21], v66, s94, v[56:57]
	v_mad_i64_i32 v[68:69], s[20:21], v68, s94, v[56:57]
	v_mad_i64_i32 v[56:57], s[20:21], v70, s94, v[56:57]
	global_load_dword v79, v[54:55], off
	global_load_dword v80, v[58:59], off
	global_load_dword v81, v[60:61], off
	global_load_dword v82, v[62:63], off
	global_load_dword v83, v[64:65], off
	global_load_dword v84, v[66:67], off
	global_load_dword v85, v[68:69], off
	global_load_dword v86, v[56:57], off
	v_add_u32_e32 v54, s19, v3
	v_add_u32_e32 v56, s19, v5
	v_add_u32_e32 v58, s19, v6
	v_add_u32_e32 v60, s19, v7
	v_add_u32_e32 v62, s19, v8
	v_add_u32_e32 v64, s19, v9
	v_add_u32_e32 v66, s19, v10
	v_add_u32_e32 v68, s19, v11
	s_ashr_i32 s11, s10, 31
	v_ashrrev_i32_e32 v55, 31, v54
	v_ashrrev_i32_e32 v57, 31, v56
	v_ashrrev_i32_e32 v59, 31, v58
	v_ashrrev_i32_e32 v61, 31, v60
	v_ashrrev_i32_e32 v63, 31, v62
	v_ashrrev_i32_e32 v65, 31, v64
	v_ashrrev_i32_e32 v67, 31, v66
	v_ashrrev_i32_e32 v69, 31, v68
	v_lshl_add_u64 v[70:71], s[10:11], 1, v[0:1]
	v_lshlrev_b64 v[54:55], 11, v[54:55]
	v_lshlrev_b64 v[56:57], 11, v[56:57]
	v_lshlrev_b64 v[58:59], 11, v[58:59]
	v_lshlrev_b64 v[60:61], 11, v[60:61]
	v_lshlrev_b64 v[62:63], 11, v[62:63]
	v_lshlrev_b64 v[64:65], 11, v[64:65]
	v_lshlrev_b64 v[66:67], 11, v[66:67]
	v_lshlrev_b64 v[68:69], 11, v[68:69]
	v_lshl_add_u64 v[54:55], v[70:71], 0, v[54:55]
	v_lshl_add_u64 v[56:57], v[70:71], 0, v[56:57]
	v_lshl_add_u64 v[58:59], v[70:71], 0, v[58:59]
	v_lshl_add_u64 v[60:61], v[70:71], 0, v[60:61]
	v_lshl_add_u64 v[62:63], v[70:71], 0, v[62:63]
	v_lshl_add_u64 v[64:65], v[70:71], 0, v[64:65]
	v_lshl_add_u64 v[66:67], v[70:71], 0, v[66:67]
	v_lshl_add_u64 v[68:69], v[70:71], 0, v[68:69]
	s_waitcnt vmcnt(16)
	s_branch .Lcv313_pj

; __device__ __forceinline__ bf16_t f2bf(float f) { unsigned u = __float_as_uint(f); u += 0x7FFFu + ((u >> 16) & 1u); return (bf16_t)(u >> 16); }
;     ...
;     for (int t_ = first; t_ < ntile * ((REP & 1) + 1); t_ += gridDim.x) { const int t = t_ % ntile;
;         const int r0 = (t / nkt) * 64, k0 = (t % nkt) * 64;
;         __syncthreads();
; #pragma unroll
;         for (int i = 0; i < 8; ++i) { const int kk = i * 8 + w; tile[kk * 65 + lane] = src(k0 + kk, r0 + lane); }
;         __syncthreads();
; #pragma unroll
;         for (int i = 0; i < 8; ++i) { const int j = i * 8 + w; Bt[(size_t)(r0 + j) * ld + k0 + lane] = f2bf(tile[lane * 65 + j]); }
;     }
; __device__ void convert_phase(unsigned char* smem, const Params& p, int l) {
;     ...
;       conv_tiles(tile, wt + W_HYRG, 2560, 1024, 71, [=](int k, int r) { const int col = r < HYC ? r : r + QKVC; return gn[k] * wi[(size_t)k * INC + col]; });
.Lcv313_top:
	s_waitcnt vmcnt(31)
	v_mul_f32_e32 v13, v13, v39
	s_waitcnt vmcnt(30)
	v_mul_f32_e32 v30, v32, v40
	s_waitcnt vmcnt(29)
	v_mul_f32_e32 v31, v33, v41
	s_waitcnt vmcnt(28)
	v_mul_f32_e32 v32, v34, v42
	s_waitcnt vmcnt(27)
	v_mul_f32_e32 v33, v35, v43
	s_waitcnt vmcnt(26)
	v_mul_f32_e32 v34, v36, v44
	s_waitcnt vmcnt(25)
	v_mul_f32_e32 v35, v37, v45
	s_waitcnt vmcnt(24)
	v_mul_f32_e32 v36, v38, v46
	ds_write_b32 v12, v13
	ds_write_b32 v12, v30 offset:2080
	ds_write_b32 v12, v31 offset:4160
	ds_write_b32 v12, v32 offset:6240
	ds_write_b32 v12, v33 offset:8320
	ds_write_b32 v12, v34 offset:10400
	ds_write_b32 v12, v35 offset:12480
	ds_write_b32 v12, v36 offset:14560
	s_waitcnt lgkmcnt(0)
	s_barrier
	ds_read2_b32 v[30:31], v4 offset1:8
	ds_read2_b32 v[32:33], v4 offset0:16 offset1:24
	ds_read2_b32 v[34:35], v4 offset0:32 offset1:40
	ds_read2_b32 v[36:37], v4 offset0:48 offset1:56
	s_waitcnt lgkmcnt(3)
	v_bfe_u32 v13, v30, 16, 1
	v_bfe_u32 v38, v31, 16, 1
	s_waitcnt lgkmcnt(2)
	v_bfe_u32 v39, v32, 16, 1
	v_bfe_u32 v40, v33, 16, 1
	s_waitcnt lgkmcnt(1)
	v_bfe_u32 v41, v34, 16, 1
	v_bfe_u32 v42, v35, 16, 1
	s_waitcnt lgkmcnt(0)
	v_bfe_u32 v43, v36, 16, 1
	v_bfe_u32 v44, v37, 16, 1
	v_add3_u32 v13, v30, v13, s88
	v_add3_u32 v30, v31, v38, s88
	v_add3_u32 v31, v32, v39, s88
	v_add3_u32 v32, v33, v40, s88
	v_add3_u32 v33, v34, v41, s88
	v_add3_u32 v34, v35, v42, s88
	v_add3_u32 v35, v36, v43, s88
	v_add3_u32 v36, v37, v44, s88
	global_store_short_d16_hi v[14:15], v13, off
	global_store_short_d16_hi v[16:17], v30, off
	global_store_short_d16_hi v[18:19], v31, off
	global_store_short_d16_hi v[20:21], v32, off
	global_store_short_d16_hi v[22:23], v33, off
	global_store_short_d16_hi v[24:25], v34, off
	global_store_short_d16_hi v[26:27], v35, off
	global_store_short_d16_hi v[28:29], v36, off
	s_lshl_b32 s98, s5, 1
	s_add_i32 s98, s98, s18
	s_cmp_lt_i32 s98, 0x280
	s_cbranch_scc0 .Lcv313_s0
	s_lshr_b32 s99, s98, 8
	s_and_b32 s100, s98, 0xff
	s_mul_i32 s101, s100, 3
	s_sub_i32 s98, s100, 128
	s_mul_i32 s98, s98, 2
	s_add_i32 s98, s98, 384
	s_cmp_lt_u32 s100, 128
	s_cselect_b32 s98, s101, s98
	s_add_i32 s98, s98, s99
	s_mul_hi_u32 s99, s98, 0x6666667
	s_mul_i32 s100, s99, 40
	s_sub_i32 s98, s98, s100
	s_mul_i32 s98, s98, 16
	s_add_i32 s98, s98, s99
	s_mul_hi_i32 s10, s98, 0x66666667
	s_lshr_b32 s19, s10, 31
	s_ashr_i32 s10, s10, 8
	s_add_i32 s10, s10, s19
	s_mulk_i32 s10, 0x280
	s_sub_i32 s10, s98, s10
	s_sext_i32_i16 s19, s10
	s_bfe_u32 s19, s19, 0x4001b
	s_add_i32 s19, s10, s19
	s_sext_i32_i16 s20, s19
	s_and_b32 s19, s19, 0xfff0
	s_lshl_b32 s20, s20, 2
	s_sub_i32 s10, s10, s19
	s_and_b32 s19, s20, 0xffffffc0
	s_movk_i32 s11, 0x600
	v_or_b32_e32 v13, s19, v2
	s_sext_i32_i16 s10, s10
	v_add_u32_e32 v15, 0x1200, v13
	v_cmp_gt_i32_e32 vcc, s11, v13
	s_lshl_b32 s10, s10, 6
	v_add_u32_e32 v14, s10, v3
	v_cndmask_b32_e32 v16, v15, v13, vcc
	v_ashrrev_i32_e32 v17, 31, v16
	v_ashrrev_i32_e32 v15, 31, v14
	v_lshl_add_u64 v[16:17], v[16:17], 2, s[6:7]
	v_add_u32_e32 v20, s10, v5
	v_add_u32_e32 v21, s10, v6
	v_add_u32_e32 v22, s10, v7
	v_add_u32_e32 v24, s10, v8
	v_add_u32_e32 v26, s10, v9
	v_add_u32_e32 v28, s10, v10
	v_add_u32_e32 v30, s10, v11
	v_lshl_add_u64 v[18:19], v[14:15], 2, s[8:9]
	v_mad_i64_i32 v[14:15], s[20:21], v14, s94, v[16:17]
	global_load_dword v13, v[18:19], off
	global_load_dword v32, v[18:19], off offset:32
	global_load_dword v33, v[18:19], off offset:64
	global_load_dword v34, v[18:19], off offset:96
	global_load_dword v35, v[18:19], off offset:128
	global_load_dword v36, v[18:19], off offset:160
	global_load_dword v37, v[18:19], off offset:192
	global_load_dword v38, v[18:19], off offset:224
	v_mad_i64_i32 v[18:19], s[20:21], v20, s94, v[16:17]
	v_mad_i64_i32 v[20:21], s[20:21], v21, s94, v[16:17]
	v_mad_i64_i32 v[22:23], s[20:21], v22, s94, v[16:17]
	v_mad_i64_i32 v[24:25], s[20:21], v24, s94, v[16:17]
	v_mad_i64_i32 v[26:27], s[20:21], v26, s94, v[16:17]
	v_mad_i64_i32 v[28:29], s[20:21], v28, s94, v[16:17]
	v_mad_i64_i32 v[16:17], s[20:21], v30, s94, v[16:17]
	global_load_dword v39, v[14:15], off
	global_load_dword v40, v[18:19], off
	global_load_dword v41, v[20:21], off
	global_load_dword v42, v[22:23], off
	global_load_dword v43, v[24:25], off
	global_load_dword v44, v[26:27], off
	global_load_dword v45, v[28:29], off
	global_load_dword v46, v[16:17], off
	v_add_u32_e32 v14, s19, v3
	v_add_u32_e32 v16, s19, v5
	v_add_u32_e32 v18, s19, v6
	v_add_u32_e32 v20, s19, v7
	v_add_u32_e32 v22, s19, v8
	v_add_u32_e32 v24, s19, v9
	v_add_u32_e32 v26, s19, v10
	v_add_u32_e32 v28, s19, v11
	s_ashr_i32 s11, s10, 31
	v_ashrrev_i32_e32 v15, 31, v14
	v_ashrrev_i32_e32 v17, 31, v16
	v_ashrrev_i32_e32 v19, 31, v18
	v_ashrrev_i32_e32 v21, 31, v20
	v_ashrrev_i32_e32 v23, 31, v22
	v_ashrrev_i32_e32 v25, 31, v24
	v_ashrrev_i32_e32 v27, 31, v26
	v_ashrrev_i32_e32 v29, 31, v28
	v_lshl_add_u64 v[30:31], s[10:11], 1, v[0:1]
	v_lshlrev_b64 v[14:15], 11, v[14:15]
	v_lshlrev_b64 v[16:17], 11, v[16:17]
	v_lshlrev_b64 v[18:19], 11, v[18:19]
	v_lshlrev_b64 v[20:21], 11, v[20:21]
	v_lshlrev_b64 v[22:23], 11, v[22:23]
	v_lshlrev_b64 v[24:25], 11, v[24:25]
	v_lshlrev_b64 v[26:27], 11, v[26:27]
	v_lshlrev_b64 v[28:29], 11, v[28:29]
	v_lshl_add_u64 v[14:15], v[30:31], 0, v[14:15]
	v_lshl_add_u64 v[16:17], v[30:31], 0, v[16:17]
	v_lshl_add_u64 v[18:19], v[30:31], 0, v[18:19]
	v_lshl_add_u64 v[20:21], v[30:31], 0, v[20:21]
	v_lshl_add_u64 v[22:23], v[30:31], 0, v[22:23]
	v_lshl_add_u64 v[24:25], v[30:31], 0, v[24:25]
	v_lshl_add_u64 v[26:27], v[30:31], 0, v[26:27]
	v_lshl_add_u64 v[28:29], v[30:31], 0, v[28:29]
	s_branch .Lcv313_n0

; __device__ __forceinline__ bf16_t f2bf(float f) { unsigned u = __float_as_uint(f); u += 0x7FFFu + ((u >> 16) & 1u); return (bf16_t)(u >> 16); }
;     ...
;     for (int t_ = first; t_ < ntile * ((REP & 1) + 1); t_ += gridDim.x) { const int t = t_ % ntile;
;         const int r0 = (t / nkt) * 64, k0 = (t % nkt) * 64;
;         __syncthreads();
; #pragma unroll
;         for (int i = 0; i < 8; ++i) { const int kk = i * 8 + w; tile[kk * 65 + lane] = src(k0 + kk, r0 + lane); }
;         __syncthreads();
; #pragma unroll
;         for (int i = 0; i < 8; ++i) { const int j = i * 8 + w; Bt[(size_t)(r0 + j) * ld + k0 + lane] = f2bf(tile[lane * 65 + j]); }
;     }
; __device__ void convert_phase(unsigned char* smem, const Params& p, int l) {
;     ...
;       conv_tiles(tile, wt + W_HYRG, 2560, 1024, 71, [=](int k, int r) { const int col = r < HYC ? r : r + QKVC; return gn[k] * wi[(size_t)k * INC + col]; });
.Lcv313_n0:
	s_add_i32 s18, s18, s5
	s_cmp_lt_i32 s18, 0x280
	s_cbranch_scc0 .LBB0_314
	s_waitcnt vmcnt(31)
	v_mul_f32_e32 v53, v53, v79
	s_waitcnt vmcnt(30)
	v_mul_f32_e32 v70, v72, v80
	s_waitcnt vmcnt(29)
	v_mul_f32_e32 v71, v73, v81
	s_waitcnt vmcnt(28)
	v_mul_f32_e32 v72, v74, v82
	s_waitcnt vmcnt(27)
	v_mul_f32_e32 v73, v75, v83
	s_waitcnt vmcnt(26)
	v_mul_f32_e32 v74, v76, v84
	s_waitcnt vmcnt(25)
	v_mul_f32_e32 v75, v77, v85
	s_waitcnt vmcnt(24)
	v_mul_f32_e32 v76, v78, v86
	ds_write_b32 v12, v53 offset:17408
	ds_write_b32 v12, v70 offset:19488
	ds_write_b32 v12, v71 offset:21568
	ds_write_b32 v12, v72 offset:23648
	ds_write_b32 v12, v73 offset:25728
	ds_write_b32 v12, v74 offset:27808
	ds_write_b32 v12, v75 offset:29888
	ds_write_b32 v12, v76 offset:31968
	s_waitcnt lgkmcnt(0)
	s_barrier
	ds_read2_b32 v[70:71], v95 offset1:8
	ds_read2_b32 v[72:73], v95 offset0:16 offset1:24
	ds_read2_b32 v[74:75], v95 offset0:32 offset1:40
	ds_read2_b32 v[76:77], v95 offset0:48 offset1:56
	s_waitcnt lgkmcnt(3)
	v_bfe_u32 v53, v70, 16, 1
	v_bfe_u32 v78, v71, 16, 1
	s_waitcnt lgkmcnt(2)
	v_bfe_u32 v79, v72, 16, 1
	v_bfe_u32 v80, v73, 16, 1
	s_waitcnt lgkmcnt(1)
	v_bfe_u32 v81, v74, 16, 1
	v_bfe_u32 v82, v75, 16, 1
	s_waitcnt lgkmcnt(0)
	v_bfe_u32 v83, v76, 16, 1
	v_bfe_u32 v84, v77, 16, 1
	v_add3_u32 v53, v70, v53, s88
	v_add3_u32 v70, v71, v78, s88
	v_add3_u32 v71, v72, v79, s88
	v_add3_u32 v72, v73, v80, s88
	v_add3_u32 v73, v74, v81, s88
	v_add3_u32 v74, v75, v82, s88
	v_add3_u32 v75, v76, v83, s88
	v_add3_u32 v76, v77, v84, s88
	global_store_short_d16_hi v[54:55], v53, off
	global_store_short_d16_hi v[56:57], v70, off
	global_store_short_d16_hi v[58:59], v71, off
	global_store_short_d16_hi v[60:61], v72, off
	global_store_short_d16_hi v[62:63], v73, off
	global_store_short_d16_hi v[64:65], v74, off
	global_store_short_d16_hi v[66:67], v75, off
	global_store_short_d16_hi v[68:69], v76, off
	s_lshl_b32 s98, s5, 1
	s_add_i32 s98, s98, s18
	s_cmp_lt_i32 s98, 0x280
	s_cbranch_scc0 .Lcv313_s1
	s_lshr_b32 s99, s98, 8
	s_and_b32 s100, s98, 0xff
	s_mul_i32 s101, s100, 3
	s_sub_i32 s98, s100, 128
	s_mul_i32 s98, s98, 2
	s_add_i32 s98, s98, 384
	s_cmp_lt_u32 s100, 128
	s_cselect_b32 s98, s101, s98
	s_add_i32 s98, s98, s99
	s_mul_hi_u32 s99, s98, 0x6666667
	s_mul_i32 s100, s99, 40
	s_sub_i32 s98, s98, s100
	s_mul_i32 s98, s98, 16
	s_add_i32 s98, s98, s99
	s_mul_hi_i32 s10, s98, 0x66666667
	s_lshr_b32 s19, s10, 31
	s_ashr_i32 s10, s10, 8
	s_add_i32 s10, s10, s19
	s_mulk_i32 s10, 0x280
	s_sub_i32 s10, s98, s10
	s_sext_i32_i16 s19, s10
	s_bfe_u32 s19, s19, 0x4001b
	s_add_i32 s19, s10, s19
	s_sext_i32_i16 s20, s19
	s_and_b32 s19, s19, 0xfff0
	s_lshl_b32 s20, s20, 2
	s_sub_i32 s10, s10, s19
	s_and_b32 s19, s20, 0xffffffc0
	s_movk_i32 s11, 0x600
	v_or_b32_e32 v53, s19, v2
	s_sext_i32_i16 s10, s10
	v_add_u32_e32 v55, 0x1200, v53
	v_cmp_gt_i32_e32 vcc, s11, v53
	s_lshl_b32 s10, s10, 6
	v_add_u32_e32 v54, s10, v3
	v_cndmask_b32_e32 v56, v55, v53, vcc
	v_ashrrev_i32_e32 v57, 31, v56
	v_ashrrev_i32_e32 v55, 31, v54
	v_lshl_add_u64 v[56:57], v[56:57], 2, s[6:7]
	v_add_u32_e32 v60, s10, v5
	v_add_u32_e32 v61, s10, v6
	v_add_u32_e32 v62, s10, v7
	v_add_u32_e32 v64, s10, v8
	v_add_u32_e32 v66, s10, v9
	v_add_u32_e32 v68, s10, v10
	v_add_u32_e32 v70, s10, v11
	v_lshl_add_u64 v[58:59], v[54:55], 2, s[8:9]
	v_mad_i64_i32 v[54:55], s[20:21], v54, s94, v[56:57]
	global_load_dword v53, v[58:59], off
	global_load_dword v72, v[58:59], off offset:32
	global_load_dword v73, v[58:59], off offset:64
	global_load_dword v74, v[58:59], off offset:96
	global_load_dword v75, v[58:59], off offset:128
	global_load_dword v76, v[58:59], off offset:160
	global_load_dword v77, v[58:59], off offset:192
	global_load_dword v78, v[58:59], off offset:224
	v_mad_i64_i32 v[58:59], s[20:21], v60, s94, v[56:57]
	v_mad_i64_i32 v[60:61], s[20:21], v61, s94, v[56:57]
	v_mad_i64_i32 v[62:63], s[20:21], v62, s94, v[56:57]
	v_mad_i64_i32 v[64:65], s[20:21], v64, s94, v[56:57]
	v_mad_i64_i32 v[66:67], s[20:21], v66, s94, v[56:57]
	v_mad_i64_i32 v[68:69], s[20:21], v68, s94, v[56:57]
	v_mad_i64_i32 v[56:57], s[20:21], v70, s94, v[56:57]
	global_load_dword v79, v[54:55], off
	global_load_dword v80, v[58:59], off
	global_load_dword v81, v[60:61], off
	global_load_dword v82, v[62:63], off
	global_load_dword v83, v[64:65], off
	global_load_dword v84, v[66:67], off
	global_load_dword v85, v[68:69], off
	global_load_dword v86, v[56:57], off
	v_add_u32_e32 v54, s19, v3
	v_add_u32_e32 v56, s19, v5
	v_add_u32_e32 v58, s19, v6
	v_add_u32_e32 v60, s19, v7
	v_add_u32_e32 v62, s19, v8
	v_add_u32_e32 v64, s19, v9
	v_add_u32_e32 v66, s19, v10
	v_add_u32_e32 v68, s19, v11
	s_ashr_i32 s11, s10, 31
	v_ashrrev_i32_e32 v55, 31, v54
	v_ashrrev_i32_e32 v57, 31, v56
	v_ashrrev_i32_e32 v59, 31, v58
	v_ashrrev_i32_e32 v61, 31, v60
	v_ashrrev_i32_e32 v63, 31, v62
	v_ashrrev_i32_e32 v65, 31, v64
	v_ashrrev_i32_e32 v67, 31, v66
	v_ashrrev_i32_e32 v69, 31, v68
	v_lshl_add_u64 v[70:71], s[10:11], 1, v[0:1]
	v_lshlrev_b64 v[54:55], 11, v[54:55]
	v_lshlrev_b64 v[56:57], 11, v[56:57]
	v_lshlrev_b64 v[58:59], 11, v[58:59]
	v_lshlrev_b64 v[60:61], 11, v[60:61]
	v_lshlrev_b64 v[62:63], 11, v[62:63]
	v_lshlrev_b64 v[64:65], 11, v[64:65]
	v_lshlrev_b64 v[66:67], 11, v[66:67]
	v_lshlrev_b64 v[68:69], 11, v[68:69]
	v_lshl_add_u64 v[54:55], v[70:71], 0, v[54:55]
	v_lshl_add_u64 v[56:57], v[70:71], 0, v[56:57]
	v_lshl_add_u64 v[58:59], v[70:71], 0, v[58:59]
	v_lshl_add_u64 v[60:61], v[70:71], 0, v[60:61]
	v_lshl_add_u64 v[62:63], v[70:71], 0, v[62:63]
	v_lshl_add_u64 v[64:65], v[70:71], 0, v[64:65]
	v_lshl_add_u64 v[66:67], v[70:71], 0, v[66:67]
	v_lshl_add_u64 v[68:69], v[70:71], 0, v[68:69]
	s_branch .Lcv313_n1

; __device__ __forceinline__ bf16_t f2bf(float f) { unsigned u = __float_as_uint(f); u += 0x7FFFu + ((u >> 16) & 1u); return (bf16_t)(u >> 16); }
;     ...
;     for (int t_ = first; t_ < ntile * ((REP & 1) + 1); t_ += gridDim.x) { const int t = t_ % ntile;
;         const int r0 = (t / nkt) * 64, k0 = (t % nkt) * 64;
;         __syncthreads();
; #pragma unroll
;         for (int i = 0; i < 8; ++i) { const int kk = i * 8 + w; tile[kk * 65 + lane] = src(k0 + kk, r0 + lane); }
;         __syncthreads();
; #pragma unroll
;         for (int i = 0; i < 8; ++i) { const int j = i * 8 + w; Bt[(size_t)(r0 + j) * ld + k0 + lane] = f2bf(tile[lane * 65 + j]); }
;     }
; __device__ void convert_phase(unsigned char* smem, const Params& p, int l) {
;     ...
;       conv_tiles(tile, wt + W_QKV, 4608, 1024, 113, [=](int k, int r) { return gn[k] * wi[(size_t)k * INC + HYC + r]; }); }
.LBB0_316:
	s_mov_b32 s98, s18
	s_lshr_b32 s99, s98, 8
	s_and_b32 s100, s98, 0xff
	s_mul_i32 s101, s100, 5
	s_sub_i32 s98, s100, 128
	s_mul_i32 s98, s98, 4
	s_add_i32 s98, s98, 640
	s_cmp_lt_u32 s100, 128
	s_cselect_b32 s98, s101, s98
	s_add_i32 s98, s98, s99
	s_mul_hi_u32 s99, s98, 0x38e38e4
	s_mul_i32 s100, s99, 72
	s_sub_i32 s98, s98, s100
	s_mul_i32 s98, s98, 16
	s_add_i32 s98, s98, s99
	s_mul_hi_i32 s10, s98, 0x38e38e39
	s_lshr_b32 s11, s10, 31
	s_ashr_i32 s10, s10, 8
	s_add_i32 s10, s10, s11
	s_mulk_i32 s10, 0x480
	s_sub_i32 s10, s98, s10
	s_sext_i32_i16 s11, s10
	s_bfe_u32 s11, s11, 0x4001b
	s_add_i32 s11, s10, s11
	s_sext_i32_i16 s19, s11
	s_and_b32 s11, s11, 0xfff0
	s_lshl_b32 s19, s19, 2
	s_sub_i32 s10, s10, s11
	s_and_b32 s11, s19, 0xffffffc0
	s_sext_i32_i16 s10, s10
	s_lshl_b32 s10, s10, 6
	v_or_b32_e32 v16, s11, v2
	v_mov_b64_e32 v[14:15], s[6:7]
	v_ashrrev_i32_e32 v17, 31, v16
	v_add_u32_e32 v18, s10, v3
	v_add_u32_e32 v13, s10, v5
	v_add_u32_e32 v24, s10, v6
	v_add_u32_e32 v26, s10, v7
	v_add_u32_e32 v28, s10, v8
	v_add_u32_e32 v30, s10, v9
	v_add_u32_e32 v32, s10, v10
	v_add_u32_e32 v34, s10, v11
	v_mad_i64_i32 v[20:21], s[20:21], v18, s94, v[14:15]
	v_lshlrev_b64 v[16:17], 2, v[16:17]
	v_mad_i64_i32 v[22:23], s[20:21], v13, s94, v[14:15]
	v_mad_i64_i32 v[24:25], s[20:21], v24, s94, v[14:15]
	v_mad_i64_i32 v[26:27], s[20:21], v26, s94, v[14:15]
	v_mad_i64_i32 v[28:29], s[20:21], v28, s94, v[14:15]
	v_mad_i64_i32 v[30:31], s[20:21], v30, s94, v[14:15]
	v_mad_i64_i32 v[32:33], s[20:21], v32, s94, v[14:15]
	v_mad_i64_i32 v[14:15], s[20:21], v34, s94, v[14:15]
	v_lshl_add_u64 v[20:21], v[20:21], 0, v[16:17]
	v_lshl_add_u64 v[22:23], v[22:23], 0, v[16:17]
	v_lshl_add_u64 v[24:25], v[24:25], 0, v[16:17]
	v_lshl_add_u64 v[26:27], v[26:27], 0, v[16:17]
	v_lshl_add_u64 v[28:29], v[28:29], 0, v[16:17]
	v_lshl_add_u64 v[30:31], v[30:31], 0, v[16:17]
	v_lshl_add_u64 v[32:33], v[32:33], 0, v[16:17]
	v_lshl_add_u64 v[14:15], v[14:15], 0, v[16:17]
	v_add_co_u32_e32 v16, vcc, s78, v20
	v_ashrrev_i32_e32 v19, 31, v18
	s_nop 0
	v_addc_co_u32_e32 v17, vcc, 0, v21, vcc
	v_add_co_u32_e32 v20, vcc, s78, v22
	v_lshl_add_u64 v[18:19], v[18:19], 2, s[8:9]
	s_nop 0
	v_addc_co_u32_e32 v21, vcc, 0, v23, vcc
	v_add_co_u32_e32 v22, vcc, s78, v24
	s_nop 1
	v_addc_co_u32_e32 v23, vcc, 0, v25, vcc
	v_add_co_u32_e32 v24, vcc, s78, v26
	s_nop 0
	v_addc_co_u32_e32 v25, vcc, 0, v27, vcc
	v_add_co_u32_e32 v26, vcc, s78, v28
	s_nop 1
	v_addc_co_u32_e32 v27, vcc, 0, v29, vcc
	v_add_co_u32_e32 v28, vcc, s78, v30
	s_nop 0
	v_addc_co_u32_e32 v29, vcc, 0, v31, vcc
	v_add_co_u32_e32 v30, vcc, s78, v32
	s_nop 1
	v_addc_co_u32_e32 v31, vcc, 0, v33, vcc
	v_add_co_u32_e32 v14, vcc, s78, v14
	global_load_dword v13, v[18:19], off
	global_load_dword v32, v[18:19], off offset:32
	global_load_dword v33, v[18:19], off offset:64
	global_load_dword v34, v[18:19], off offset:96
	global_load_dword v35, v[18:19], off offset:128
	global_load_dword v36, v[18:19], off offset:160
	global_load_dword v37, v[18:19], off offset:192
	global_load_dword v38, v[18:19], off offset:224
	v_addc_co_u32_e32 v15, vcc, 0, v15, vcc
	global_load_dword v39, v[16:17], off offset:2048
	global_load_dword v40, v[20:21], off offset:2048
	global_load_dword v41, v[22:23], off offset:2048
	global_load_dword v42, v[24:25], off offset:2048
	global_load_dword v43, v[26:27], off offset:2048
	global_load_dword v44, v[28:29], off offset:2048
	global_load_dword v45, v[30:31], off offset:2048
	global_load_dword v46, v[14:15], off offset:2048
	v_add_u32_e32 v14, s11, v3
	v_add_u32_e32 v16, s11, v5
	v_add_u32_e32 v18, s11, v6
	v_add_u32_e32 v20, s11, v7
	v_add_u32_e32 v22, s11, v8
	v_add_u32_e32 v24, s11, v9
	v_add_u32_e32 v26, s11, v10
	v_add_u32_e32 v28, s11, v11
	s_ashr_i32 s11, s10, 31
	v_ashrrev_i32_e32 v15, 31, v14
	v_ashrrev_i32_e32 v17, 31, v16
	v_ashrrev_i32_e32 v19, 31, v18
	v_ashrrev_i32_e32 v21, 31, v20
	v_ashrrev_i32_e32 v23, 31, v22
	v_ashrrev_i32_e32 v25, 31, v24
	v_ashrrev_i32_e32 v27, 31, v26
	v_ashrrev_i32_e32 v29, 31, v28
	v_lshl_add_u64 v[30:31], s[10:11], 1, v[0:1]
	v_lshlrev_b64 v[14:15], 11, v[14:15]
	v_lshlrev_b64 v[16:17], 11, v[16:17]
	v_lshlrev_b64 v[18:19], 11, v[18:19]
	v_lshlrev_b64 v[20:21], 11, v[20:21]
	v_lshlrev_b64 v[22:23], 11, v[22:23]
	v_lshlrev_b64 v[24:25], 11, v[24:25]
	v_lshlrev_b64 v[26:27], 11, v[26:27]
	v_lshlrev_b64 v[28:29], 11, v[28:29]
	v_lshl_add_u64 v[14:15], v[30:31], 0, v[14:15]
	v_lshl_add_u64 v[16:17], v[30:31], 0, v[16:17]
	v_lshl_add_u64 v[18:19], v[30:31], 0, v[18:19]
	v_lshl_add_u64 v[20:21], v[30:31], 0, v[20:21]
	v_lshl_add_u64 v[22:23], v[30:31], 0, v[22:23]
	v_lshl_add_u64 v[24:25], v[30:31], 0, v[24:25]
	v_lshl_add_u64 v[26:27], v[30:31], 0, v[26:27]
	v_lshl_add_u64 v[28:29], v[30:31], 0, v[28:29]
	s_add_i32 s98, s18, s5
	s_cmp_lt_i32 s98, 0x480
	s_cbranch_scc0 .Lcv316_p1skip
; __device__ __forceinline__ bf16_t f2bf(float f) { unsigned u = __float_as_uint(f); u += 0x7FFFu + ((u >> 16) & 1u); return (bf16_t)(u >> 16); }
;     ...
;     for (int t_ = first; t_ < ntile * ((REP & 1) + 1); t_ += gridDim.x) { const int t = t_ % ntile;
;         const int r0 = (t / nkt) * 64, k0 = (t % nkt) * 64;
;         __syncthreads();
; #pragma unroll
;         for (int i = 0; i < 8; ++i) { const int kk = i * 8 + w; tile[kk * 65 + lane] = src(k0 + kk, r0 + lane); }
;         __syncthreads();
; #pragma unroll
;         for (int i = 0; i < 8; ++i) { const int j = i * 8 + w; Bt[(size_t)(r0 + j) * ld + k0 + lane] = f2bf(tile[lane * 65 + j]); }
;     }
; __device__ void convert_phase(unsigned char* smem, const Params& p, int l) {
;     ...
;       conv_tiles(tile, wt + W_QKV, 4608, 1024, 113, [=](int k, int r) { return gn[k] * wi[(size_t)k * INC + HYC + r]; }); }
	s_lshr_b32 s99, s98, 8
	s_and_b32 s100, s98, 0xff
	s_mul_i32 s101, s100, 5
	s_sub_i32 s98, s100, 128
	s_mul_i32 s98, s98, 4
	s_add_i32 s98, s98, 640
	s_cmp_lt_u32 s100, 128
	s_cselect_b32 s98, s101, s98
	s_add_i32 s98, s98, s99
	s_mul_hi_u32 s99, s98, 0x38e38e4
	s_mul_i32 s100, s99, 72
	s_sub_i32 s98, s98, s100
	s_mul_i32 s98, s98, 16
	s_add_i32 s98, s98, s99
	s_mul_hi_i32 s10, s98, 0x38e38e39
	s_lshr_b32 s11, s10, 31
	s_ashr_i32 s10, s10, 8
	s_add_i32 s10, s10, s11
	s_mulk_i32 s10, 0x480
	s_sub_i32 s10, s98, s10
	s_sext_i32_i16 s11, s10
	s_bfe_u32 s11, s11, 0x4001b
	s_add_i32 s11, s10, s11
	s_sext_i32_i16 s19, s11
	s_and_b32 s11, s11, 0xfff0
	s_lshl_b32 s19, s19, 2
	s_sub_i32 s10, s10, s11
	s_and_b32 s11, s19, 0xffffffc0
	s_sext_i32_i16 s10, s10
	s_lshl_b32 s10, s10, 6
	v_or_b32_e32 v56, s11, v2
	v_mov_b64_e32 v[54:55], s[6:7]
	v_ashrrev_i32_e32 v57, 31, v56
	v_add_u32_e32 v58, s10, v3
	v_add_u32_e32 v53, s10, v5
	v_add_u32_e32 v64, s10, v6
	v_add_u32_e32 v66, s10, v7
	v_add_u32_e32 v68, s10, v8
	v_add_u32_e32 v70, s10, v9
	v_add_u32_e32 v72, s10, v10
	v_add_u32_e32 v74, s10, v11
	v_mad_i64_i32 v[60:61], s[20:21], v58, s94, v[54:55]
	v_lshlrev_b64 v[56:57], 2, v[56:57]
	v_mad_i64_i32 v[62:63], s[20:21], v53, s94, v[54:55]
	v_mad_i64_i32 v[64:65], s[20:21], v64, s94, v[54:55]
	v_mad_i64_i32 v[66:67], s[20:21], v66, s94, v[54:55]
	v_mad_i64_i32 v[68:69], s[20:21], v68, s94, v[54:55]
	v_mad_i64_i32 v[70:71], s[20:21], v70, s94, v[54:55]
	v_mad_i64_i32 v[72:73], s[20:21], v72, s94, v[54:55]
	v_mad_i64_i32 v[54:55], s[20:21], v74, s94, v[54:55]
	v_lshl_add_u64 v[60:61], v[60:61], 0, v[56:57]
	v_lshl_add_u64 v[62:63], v[62:63], 0, v[56:57]
	v_lshl_add_u64 v[64:65], v[64:65], 0, v[56:57]
	v_lshl_add_u64 v[66:67], v[66:67], 0, v[56:57]
	v_lshl_add_u64 v[68:69], v[68:69], 0, v[56:57]
	v_lshl_add_u64 v[70:71], v[70:71], 0, v[56:57]
	v_lshl_add_u64 v[72:73], v[72:73], 0, v[56:57]
	v_lshl_add_u64 v[54:55], v[54:55], 0, v[56:57]
	v_add_co_u32_e32 v56, vcc, s78, v60
	v_ashrrev_i32_e32 v59, 31, v58
	s_nop 0
	v_addc_co_u32_e32 v57, vcc, 0, v61, vcc
	v_add_co_u32_e32 v60, vcc, s78, v62
	v_lshl_add_u64 v[58:59], v[58:59], 2, s[8:9]
	s_nop 0
	v_addc_co_u32_e32 v61, vcc, 0, v63, vcc
	v_add_co_u32_e32 v62, vcc, s78, v64
	s_nop 1
	v_addc_co_u32_e32 v63, vcc, 0, v65, vcc
	v_add_co_u32_e32 v64, vcc, s78, v66
	s_nop 0
	v_addc_co_u32_e32 v65, vcc, 0, v67, vcc
	v_add_co_u32_e32 v66, vcc, s78, v68
	s_nop 1
	v_addc_co_u32_e32 v67, vcc, 0, v69, vcc
	v_add_co_u32_e32 v68, vcc, s78, v70
	s_nop 0
	v_addc_co_u32_e32 v69, vcc, 0, v71, vcc
	v_add_co_u32_e32 v70, vcc, s78, v72
	s_nop 1
	v_addc_co_u32_e32 v71, vcc, 0, v73, vcc
	v_add_co_u32_e32 v54, vcc, s78, v54
	global_load_dword v53, v[58:59], off
	global_load_dword v72, v[58:59], off offset:32
	global_load_dword v73, v[58:59], off offset:64
	global_load_dword v74, v[58:59], off offset:96
	global_load_dword v75, v[58:59], off offset:128
	global_load_dword v76, v[58:59], off offset:160
	global_load_dword v77, v[58:59], off offset:192
	global_load_dword v78, v[58:59], off offset:224
	v_addc_co_u32_e32 v55, vcc, 0, v55, vcc
	global_load_dword v79, v[56:57], off offset:2048
	global_load_dword v80, v[60:61], off offset:2048
	global_load_dword v81, v[62:63], off offset:2048
	global_load_dword v82, v[64:65], off offset:2048
	global_load_dword v83, v[66:67], off offset:2048
	global_load_dword v84, v[68:69], off offset:2048
	global_load_dword v85, v[70:71], off offset:2048
	global_load_dword v86, v[54:55], off offset:2048
	v_add_u32_e32 v54, s11, v3
	v_add_u32_e32 v56, s11, v5
	v_add_u32_e32 v58, s11, v6
	v_add_u32_e32 v60, s11, v7
	v_add_u32_e32 v62, s11, v8
	v_add_u32_e32 v64, s11, v9
	v_add_u32_e32 v66, s11, v10
	v_add_u32_e32 v68, s11, v11
	s_ashr_i32 s11, s10, 31
	v_ashrrev_i32_e32 v55, 31, v54
	v_ashrrev_i32_e32 v57, 31, v56
	v_ashrrev_i32_e32 v59, 31, v58
	v_ashrrev_i32_e32 v61, 31, v60
	v_ashrrev_i32_e32 v63, 31, v62
	v_ashrrev_i32_e32 v65, 31, v64
	v_ashrrev_i32_e32 v67, 31, v66
	v_ashrrev_i32_e32 v69, 31, v68
	v_lshl_add_u64 v[70:71], s[10:11], 1, v[0:1]
	v_lshlrev_b64 v[54:55], 11, v[54:55]
	v_lshlrev_b64 v[56:57], 11, v[56:57]
	v_lshlrev_b64 v[58:59], 11, v[58:59]
	v_lshlrev_b64 v[60:61], 11, v[60:61]
	v_lshlrev_b64 v[62:63], 11, v[62:63]
	v_lshlrev_b64 v[64:65], 11, v[64:65]
	v_lshlrev_b64 v[66:67], 11, v[66:67]
	v_lshlrev_b64 v[68:69], 11, v[68:69]
	v_lshl_add_u64 v[54:55], v[70:71], 0, v[54:55]
	v_lshl_add_u64 v[56:57], v[70:71], 0, v[56:57]
	v_lshl_add_u64 v[58:59], v[70:71], 0, v[58:59]
	v_lshl_add_u64 v[60:61], v[70:71], 0, v[60:61]
	v_lshl_add_u64 v[62:63], v[70:71], 0, v[62:63]
	v_lshl_add_u64 v[64:65], v[70:71], 0, v[64:65]
	v_lshl_add_u64 v[66:67], v[70:71], 0, v[66:67]
	v_lshl_add_u64 v[68:69], v[70:71], 0, v[68:69]
	s_waitcnt vmcnt(16)
	s_branch .Lcv316_pj

; __device__ __forceinline__ bf16_t f2bf(float f) { unsigned u = __float_as_uint(f); u += 0x7FFFu + ((u >> 16) & 1u); return (bf16_t)(u >> 16); }
;     ...
;     for (int t_ = first; t_ < ntile * ((REP & 1) + 1); t_ += gridDim.x) { const int t = t_ % ntile;
;         const int r0 = (t / nkt) * 64, k0 = (t % nkt) * 64;
;         __syncthreads();
; #pragma unroll
;         for (int i = 0; i < 8; ++i) { const int kk = i * 8 + w; tile[kk * 65 + lane] = src(k0 + kk, r0 + lane); }
;         __syncthreads();
; #pragma unroll
;         for (int i = 0; i < 8; ++i) { const int j = i * 8 + w; Bt[(size_t)(r0 + j) * ld + k0 + lane] = f2bf(tile[lane * 65 + j]); }
;     }
; __device__ void convert_phase(unsigned char* smem, const Params& p, int l) {
;     ...
;       conv_tiles(tile, wt + W_QKV, 4608, 1024, 113, [=](int k, int r) { return gn[k] * wi[(size_t)k * INC + HYC + r]; }); }
.Lcv316_top:
	s_waitcnt vmcnt(31)
	v_mul_f32_e32 v13, v13, v39
	s_waitcnt vmcnt(30)
	v_mul_f32_e32 v30, v32, v40
	s_waitcnt vmcnt(29)
	v_mul_f32_e32 v31, v33, v41
	s_waitcnt vmcnt(28)
	v_mul_f32_e32 v32, v34, v42
	s_waitcnt vmcnt(27)
	v_mul_f32_e32 v33, v35, v43
	s_waitcnt vmcnt(26)
	v_mul_f32_e32 v34, v36, v44
	s_waitcnt vmcnt(25)
	v_mul_f32_e32 v35, v37, v45
	s_waitcnt vmcnt(24)
	v_mul_f32_e32 v36, v38, v46
	ds_write_b32 v12, v13
	ds_write_b32 v12, v30 offset:2080
	ds_write_b32 v12, v31 offset:4160
	ds_write_b32 v12, v32 offset:6240
	ds_write_b32 v12, v33 offset:8320
	ds_write_b32 v12, v34 offset:10400
	ds_write_b32 v12, v35 offset:12480
	ds_write_b32 v12, v36 offset:14560
	s_waitcnt lgkmcnt(0)
	s_barrier
	ds_read2_b32 v[30:31], v4 offset1:8
	ds_read2_b32 v[32:33], v4 offset0:16 offset1:24
	ds_read2_b32 v[34:35], v4 offset0:32 offset1:40
	ds_read2_b32 v[36:37], v4 offset0:48 offset1:56
	s_waitcnt lgkmcnt(3)
	v_bfe_u32 v13, v30, 16, 1
	v_bfe_u32 v38, v31, 16, 1
	s_waitcnt lgkmcnt(2)
	v_bfe_u32 v39, v32, 16, 1
	v_bfe_u32 v40, v33, 16, 1
	s_waitcnt lgkmcnt(1)
	v_bfe_u32 v41, v34, 16, 1
	v_bfe_u32 v42, v35, 16, 1
	s_waitcnt lgkmcnt(0)
	v_bfe_u32 v43, v36, 16, 1
	v_bfe_u32 v44, v37, 16, 1
	v_add3_u32 v13, v30, v13, s88
	v_add3_u32 v30, v31, v38, s88
	v_add3_u32 v31, v32, v39, s88
	v_add3_u32 v32, v33, v40, s88
	v_add3_u32 v33, v34, v41, s88
	v_add3_u32 v34, v35, v42, s88
	v_add3_u32 v35, v36, v43, s88
	v_add3_u32 v36, v37, v44, s88
	global_store_short_d16_hi v[14:15], v13, off
	global_store_short_d16_hi v[16:17], v30, off
	global_store_short_d16_hi v[18:19], v31, off
	global_store_short_d16_hi v[20:21], v32, off
	global_store_short_d16_hi v[22:23], v33, off
	global_store_short_d16_hi v[24:25], v34, off
	global_store_short_d16_hi v[26:27], v35, off
	global_store_short_d16_hi v[28:29], v36, off
	s_lshl_b32 s98, s5, 1
	s_add_i32 s98, s98, s18
	s_cmp_lt_i32 s98, 0x480
	s_cbranch_scc0 .Lcv316_s0
	s_lshr_b32 s99, s98, 8
	s_and_b32 s100, s98, 0xff
	s_mul_i32 s101, s100, 5
	s_sub_i32 s98, s100, 128
	s_mul_i32 s98, s98, 4
	s_add_i32 s98, s98, 640
	s_cmp_lt_u32 s100, 128
	s_cselect_b32 s98, s101, s98
	s_add_i32 s98, s98, s99
	s_mul_hi_u32 s99, s98, 0x38e38e4
	s_mul_i32 s100, s99, 72
	s_sub_i32 s98, s98, s100
	s_mul_i32 s98, s98, 16
	s_add_i32 s98, s98, s99
	s_mul_hi_i32 s10, s98, 0x38e38e39
	s_lshr_b32 s11, s10, 31
	s_ashr_i32 s10, s10, 8
	s_add_i32 s10, s10, s11
	s_mulk_i32 s10, 0x480
	s_sub_i32 s10, s98, s10
	s_sext_i32_i16 s11, s10
	s_bfe_u32 s11, s11, 0x4001b
	s_add_i32 s11, s10, s11
	s_sext_i32_i16 s19, s11
	s_and_b32 s11, s11, 0xfff0
	s_lshl_b32 s19, s19, 2
	s_sub_i32 s10, s10, s11
	s_and_b32 s11, s19, 0xffffffc0
	s_sext_i32_i16 s10, s10
	s_lshl_b32 s10, s10, 6
	v_or_b32_e32 v16, s11, v2
	v_mov_b64_e32 v[14:15], s[6:7]
	v_ashrrev_i32_e32 v17, 31, v16
	v_add_u32_e32 v18, s10, v3
	v_add_u32_e32 v13, s10, v5
	v_add_u32_e32 v24, s10, v6
	v_add_u32_e32 v26, s10, v7
	v_add_u32_e32 v28, s10, v8
	v_add_u32_e32 v30, s10, v9
	v_add_u32_e32 v32, s10, v10
	v_add_u32_e32 v34, s10, v11
	v_mad_i64_i32 v[20:21], s[20:21], v18, s94, v[14:15]
	v_lshlrev_b64 v[16:17], 2, v[16:17]
	v_mad_i64_i32 v[22:23], s[20:21], v13, s94, v[14:15]
	v_mad_i64_i32 v[24:25], s[20:21], v24, s94, v[14:15]
	v_mad_i64_i32 v[26:27], s[20:21], v26, s94, v[14:15]
	v_mad_i64_i32 v[28:29], s[20:21], v28, s94, v[14:15]
	v_mad_i64_i32 v[30:31], s[20:21], v30, s94, v[14:15]
	v_mad_i64_i32 v[32:33], s[20:21], v32, s94, v[14:15]
	v_mad_i64_i32 v[14:15], s[20:21], v34, s94, v[14:15]
	v_lshl_add_u64 v[20:21], v[20:21], 0, v[16:17]
	v_lshl_add_u64 v[22:23], v[22:23], 0, v[16:17]
	v_lshl_add_u64 v[24:25], v[24:25], 0, v[16:17]
	v_lshl_add_u64 v[26:27], v[26:27], 0, v[16:17]
	v_lshl_add_u64 v[28:29], v[28:29], 0, v[16:17]
	v_lshl_add_u64 v[30:31], v[30:31], 0, v[16:17]
	v_lshl_add_u64 v[32:33], v[32:33], 0, v[16:17]
	v_lshl_add_u64 v[14:15], v[14:15], 0, v[16:17]
	v_add_co_u32_e32 v16, vcc, s78, v20
	v_ashrrev_i32_e32 v19, 31, v18
	s_nop 0
	v_addc_co_u32_e32 v17, vcc, 0, v21, vcc
	v_add_co_u32_e32 v20, vcc, s78, v22
	v_lshl_add_u64 v[18:19], v[18:19], 2, s[8:9]
	s_nop 0
	v_addc_co_u32_e32 v21, vcc, 0, v23, vcc
	v_add_co_u32_e32 v22, vcc, s78, v24
	s_nop 1
	v_addc_co_u32_e32 v23, vcc, 0, v25, vcc
	v_add_co_u32_e32 v24, vcc, s78, v26
	s_nop 0
	v_addc_co_u32_e32 v25, vcc, 0, v27, vcc
	v_add_co_u32_e32 v26, vcc, s78, v28
	s_nop 1
	v_addc_co_u32_e32 v27, vcc, 0, v29, vcc
	v_add_co_u32_e32 v28, vcc, s78, v30
	s_nop 0
	v_addc_co_u32_e32 v29, vcc, 0, v31, vcc
	v_add_co_u32_e32 v30, vcc, s78, v32
	s_nop 1
	v_addc_co_u32_e32 v31, vcc, 0, v33, vcc
	v_add_co_u32_e32 v14, vcc, s78, v14
	global_load_dword v13, v[18:19], off
	global_load_dword v32, v[18:19], off offset:32
	global_load_dword v33, v[18:19], off offset:64
	global_load_dword v34, v[18:19], off offset:96
	global_load_dword v35, v[18:19], off offset:128
	global_load_dword v36, v[18:19], off offset:160
	global_load_dword v37, v[18:19], off offset:192
	global_load_dword v38, v[18:19], off offset:224
	v_addc_co_u32_e32 v15, vcc, 0, v15, vcc
	global_load_dword v39, v[16:17], off offset:2048
	global_load_dword v40, v[20:21], off offset:2048
	global_load_dword v41, v[22:23], off offset:2048
	global_load_dword v42, v[24:25], off offset:2048
	global_load_dword v43, v[26:27], off offset:2048
	global_load_dword v44, v[28:29], off offset:2048
	global_load_dword v45, v[30:31], off offset:2048
	global_load_dword v46, v[14:15], off offset:2048
	v_add_u32_e32 v14, s11, v3
	v_add_u32_e32 v16, s11, v5
	v_add_u32_e32 v18, s11, v6
	v_add_u32_e32 v20, s11, v7
	v_add_u32_e32 v22, s11, v8
	v_add_u32_e32 v24, s11, v9
	v_add_u32_e32 v26, s11, v10
	v_add_u32_e32 v28, s11, v11
	s_ashr_i32 s11, s10, 31
	v_ashrrev_i32_e32 v15, 31, v14
	v_ashrrev_i32_e32 v17, 31, v16
	v_ashrrev_i32_e32 v19, 31, v18
	v_ashrrev_i32_e32 v21, 31, v20
	v_ashrrev_i32_e32 v23, 31, v22
	v_ashrrev_i32_e32 v25, 31, v24
	v_ashrrev_i32_e32 v27, 31, v26
	v_ashrrev_i32_e32 v29, 31, v28
	v_lshl_add_u64 v[30:31], s[10:11], 1, v[0:1]
	v_lshlrev_b64 v[14:15], 11, v[14:15]
	v_lshlrev_b64 v[16:17], 11, v[16:17]
	v_lshlrev_b64 v[18:19], 11, v[18:19]
	v_lshlrev_b64 v[20:21], 11, v[20:21]
	v_lshlrev_b64 v[22:23], 11, v[22:23]
	v_lshlrev_b64 v[24:25], 11, v[24:25]
	v_lshlrev_b64 v[26:27], 11, v[26:27]
	v_lshlrev_b64 v[28:29], 11, v[28:29]
	v_lshl_add_u64 v[14:15], v[30:31], 0, v[14:15]
	v_lshl_add_u64 v[16:17], v[30:31], 0, v[16:17]
	v_lshl_add_u64 v[18:19], v[30:31], 0, v[18:19]
	v_lshl_add_u64 v[20:21], v[30:31], 0, v[20:21]
	v_lshl_add_u64 v[22:23], v[30:31], 0, v[22:23]
	v_lshl_add_u64 v[24:25], v[30:31], 0, v[24:25]
	v_lshl_add_u64 v[26:27], v[30:31], 0, v[26:27]
	v_lshl_add_u64 v[28:29], v[30:31], 0, v[28:29]
	s_branch .Lcv316_n0

; __device__ __forceinline__ bf16_t f2bf(float f) { unsigned u = __float_as_uint(f); u += 0x7FFFu + ((u >> 16) & 1u); return (bf16_t)(u >> 16); }
;     ...
;     for (int t_ = first; t_ < ntile * ((REP & 1) + 1); t_ += gridDim.x) { const int t = t_ % ntile;
;         const int r0 = (t / nkt) * 64, k0 = (t % nkt) * 64;
;         __syncthreads();
; #pragma unroll
;         for (int i = 0; i < 8; ++i) { const int kk = i * 8 + w; tile[kk * 65 + lane] = src(k0 + kk, r0 + lane); }
;         __syncthreads();
; #pragma unroll
;         for (int i = 0; i < 8; ++i) { const int j = i * 8 + w; Bt[(size_t)(r0 + j) * ld + k0 + lane] = f2bf(tile[lane * 65 + j]); }
;     }
; __device__ void convert_phase(unsigned char* smem, const Params& p, int l) {
;     ...
;       conv_tiles(tile, wt + W_QKV, 4608, 1024, 113, [=](int k, int r) { return gn[k] * wi[(size_t)k * INC + HYC + r]; }); }
.Lcv316_n0:
	s_add_i32 s18, s18, s5
	s_cmp_lt_i32 s18, 0x480
	s_cbranch_scc0 .LBB0_317
	s_waitcnt vmcnt(31)
	v_mul_f32_e32 v53, v53, v79
	s_waitcnt vmcnt(30)
	v_mul_f32_e32 v70, v72, v80
	s_waitcnt vmcnt(29)
	v_mul_f32_e32 v71, v73, v81
	s_waitcnt vmcnt(28)
	v_mul_f32_e32 v72, v74, v82
	s_waitcnt vmcnt(27)
	v_mul_f32_e32 v73, v75, v83
	s_waitcnt vmcnt(26)
	v_mul_f32_e32 v74, v76, v84
	s_waitcnt vmcnt(25)
	v_mul_f32_e32 v75, v77, v85
	s_waitcnt vmcnt(24)
	v_mul_f32_e32 v76, v78, v86
	ds_write_b32 v12, v53 offset:17408
	ds_write_b32 v12, v70 offset:19488
	ds_write_b32 v12, v71 offset:21568
	ds_write_b32 v12, v72 offset:23648
	ds_write_b32 v12, v73 offset:25728
	ds_write_b32 v12, v74 offset:27808
	ds_write_b32 v12, v75 offset:29888
	ds_write_b32 v12, v76 offset:31968
	s_waitcnt lgkmcnt(0)
	s_barrier
	ds_read2_b32 v[70:71], v95 offset1:8
	ds_read2_b32 v[72:73], v95 offset0:16 offset1:24
	ds_read2_b32 v[74:75], v95 offset0:32 offset1:40
	ds_read2_b32 v[76:77], v95 offset0:48 offset1:56
	s_waitcnt lgkmcnt(3)
	v_bfe_u32 v53, v70, 16, 1
	v_bfe_u32 v78, v71, 16, 1
	s_waitcnt lgkmcnt(2)
	v_bfe_u32 v79, v72, 16, 1
	v_bfe_u32 v80, v73, 16, 1
	s_waitcnt lgkmcnt(1)
	v_bfe_u32 v81, v74, 16, 1
	v_bfe_u32 v82, v75, 16, 1
	s_waitcnt lgkmcnt(0)
	v_bfe_u32 v83, v76, 16, 1
	v_bfe_u32 v84, v77, 16, 1
	v_add3_u32 v53, v70, v53, s88
	v_add3_u32 v70, v71, v78, s88
	v_add3_u32 v71, v72, v79, s88
	v_add3_u32 v72, v73, v80, s88
	v_add3_u32 v73, v74, v81, s88
	v_add3_u32 v74, v75, v82, s88
	v_add3_u32 v75, v76, v83, s88
	v_add3_u32 v76, v77, v84, s88
	global_store_short_d16_hi v[54:55], v53, off
	global_store_short_d16_hi v[56:57], v70, off
	global_store_short_d16_hi v[58:59], v71, off
	global_store_short_d16_hi v[60:61], v72, off
	global_store_short_d16_hi v[62:63], v73, off
	global_store_short_d16_hi v[64:65], v74, off
	global_store_short_d16_hi v[66:67], v75, off
	global_store_short_d16_hi v[68:69], v76, off
	s_lshl_b32 s98, s5, 1
	s_add_i32 s98, s98, s18
	s_cmp_lt_i32 s98, 0x480
	s_cbranch_scc0 .Lcv316_s1
	s_lshr_b32 s99, s98, 8
	s_and_b32 s100, s98, 0xff
	s_mul_i32 s101, s100, 5
	s_sub_i32 s98, s100, 128
	s_mul_i32 s98, s98, 4
	s_add_i32 s98, s98, 640
	s_cmp_lt_u32 s100, 128
	s_cselect_b32 s98, s101, s98
	s_add_i32 s98, s98, s99
	s_mul_hi_u32 s99, s98, 0x38e38e4
	s_mul_i32 s100, s99, 72
	s_sub_i32 s98, s98, s100
	s_mul_i32 s98, s98, 16
	s_add_i32 s98, s98, s99
	s_mul_hi_i32 s10, s98, 0x38e38e39
	s_lshr_b32 s11, s10, 31
	s_ashr_i32 s10, s10, 8
	s_add_i32 s10, s10, s11
	s_mulk_i32 s10, 0x480
	s_sub_i32 s10, s98, s10
	s_sext_i32_i16 s11, s10
	s_bfe_u32 s11, s11, 0x4001b
	s_add_i32 s11, s10, s11
	s_sext_i32_i16 s19, s11
	s_and_b32 s11, s11, 0xfff0
	s_lshl_b32 s19, s19, 2
	s_sub_i32 s10, s10, s11
	s_and_b32 s11, s19, 0xffffffc0
	s_sext_i32_i16 s10, s10
	s_lshl_b32 s10, s10, 6
	v_or_b32_e32 v56, s11, v2
	v_mov_b64_e32 v[54:55], s[6:7]
	v_ashrrev_i32_e32 v57, 31, v56
	v_add_u32_e32 v58, s10, v3
	v_add_u32_e32 v53, s10, v5
	v_add_u32_e32 v64, s10, v6
	v_add_u32_e32 v66, s10, v7
	v_add_u32_e32 v68, s10, v8
	v_add_u32_e32 v70, s10, v9
	v_add_u32_e32 v72, s10, v10
	v_add_u32_e32 v74, s10, v11
	v_mad_i64_i32 v[60:61], s[20:21], v58, s94, v[54:55]
	v_lshlrev_b64 v[56:57], 2, v[56:57]
	v_mad_i64_i32 v[62:63], s[20:21], v53, s94, v[54:55]
	v_mad_i64_i32 v[64:65], s[20:21], v64, s94, v[54:55]
	v_mad_i64_i32 v[66:67], s[20:21], v66, s94, v[54:55]
	v_mad_i64_i32 v[68:69], s[20:21], v68, s94, v[54:55]
	v_mad_i64_i32 v[70:71], s[20:21], v70, s94, v[54:55]
	v_mad_i64_i32 v[72:73], s[20:21], v72, s94, v[54:55]
	v_mad_i64_i32 v[54:55], s[20:21], v74, s94, v[54:55]
	v_lshl_add_u64 v[60:61], v[60:61], 0, v[56:57]
	v_lshl_add_u64 v[62:63], v[62:63], 0, v[56:57]
	v_lshl_add_u64 v[64:65], v[64:65], 0, v[56:57]
	v_lshl_add_u64 v[66:67], v[66:67], 0, v[56:57]
	v_lshl_add_u64 v[68:69], v[68:69], 0, v[56:57]
	v_lshl_add_u64 v[70:71], v[70:71], 0, v[56:57]
	v_lshl_add_u64 v[72:73], v[72:73], 0, v[56:57]
	v_lshl_add_u64 v[54:55], v[54:55], 0, v[56:57]
	v_add_co_u32_e32 v56, vcc, s78, v60
	v_ashrrev_i32_e32 v59, 31, v58
	s_nop 0
	v_addc_co_u32_e32 v57, vcc, 0, v61, vcc
	v_add_co_u32_e32 v60, vcc, s78, v62
	v_lshl_add_u64 v[58:59], v[58:59], 2, s[8:9]
	s_nop 0
	v_addc_co_u32_e32 v61, vcc, 0, v63, vcc
	v_add_co_u32_e32 v62, vcc, s78, v64
	s_nop 1
	v_addc_co_u32_e32 v63, vcc, 0, v65, vcc
	v_add_co_u32_e32 v64, vcc, s78, v66
	s_nop 0
	v_addc_co_u32_e32 v65, vcc, 0, v67, vcc
	v_add_co_u32_e32 v66, vcc, s78, v68
	s_nop 1
	v_addc_co_u32_e32 v67, vcc, 0, v69, vcc
	v_add_co_u32_e32 v68, vcc, s78, v70
	s_nop 0
	v_addc_co_u32_e32 v69, vcc, 0, v71, vcc
	v_add_co_u32_e32 v70, vcc, s78, v72
	s_nop 1
	v_addc_co_u32_e32 v71, vcc, 0, v73, vcc
	v_add_co_u32_e32 v54, vcc, s78, v54
	global_load_dword v53, v[58:59], off
	global_load_dword v72, v[58:59], off offset:32
	global_load_dword v73, v[58:59], off offset:64
	global_load_dword v74, v[58:59], off offset:96
	global_load_dword v75, v[58:59], off offset:128
	global_load_dword v76, v[58:59], off offset:160
	global_load_dword v77, v[58:59], off offset:192
	global_load_dword v78, v[58:59], off offset:224
	v_addc_co_u32_e32 v55, vcc, 0, v55, vcc
	global_load_dword v79, v[56:57], off offset:2048
	global_load_dword v80, v[60:61], off offset:2048
	global_load_dword v81, v[62:63], off offset:2048
	global_load_dword v82, v[64:65], off offset:2048
	global_load_dword v83, v[66:67], off offset:2048
	global_load_dword v84, v[68:69], off offset:2048
	global_load_dword v85, v[70:71], off offset:2048
	global_load_dword v86, v[54:55], off offset:2048
	v_add_u32_e32 v54, s11, v3
	v_add_u32_e32 v56, s11, v5
	v_add_u32_e32 v58, s11, v6
	v_add_u32_e32 v60, s11, v7
	v_add_u32_e32 v62, s11, v8
	v_add_u32_e32 v64, s11, v9
	v_add_u32_e32 v66, s11, v10
	v_add_u32_e32 v68, s11, v11
	s_ashr_i32 s11, s10, 31
	v_ashrrev_i32_e32 v55, 31, v54
	v_ashrrev_i32_e32 v57, 31, v56
	v_ashrrev_i32_e32 v59, 31, v58
	v_ashrrev_i32_e32 v61, 31, v60
	v_ashrrev_i32_e32 v63, 31, v62
	v_ashrrev_i32_e32 v65, 31, v64
	v_ashrrev_i32_e32 v67, 31, v66
	v_ashrrev_i32_e32 v69, 31, v68
	v_lshl_add_u64 v[70:71], s[10:11], 1, v[0:1]
	v_lshlrev_b64 v[54:55], 11, v[54:55]
	v_lshlrev_b64 v[56:57], 11, v[56:57]
	v_lshlrev_b64 v[58:59], 11, v[58:59]
	v_lshlrev_b64 v[60:61], 11, v[60:61]
	v_lshlrev_b64 v[62:63], 11, v[62:63]
	v_lshlrev_b64 v[64:65], 11, v[64:65]
	v_lshlrev_b64 v[66:67], 11, v[66:67]
	v_lshlrev_b64 v[68:69], 11, v[68:69]
	v_lshl_add_u64 v[54:55], v[70:71], 0, v[54:55]
	v_lshl_add_u64 v[56:57], v[70:71], 0, v[56:57]
	v_lshl_add_u64 v[58:59], v[70:71], 0, v[58:59]
	v_lshl_add_u64 v[60:61], v[70:71], 0, v[60:61]
	v_lshl_add_u64 v[62:63], v[70:71], 0, v[62:63]
	v_lshl_add_u64 v[64:65], v[70:71], 0, v[64:65]
	v_lshl_add_u64 v[66:67], v[70:71], 0, v[66:67]
	v_lshl_add_u64 v[68:69], v[70:71], 0, v[68:69]
	s_branch .Lcv316_n1

; __device__ __forceinline__ bf16_t f2bf(float f) { unsigned u = __float_as_uint(f); u += 0x7FFFu + ((u >> 16) & 1u); return (bf16_t)(u >> 16); }
;     ...
;     for (int t_ = first; t_ < ntile * ((REP & 1) + 1); t_ += gridDim.x) { const int t = t_ % ntile;
;         const int r0 = (t / nkt) * 64, k0 = (t % nkt) * 64;
;         __syncthreads();
; #pragma unroll
;         for (int i = 0; i < 8; ++i) { const int kk = i * 8 + w; tile[kk * 65 + lane] = src(k0 + kk, r0 + lane); }
;         __syncthreads();
; #pragma unroll
;         for (int i = 0; i < 8; ++i) { const int j = i * 8 + w; Bt[(size_t)(r0 + j) * ld + k0 + lane] = f2bf(tile[lane * 65 + j]); }
;     }
; __device__ void convert_phase(unsigned char* smem, const Params& p, int l) {
;     ...
;     { const float* wgt = ((const float*)ldp(26)) + (size_t)l * DM * 3072; const float* gn = ((const float*)ldp(5)) + l * DM; conv_tiles(tile, wt + W_GATE, 3072, 1024, 151, [=](int k, int r) { return gn[k] * wgt[(size_t)k * 3072 + r]; }); }
.LBB0_319:
	s_mov_b32 s98, s17
	s_lshr_b32 s99, s98, 8
	s_and_b32 s100, s98, 0xff
	s_mul_i32 s101, s100, 3
	s_sub_i32 s98, s100, 256
	s_mul_i32 s98, s98, 2
	s_add_i32 s98, s98, 768
	s_cmp_lt_u32 s100, 256
	s_cselect_b32 s98, s101, s98
	s_add_i32 s98, s98, s99
	s_mul_hi_u32 s99, s98, 0x5555556
	s_mul_i32 s100, s99, 48
	s_sub_i32 s98, s98, s100
	s_mul_i32 s98, s98, 16
	s_add_i32 s98, s98, s99
	s_mul_hi_i32 s10, s98, 0x2aaaaaab
	s_lshr_b32 s11, s10, 31
	s_lshr_b32 s10, s10, 7
	s_add_i32 s10, s10, s11
	s_mulk_i32 s10, 0x300
	s_sub_i32 s10, s98, s10
	s_sext_i32_i16 s11, s10
	s_bfe_u32 s11, s11, 0x4001b
	s_add_i32 s11, s10, s11
	s_sext_i32_i16 s18, s11
	s_and_b32 s11, s11, 0xfff0
	s_sub_i32 s10, s10, s11
	s_lshl_b32 s18, s18, 2
	s_sext_i32_i16 s10, s10
	s_and_b32 s11, s18, 0xffffffc0
	s_lshl_b32 s10, s10, 6
	v_or_b32_e32 v14, s11, v2
	v_add_u32_e32 v16, s10, v3
	v_ashrrev_i32_e32 v15, 31, v14
	v_ashrrev_i32_e32 v17, 31, v16
	v_add_u32_e32 v13, s10, v5
	v_add_u32_e32 v22, s10, v6
	v_add_u32_e32 v24, s10, v7
	v_add_u32_e32 v26, s10, v8
	v_add_u32_e32 v28, s10, v9
	v_add_u32_e32 v30, s10, v10
	v_add_u32_e32 v32, s10, v11
	v_lshl_add_u64 v[14:15], v[14:15], 2, s[6:7]
	v_lshl_add_u64 v[18:19], v[16:17], 2, s[8:9]
	v_mad_i64_i32 v[16:17], s[18:19], v16, s79, v[14:15]
	v_mad_i64_i32 v[20:21], s[18:19], v13, s79, v[14:15]
	v_mad_i64_i32 v[22:23], s[18:19], v22, s79, v[14:15]
	v_mad_i64_i32 v[24:25], s[18:19], v24, s79, v[14:15]
	v_mad_i64_i32 v[26:27], s[18:19], v26, s79, v[14:15]
	v_mad_i64_i32 v[28:29], s[18:19], v28, s79, v[14:15]
	v_mad_i64_i32 v[30:31], s[18:19], v30, s79, v[14:15]
	v_mad_i64_i32 v[14:15], s[18:19], v32, s79, v[14:15]
	global_load_dword v13, v[18:19], off
	global_load_dword v32, v[18:19], off offset:32
	global_load_dword v33, v[18:19], off offset:64
	global_load_dword v34, v[18:19], off offset:96
	global_load_dword v35, v[18:19], off offset:128
	global_load_dword v36, v[18:19], off offset:160
	global_load_dword v37, v[18:19], off offset:192
	global_load_dword v38, v[18:19], off offset:224
	global_load_dword v39, v[16:17], off
	global_load_dword v40, v[20:21], off
	global_load_dword v41, v[22:23], off
	global_load_dword v42, v[24:25], off
	global_load_dword v43, v[26:27], off
	global_load_dword v44, v[28:29], off
	global_load_dword v45, v[30:31], off
	global_load_dword v46, v[14:15], off
	v_add_u32_e32 v14, s11, v3
	v_add_u32_e32 v16, s11, v5
	v_add_u32_e32 v18, s11, v6
	v_add_u32_e32 v20, s11, v7
	v_add_u32_e32 v22, s11, v8
	v_add_u32_e32 v24, s11, v9
	v_add_u32_e32 v26, s11, v10
	v_add_u32_e32 v28, s11, v11
	s_ashr_i32 s11, s10, 31
	v_ashrrev_i32_e32 v15, 31, v14
	v_ashrrev_i32_e32 v17, 31, v16
	v_ashrrev_i32_e32 v19, 31, v18
	v_ashrrev_i32_e32 v21, 31, v20
	v_ashrrev_i32_e32 v23, 31, v22
	v_ashrrev_i32_e32 v25, 31, v24
	v_ashrrev_i32_e32 v27, 31, v26
	v_ashrrev_i32_e32 v29, 31, v28
	v_lshl_add_u64 v[30:31], s[10:11], 1, v[0:1]
	v_lshlrev_b64 v[14:15], 11, v[14:15]
	v_lshlrev_b64 v[16:17], 11, v[16:17]
	v_lshlrev_b64 v[18:19], 11, v[18:19]
	v_lshlrev_b64 v[20:21], 11, v[20:21]
	v_lshlrev_b64 v[22:23], 11, v[22:23]
	v_lshlrev_b64 v[24:25], 11, v[24:25]
	v_lshlrev_b64 v[26:27], 11, v[26:27]
	v_lshlrev_b64 v[28:29], 11, v[28:29]
	v_lshl_add_u64 v[14:15], v[30:31], 0, v[14:15]
	v_lshl_add_u64 v[16:17], v[30:31], 0, v[16:17]
	v_lshl_add_u64 v[18:19], v[30:31], 0, v[18:19]
	v_lshl_add_u64 v[20:21], v[30:31], 0, v[20:21]
	v_lshl_add_u64 v[22:23], v[30:31], 0, v[22:23]
	v_lshl_add_u64 v[24:25], v[30:31], 0, v[24:25]
	v_lshl_add_u64 v[26:27], v[30:31], 0, v[26:27]
	v_lshl_add_u64 v[28:29], v[30:31], 0, v[28:29]
	s_add_i32 s98, s17, s5
	s_cmp_lt_i32 s98, 0x300
	s_cbranch_scc0 .Lcv319_p1skip
; __device__ __forceinline__ bf16_t f2bf(float f) { unsigned u = __float_as_uint(f); u += 0x7FFFu + ((u >> 16) & 1u); return (bf16_t)(u >> 16); }
;     ...
;     for (int t_ = first; t_ < ntile * ((REP & 1) + 1); t_ += gridDim.x) { const int t = t_ % ntile;
;         const int r0 = (t / nkt) * 64, k0 = (t % nkt) * 64;
;         __syncthreads();
; #pragma unroll
;         for (int i = 0; i < 8; ++i) { const int kk = i * 8 + w; tile[kk * 65 + lane] = src(k0 + kk, r0 + lane); }
;         __syncthreads();
; #pragma unroll
;         for (int i = 0; i < 8; ++i) { const int j = i * 8 + w; Bt[(size_t)(r0 + j) * ld + k0 + lane] = f2bf(tile[lane * 65 + j]); }
;     }
; __device__ void convert_phase(unsigned char* smem, const Params& p, int l) {
;     ...
;     { const float* wgt = ((const float*)ldp(26)) + (size_t)l * DM * 3072; const float* gn = ((const float*)ldp(5)) + l * DM; conv_tiles(tile, wt + W_GATE, 3072, 1024, 151, [=](int k, int r) { return gn[k] * wgt[(size_t)k * 3072 + r]; }); }
	s_lshr_b32 s99, s98, 8
	s_and_b32 s100, s98, 0xff
	s_mul_i32 s101, s100, 3
	s_sub_i32 s98, s100, 256
	s_mul_i32 s98, s98, 2
	s_add_i32 s98, s98, 768
	s_cmp_lt_u32 s100, 256
	s_cselect_b32 s98, s101, s98
	s_add_i32 s98, s98, s99
	s_mul_hi_u32 s99, s98, 0x5555556
	s_mul_i32 s100, s99, 48
	s_sub_i32 s98, s98, s100
	s_mul_i32 s98, s98, 16
	s_add_i32 s98, s98, s99
	s_mul_hi_i32 s10, s98, 0x2aaaaaab
	s_lshr_b32 s11, s10, 31
	s_lshr_b32 s10, s10, 7
	s_add_i32 s10, s10, s11
	s_mulk_i32 s10, 0x300
	s_sub_i32 s10, s98, s10
	s_sext_i32_i16 s11, s10
	s_bfe_u32 s11, s11, 0x4001b
	s_add_i32 s11, s10, s11
	s_sext_i32_i16 s18, s11
	s_and_b32 s11, s11, 0xfff0
	s_sub_i32 s10, s10, s11
	s_lshl_b32 s18, s18, 2
	s_sext_i32_i16 s10, s10
	s_and_b32 s11, s18, 0xffffffc0
	s_lshl_b32 s10, s10, 6
	v_or_b32_e32 v54, s11, v2
	v_add_u32_e32 v56, s10, v3
	v_ashrrev_i32_e32 v55, 31, v54
	v_ashrrev_i32_e32 v57, 31, v56
	v_add_u32_e32 v53, s10, v5
	v_add_u32_e32 v62, s10, v6
	v_add_u32_e32 v64, s10, v7
	v_add_u32_e32 v66, s10, v8
	v_add_u32_e32 v68, s10, v9
	v_add_u32_e32 v70, s10, v10
	v_add_u32_e32 v72, s10, v11
	v_lshl_add_u64 v[54:55], v[54:55], 2, s[6:7]
	v_lshl_add_u64 v[58:59], v[56:57], 2, s[8:9]
	v_mad_i64_i32 v[56:57], s[18:19], v56, s79, v[54:55]
	v_mad_i64_i32 v[60:61], s[18:19], v53, s79, v[54:55]
	v_mad_i64_i32 v[62:63], s[18:19], v62, s79, v[54:55]
	v_mad_i64_i32 v[64:65], s[18:19], v64, s79, v[54:55]
	v_mad_i64_i32 v[66:67], s[18:19], v66, s79, v[54:55]
	v_mad_i64_i32 v[68:69], s[18:19], v68, s79, v[54:55]
	v_mad_i64_i32 v[70:71], s[18:19], v70, s79, v[54:55]
	v_mad_i64_i32 v[54:55], s[18:19], v72, s79, v[54:55]
	global_load_dword v53, v[58:59], off
	global_load_dword v72, v[58:59], off offset:32
	global_load_dword v73, v[58:59], off offset:64
	global_load_dword v74, v[58:59], off offset:96
	global_load_dword v75, v[58:59], off offset:128
	global_load_dword v76, v[58:59], off offset:160
	global_load_dword v77, v[58:59], off offset:192
	global_load_dword v78, v[58:59], off offset:224
	global_load_dword v79, v[56:57], off
	global_load_dword v80, v[60:61], off
	global_load_dword v81, v[62:63], off
	global_load_dword v82, v[64:65], off
	global_load_dword v83, v[66:67], off
	global_load_dword v84, v[68:69], off
	global_load_dword v85, v[70:71], off
	global_load_dword v86, v[54:55], off
	v_add_u32_e32 v54, s11, v3
	v_add_u32_e32 v56, s11, v5
	v_add_u32_e32 v58, s11, v6
	v_add_u32_e32 v60, s11, v7
	v_add_u32_e32 v62, s11, v8
	v_add_u32_e32 v64, s11, v9
	v_add_u32_e32 v66, s11, v10
	v_add_u32_e32 v68, s11, v11
	s_ashr_i32 s11, s10, 31
	v_ashrrev_i32_e32 v55, 31, v54
	v_ashrrev_i32_e32 v57, 31, v56
	v_ashrrev_i32_e32 v59, 31, v58
	v_ashrrev_i32_e32 v61, 31, v60
	v_ashrrev_i32_e32 v63, 31, v62
	v_ashrrev_i32_e32 v65, 31, v64
	v_ashrrev_i32_e32 v67, 31, v66
	v_ashrrev_i32_e32 v69, 31, v68
	v_lshl_add_u64 v[70:71], s[10:11], 1, v[0:1]
	v_lshlrev_b64 v[54:55], 11, v[54:55]
	v_lshlrev_b64 v[56:57], 11, v[56:57]
	v_lshlrev_b64 v[58:59], 11, v[58:59]
	v_lshlrev_b64 v[60:61], 11, v[60:61]
	v_lshlrev_b64 v[62:63], 11, v[62:63]
	v_lshlrev_b64 v[64:65], 11, v[64:65]
	v_lshlrev_b64 v[66:67], 11, v[66:67]
	v_lshlrev_b64 v[68:69], 11, v[68:69]
	v_lshl_add_u64 v[54:55], v[70:71], 0, v[54:55]
	v_lshl_add_u64 v[56:57], v[70:71], 0, v[56:57]
	v_lshl_add_u64 v[58:59], v[70:71], 0, v[58:59]
	v_lshl_add_u64 v[60:61], v[70:71], 0, v[60:61]
	v_lshl_add_u64 v[62:63], v[70:71], 0, v[62:63]
	v_lshl_add_u64 v[64:65], v[70:71], 0, v[64:65]
	v_lshl_add_u64 v[66:67], v[70:71], 0, v[66:67]
	v_lshl_add_u64 v[68:69], v[70:71], 0, v[68:69]
	s_waitcnt vmcnt(16)
	s_branch .Lcv319_pj

; __device__ __forceinline__ bf16_t f2bf(float f) { unsigned u = __float_as_uint(f); u += 0x7FFFu + ((u >> 16) & 1u); return (bf16_t)(u >> 16); }
;     ...
;     for (int t_ = first; t_ < ntile * ((REP & 1) + 1); t_ += gridDim.x) { const int t = t_ % ntile;
;         const int r0 = (t / nkt) * 64, k0 = (t % nkt) * 64;
;         __syncthreads();
; #pragma unroll
;         for (int i = 0; i < 8; ++i) { const int kk = i * 8 + w; tile[kk * 65 + lane] = src(k0 + kk, r0 + lane); }
;         __syncthreads();
; #pragma unroll
;         for (int i = 0; i < 8; ++i) { const int j = i * 8 + w; Bt[(size_t)(r0 + j) * ld + k0 + lane] = f2bf(tile[lane * 65 + j]); }
;     }
; __device__ void convert_phase(unsigned char* smem, const Params& p, int l) {
;     ...
;     { const float* wgt = ((const float*)ldp(26)) + (size_t)l * DM * 3072; const float* gn = ((const float*)ldp(5)) + l * DM; conv_tiles(tile, wt + W_GATE, 3072, 1024, 151, [=](int k, int r) { return gn[k] * wgt[(size_t)k * 3072 + r]; }); }
.Lcv319_top:
	s_waitcnt vmcnt(31)
	v_mul_f32_e32 v13, v13, v39
	s_waitcnt vmcnt(30)
	v_mul_f32_e32 v30, v32, v40
	s_waitcnt vmcnt(29)
	v_mul_f32_e32 v31, v33, v41
	s_waitcnt vmcnt(28)
	v_mul_f32_e32 v32, v34, v42
	s_waitcnt vmcnt(27)
	v_mul_f32_e32 v33, v35, v43
	s_waitcnt vmcnt(26)
	v_mul_f32_e32 v34, v36, v44
	s_waitcnt vmcnt(25)
	v_mul_f32_e32 v35, v37, v45
	s_waitcnt vmcnt(24)
	v_mul_f32_e32 v36, v38, v46
	ds_write_b32 v12, v13
	ds_write_b32 v12, v30 offset:2080
	ds_write_b32 v12, v31 offset:4160
	ds_write_b32 v12, v32 offset:6240
	ds_write_b32 v12, v33 offset:8320
	ds_write_b32 v12, v34 offset:10400
	ds_write_b32 v12, v35 offset:12480
	ds_write_b32 v12, v36 offset:14560
	s_waitcnt lgkmcnt(0)
	s_barrier
	ds_read2_b32 v[30:31], v4 offset1:8
	ds_read2_b32 v[32:33], v4 offset0:16 offset1:24
	ds_read2_b32 v[34:35], v4 offset0:32 offset1:40
	ds_read2_b32 v[36:37], v4 offset0:48 offset1:56
	s_waitcnt lgkmcnt(3)
	v_bfe_u32 v13, v30, 16, 1
	v_bfe_u32 v38, v31, 16, 1
	s_waitcnt lgkmcnt(2)
	v_bfe_u32 v39, v32, 16, 1
	v_bfe_u32 v40, v33, 16, 1
	s_waitcnt lgkmcnt(1)
	v_bfe_u32 v41, v34, 16, 1
	v_bfe_u32 v42, v35, 16, 1
	s_waitcnt lgkmcnt(0)
	v_bfe_u32 v43, v36, 16, 1
	v_bfe_u32 v44, v37, 16, 1
	v_add3_u32 v13, v30, v13, s88
	v_add3_u32 v30, v31, v38, s88
	v_add3_u32 v31, v32, v39, s88
	v_add3_u32 v32, v33, v40, s88
	v_add3_u32 v33, v34, v41, s88
	v_add3_u32 v34, v35, v42, s88
	v_add3_u32 v35, v36, v43, s88
	v_add3_u32 v36, v37, v44, s88
	global_store_short_d16_hi v[14:15], v13, off
	global_store_short_d16_hi v[16:17], v30, off
	global_store_short_d16_hi v[18:19], v31, off
	global_store_short_d16_hi v[20:21], v32, off
	global_store_short_d16_hi v[22:23], v33, off
	global_store_short_d16_hi v[24:25], v34, off
	global_store_short_d16_hi v[26:27], v35, off
	global_store_short_d16_hi v[28:29], v36, off
	s_lshl_b32 s98, s5, 1
	s_add_i32 s98, s98, s17
	s_cmp_lt_i32 s98, 0x300
	s_cbranch_scc0 .Lcv319_s0
	s_lshr_b32 s99, s98, 8
	s_and_b32 s100, s98, 0xff
	s_mul_i32 s101, s100, 3
	s_sub_i32 s98, s100, 256
	s_mul_i32 s98, s98, 2
	s_add_i32 s98, s98, 768
	s_cmp_lt_u32 s100, 256
	s_cselect_b32 s98, s101, s98
	s_add_i32 s98, s98, s99
	s_mul_hi_u32 s99, s98, 0x5555556
	s_mul_i32 s100, s99, 48
	s_sub_i32 s98, s98, s100
	s_mul_i32 s98, s98, 16
	s_add_i32 s98, s98, s99
	s_mul_hi_i32 s10, s98, 0x2aaaaaab
	s_lshr_b32 s11, s10, 31
	s_lshr_b32 s10, s10, 7
	s_add_i32 s10, s10, s11
	s_mulk_i32 s10, 0x300
	s_sub_i32 s10, s98, s10
	s_sext_i32_i16 s11, s10
	s_bfe_u32 s11, s11, 0x4001b
	s_add_i32 s11, s10, s11
	s_sext_i32_i16 s18, s11
	s_and_b32 s11, s11, 0xfff0
	s_sub_i32 s10, s10, s11
	s_lshl_b32 s18, s18, 2
	s_sext_i32_i16 s10, s10
	s_and_b32 s11, s18, 0xffffffc0
	s_lshl_b32 s10, s10, 6
	v_or_b32_e32 v14, s11, v2
	v_add_u32_e32 v16, s10, v3
	v_ashrrev_i32_e32 v15, 31, v14
	v_ashrrev_i32_e32 v17, 31, v16
	v_add_u32_e32 v13, s10, v5
	v_add_u32_e32 v22, s10, v6
	v_add_u32_e32 v24, s10, v7
	v_add_u32_e32 v26, s10, v8
	v_add_u32_e32 v28, s10, v9
	v_add_u32_e32 v30, s10, v10
	v_add_u32_e32 v32, s10, v11
	v_lshl_add_u64 v[14:15], v[14:15], 2, s[6:7]
	v_lshl_add_u64 v[18:19], v[16:17], 2, s[8:9]
	v_mad_i64_i32 v[16:17], s[18:19], v16, s79, v[14:15]
	v_mad_i64_i32 v[20:21], s[18:19], v13, s79, v[14:15]
	v_mad_i64_i32 v[22:23], s[18:19], v22, s79, v[14:15]
	v_mad_i64_i32 v[24:25], s[18:19], v24, s79, v[14:15]
	v_mad_i64_i32 v[26:27], s[18:19], v26, s79, v[14:15]
	v_mad_i64_i32 v[28:29], s[18:19], v28, s79, v[14:15]
	v_mad_i64_i32 v[30:31], s[18:19], v30, s79, v[14:15]
	v_mad_i64_i32 v[14:15], s[18:19], v32, s79, v[14:15]
	global_load_dword v13, v[18:19], off
	global_load_dword v32, v[18:19], off offset:32
	global_load_dword v33, v[18:19], off offset:64
	global_load_dword v34, v[18:19], off offset:96
	global_load_dword v35, v[18:19], off offset:128
	global_load_dword v36, v[18:19], off offset:160
	global_load_dword v37, v[18:19], off offset:192
	global_load_dword v38, v[18:19], off offset:224
	global_load_dword v39, v[16:17], off
	global_load_dword v40, v[20:21], off
	global_load_dword v41, v[22:23], off
	global_load_dword v42, v[24:25], off
	global_load_dword v43, v[26:27], off
	global_load_dword v44, v[28:29], off
	global_load_dword v45, v[30:31], off
	global_load_dword v46, v[14:15], off
	v_add_u32_e32 v14, s11, v3
	v_add_u32_e32 v16, s11, v5
	v_add_u32_e32 v18, s11, v6
	v_add_u32_e32 v20, s11, v7
	v_add_u32_e32 v22, s11, v8
	v_add_u32_e32 v24, s11, v9
	v_add_u32_e32 v26, s11, v10
	v_add_u32_e32 v28, s11, v11
	s_ashr_i32 s11, s10, 31
	v_ashrrev_i32_e32 v15, 31, v14
	v_ashrrev_i32_e32 v17, 31, v16
	v_ashrrev_i32_e32 v19, 31, v18
	v_ashrrev_i32_e32 v21, 31, v20
	v_ashrrev_i32_e32 v23, 31, v22
	v_ashrrev_i32_e32 v25, 31, v24
	v_ashrrev_i32_e32 v27, 31, v26
	v_ashrrev_i32_e32 v29, 31, v28
	v_lshl_add_u64 v[30:31], s[10:11], 1, v[0:1]
	v_lshlrev_b64 v[14:15], 11, v[14:15]
	v_lshlrev_b64 v[16:17], 11, v[16:17]
	v_lshlrev_b64 v[18:19], 11, v[18:19]
	v_lshlrev_b64 v[20:21], 11, v[20:21]
	v_lshlrev_b64 v[22:23], 11, v[22:23]
	v_lshlrev_b64 v[24:25], 11, v[24:25]
	v_lshlrev_b64 v[26:27], 11, v[26:27]
	v_lshlrev_b64 v[28:29], 11, v[28:29]
	v_lshl_add_u64 v[14:15], v[30:31], 0, v[14:15]
	v_lshl_add_u64 v[16:17], v[30:31], 0, v[16:17]
	v_lshl_add_u64 v[18:19], v[30:31], 0, v[18:19]
	v_lshl_add_u64 v[20:21], v[30:31], 0, v[20:21]
	v_lshl_add_u64 v[22:23], v[30:31], 0, v[22:23]
	v_lshl_add_u64 v[24:25], v[30:31], 0, v[24:25]
	v_lshl_add_u64 v[26:27], v[30:31], 0, v[26:27]
	v_lshl_add_u64 v[28:29], v[30:31], 0, v[28:29]
	s_branch .Lcv319_n0

; __device__ __forceinline__ bf16_t f2bf(float f) { unsigned u = __float_as_uint(f); u += 0x7FFFu + ((u >> 16) & 1u); return (bf16_t)(u >> 16); }
;     ...
;     for (int t_ = first; t_ < ntile * ((REP & 1) + 1); t_ += gridDim.x) { const int t = t_ % ntile;
;         const int r0 = (t / nkt) * 64, k0 = (t % nkt) * 64;
;         __syncthreads();
; #pragma unroll
;         for (int i = 0; i < 8; ++i) { const int kk = i * 8 + w; tile[kk * 65 + lane] = src(k0 + kk, r0 + lane); }
;         __syncthreads();
; #pragma unroll
;         for (int i = 0; i < 8; ++i) { const int j = i * 8 + w; Bt[(size_t)(r0 + j) * ld + k0 + lane] = f2bf(tile[lane * 65 + j]); }
;     }
; __device__ void convert_phase(unsigned char* smem, const Params& p, int l) {
;     ...
;     { const float* wgt = ((const float*)ldp(26)) + (size_t)l * DM * 3072; const float* gn = ((const float*)ldp(5)) + l * DM; conv_tiles(tile, wt + W_GATE, 3072, 1024, 151, [=](int k, int r) { return gn[k] * wgt[(size_t)k * 3072 + r]; }); }
.Lcv319_n0:
	s_add_i32 s17, s17, s5
	s_cmp_lt_i32 s17, 0x300
	s_cbranch_scc0 .LBB0_320
	s_waitcnt vmcnt(31)
	v_mul_f32_e32 v53, v53, v79
	s_waitcnt vmcnt(30)
	v_mul_f32_e32 v70, v72, v80
	s_waitcnt vmcnt(29)
	v_mul_f32_e32 v71, v73, v81
	s_waitcnt vmcnt(28)
	v_mul_f32_e32 v72, v74, v82
	s_waitcnt vmcnt(27)
	v_mul_f32_e32 v73, v75, v83
	s_waitcnt vmcnt(26)
	v_mul_f32_e32 v74, v76, v84
	s_waitcnt vmcnt(25)
	v_mul_f32_e32 v75, v77, v85
	s_waitcnt vmcnt(24)
	v_mul_f32_e32 v76, v78, v86
	ds_write_b32 v12, v53 offset:17408
	ds_write_b32 v12, v70 offset:19488
	ds_write_b32 v12, v71 offset:21568
	ds_write_b32 v12, v72 offset:23648
	ds_write_b32 v12, v73 offset:25728
	ds_write_b32 v12, v74 offset:27808
	ds_write_b32 v12, v75 offset:29888
	ds_write_b32 v12, v76 offset:31968
	s_waitcnt lgkmcnt(0)
	s_barrier
	ds_read2_b32 v[70:71], v95 offset1:8
	ds_read2_b32 v[72:73], v95 offset0:16 offset1:24
	ds_read2_b32 v[74:75], v95 offset0:32 offset1:40
	ds_read2_b32 v[76:77], v95 offset0:48 offset1:56
	s_waitcnt lgkmcnt(3)
	v_bfe_u32 v53, v70, 16, 1
	v_bfe_u32 v78, v71, 16, 1
	s_waitcnt lgkmcnt(2)
	v_bfe_u32 v79, v72, 16, 1
	v_bfe_u32 v80, v73, 16, 1
	s_waitcnt lgkmcnt(1)
	v_bfe_u32 v81, v74, 16, 1
	v_bfe_u32 v82, v75, 16, 1
	s_waitcnt lgkmcnt(0)
	v_bfe_u32 v83, v76, 16, 1
	v_bfe_u32 v84, v77, 16, 1
	v_add3_u32 v53, v70, v53, s88
	v_add3_u32 v70, v71, v78, s88
	v_add3_u32 v71, v72, v79, s88
	v_add3_u32 v72, v73, v80, s88
	v_add3_u32 v73, v74, v81, s88
	v_add3_u32 v74, v75, v82, s88
	v_add3_u32 v75, v76, v83, s88
	v_add3_u32 v76, v77, v84, s88
	global_store_short_d16_hi v[54:55], v53, off
	global_store_short_d16_hi v[56:57], v70, off
	global_store_short_d16_hi v[58:59], v71, off
	global_store_short_d16_hi v[60:61], v72, off
	global_store_short_d16_hi v[62:63], v73, off
	global_store_short_d16_hi v[64:65], v74, off
	global_store_short_d16_hi v[66:67], v75, off
	global_store_short_d16_hi v[68:69], v76, off
	s_lshl_b32 s98, s5, 1
	s_add_i32 s98, s98, s17
	s_cmp_lt_i32 s98, 0x300
	s_cbranch_scc0 .Lcv319_s1
	s_lshr_b32 s99, s98, 8
	s_and_b32 s100, s98, 0xff
	s_mul_i32 s101, s100, 3
	s_sub_i32 s98, s100, 256
	s_mul_i32 s98, s98, 2
	s_add_i32 s98, s98, 768
	s_cmp_lt_u32 s100, 256
	s_cselect_b32 s98, s101, s98
	s_add_i32 s98, s98, s99
	s_mul_hi_u32 s99, s98, 0x5555556
	s_mul_i32 s100, s99, 48
	s_sub_i32 s98, s98, s100
	s_mul_i32 s98, s98, 16
	s_add_i32 s98, s98, s99
	s_mul_hi_i32 s10, s98, 0x2aaaaaab
	s_lshr_b32 s11, s10, 31
	s_lshr_b32 s10, s10, 7
	s_add_i32 s10, s10, s11
	s_mulk_i32 s10, 0x300
	s_sub_i32 s10, s98, s10
	s_sext_i32_i16 s11, s10
	s_bfe_u32 s11, s11, 0x4001b
	s_add_i32 s11, s10, s11
	s_sext_i32_i16 s18, s11
	s_and_b32 s11, s11, 0xfff0
	s_sub_i32 s10, s10, s11
	s_lshl_b32 s18, s18, 2
	s_sext_i32_i16 s10, s10
	s_and_b32 s11, s18, 0xffffffc0
	s_lshl_b32 s10, s10, 6
	v_or_b32_e32 v54, s11, v2
	v_add_u32_e32 v56, s10, v3
	v_ashrrev_i32_e32 v55, 31, v54
	v_ashrrev_i32_e32 v57, 31, v56
	v_add_u32_e32 v53, s10, v5
	v_add_u32_e32 v62, s10, v6
	v_add_u32_e32 v64, s10, v7
	v_add_u32_e32 v66, s10, v8
	v_add_u32_e32 v68, s10, v9
	v_add_u32_e32 v70, s10, v10
	v_add_u32_e32 v72, s10, v11
	v_lshl_add_u64 v[54:55], v[54:55], 2, s[6:7]
	v_lshl_add_u64 v[58:59], v[56:57], 2, s[8:9]
	v_mad_i64_i32 v[56:57], s[18:19], v56, s79, v[54:55]
	v_mad_i64_i32 v[60:61], s[18:19], v53, s79, v[54:55]
	v_mad_i64_i32 v[62:63], s[18:19], v62, s79, v[54:55]
	v_mad_i64_i32 v[64:65], s[18:19], v64, s79, v[54:55]
	v_mad_i64_i32 v[66:67], s[18:19], v66, s79, v[54:55]
	v_mad_i64_i32 v[68:69], s[18:19], v68, s79, v[54:55]
	v_mad_i64_i32 v[70:71], s[18:19], v70, s79, v[54:55]
	v_mad_i64_i32 v[54:55], s[18:19], v72, s79, v[54:55]
	global_load_dword v53, v[58:59], off
	global_load_dword v72, v[58:59], off offset:32
	global_load_dword v73, v[58:59], off offset:64
	global_load_dword v74, v[58:59], off offset:96
	global_load_dword v75, v[58:59], off offset:128
	global_load_dword v76, v[58:59], off offset:160
	global_load_dword v77, v[58:59], off offset:192
	global_load_dword v78, v[58:59], off offset:224
	global_load_dword v79, v[56:57], off
	global_load_dword v80, v[60:61], off
	global_load_dword v81, v[62:63], off
	global_load_dword v82, v[64:65], off
	global_load_dword v83, v[66:67], off
	global_load_dword v84, v[68:69], off
	global_load_dword v85, v[70:71], off
	global_load_dword v86, v[54:55], off
	v_add_u32_e32 v54, s11, v3
	v_add_u32_e32 v56, s11, v5
	v_add_u32_e32 v58, s11, v6
	v_add_u32_e32 v60, s11, v7
	v_add_u32_e32 v62, s11, v8
	v_add_u32_e32 v64, s11, v9
	v_add_u32_e32 v66, s11, v10
	v_add_u32_e32 v68, s11, v11
	s_ashr_i32 s11, s10, 31
	v_ashrrev_i32_e32 v55, 31, v54
	v_ashrrev_i32_e32 v57, 31, v56
	v_ashrrev_i32_e32 v59, 31, v58
	v_ashrrev_i32_e32 v61, 31, v60
	v_ashrrev_i32_e32 v63, 31, v62
	v_ashrrev_i32_e32 v65, 31, v64
	v_ashrrev_i32_e32 v67, 31, v66
	v_ashrrev_i32_e32 v69, 31, v68
	v_lshl_add_u64 v[70:71], s[10:11], 1, v[0:1]
	v_lshlrev_b64 v[54:55], 11, v[54:55]
	v_lshlrev_b64 v[56:57], 11, v[56:57]
	v_lshlrev_b64 v[58:59], 11, v[58:59]
	v_lshlrev_b64 v[60:61], 11, v[60:61]
	v_lshlrev_b64 v[62:63], 11, v[62:63]
	v_lshlrev_b64 v[64:65], 11, v[64:65]
	v_lshlrev_b64 v[66:67], 11, v[66:67]
	v_lshlrev_b64 v[68:69], 11, v[68:69]
	v_lshl_add_u64 v[54:55], v[70:71], 0, v[54:55]
	v_lshl_add_u64 v[56:57], v[70:71], 0, v[56:57]
	v_lshl_add_u64 v[58:59], v[70:71], 0, v[58:59]
	v_lshl_add_u64 v[60:61], v[70:71], 0, v[60:61]
	v_lshl_add_u64 v[62:63], v[70:71], 0, v[62:63]
	v_lshl_add_u64 v[64:65], v[70:71], 0, v[64:65]
	v_lshl_add_u64 v[66:67], v[70:71], 0, v[66:67]
	v_lshl_add_u64 v[68:69], v[70:71], 0, v[68:69]
	s_branch .Lcv319_n1

; __device__ __forceinline__ bf16_t f2bf(float f) { unsigned u = __float_as_uint(f); u += 0x7FFFu + ((u >> 16) & 1u); return (bf16_t)(u >> 16); }
;     ...
;     for (int t_ = first; t_ < ntile * ((REP & 1) + 1); t_ += gridDim.x) { const int t = t_ % ntile;
;         const int r0 = (t / nkt) * 64, k0 = (t % nkt) * 64;
;         __syncthreads();
; #pragma unroll
;         for (int i = 0; i < 8; ++i) { const int kk = i * 8 + w; tile[kk * 65 + lane] = src(k0 + kk, r0 + lane); }
;         __syncthreads();
; #pragma unroll
;         for (int i = 0; i < 8; ++i) { const int j = i * 8 + w; Bt[(size_t)(r0 + j) * ld + k0 + lane] = f2bf(tile[lane * 65 + j]); }
;     }
; __device__ void convert_phase(unsigned char* smem, const Params& p, int l) {
;     ...
;       conv_tiles(tile, wt + W_UP2, 5632, 1024, 53, [=](int k, int r) { const int col = (r >> 5) * 16 + (r & 15); return gn[k] * (((r >> 4) & 1) ? wu[(size_t)k * DFF + col] : wg[(size_t)k * DFF + col]); }); }
.LBB0_334:
	s_mov_b32 s98, s10
	s_lshr_b32 s99, s98, 8
	s_and_b32 s100, s98, 0xff
	s_mul_i32 s101, s100, 6
	s_sub_i32 s98, s100, 128
	s_mul_i32 s98, s98, 5
	s_add_i32 s98, s98, 768
	s_cmp_lt_u32 s100, 128
	s_cselect_b32 s98, s101, s98
	s_add_i32 s98, s98, s99
	s_mul_hi_u32 s99, s98, 0x2e8ba2f
	s_mul_i32 s100, s99, 88
	s_sub_i32 s98, s98, s100
	s_mul_i32 s98, s98, 16
	s_add_i32 s98, s98, s99
	s_mul_hi_i32 s8, s98, 0x2e8ba2e9
	s_lshr_b32 s9, s8, 31
	s_ashr_i32 s8, s8, 8
	s_add_i32 s8, s8, s9
	s_mulk_i32 s8, 0x580
	s_sub_i32 s8, s98, s8
	s_sext_i32_i16 s9, s8
	s_bfe_u32 s9, s9, 0x4001b
	s_add_i32 s9, s8, s9
	s_sext_i32_i16 s11, s9
	s_lshl_b32 s11, s11, 2
	s_and_b32 s9, s9, 0xfff0
	s_andn2_b32 s11, s11, 63
	s_sub_i32 s8, s8, s9
	v_or_b32_e32 v16, s11, v4
	s_sext_i32_i16 s8, s8
	v_ashrrev_i32_e32 v17, 1, v16
	s_lshl_b32 s8, s8, 6
	v_and_or_b32 v18, v17, -16, v6
	v_add_u32_e32 v16, s8, v5
	v_ashrrev_i32_e32 v19, 31, v18
	v_ashrrev_i32_e32 v17, 31, v16
	v_lshl_add_u64 v[18:19], v[18:19], 2, v[0:1]
	v_add_u32_e32 v22, s8, v8
	v_add_u32_e32 v23, s8, v9
	v_add_u32_e32 v24, s8, v10
	v_add_u32_e32 v26, s8, v11
	v_add_u32_e32 v28, s8, v12
	v_add_u32_e32 v30, s8, v13
	v_add_u32_e32 v32, s8, v14
	v_lshl_add_u64 v[20:21], v[16:17], 2, s[6:7]
	v_mad_i64_i32 v[16:17], s[16:17], v16, s33, v[18:19]
	global_load_dword v34, v[20:21], off
	global_load_dword v35, v[20:21], off offset:32
	global_load_dword v36, v[20:21], off offset:64
	global_load_dword v37, v[20:21], off offset:96
	global_load_dword v38, v[20:21], off offset:128
	global_load_dword v39, v[20:21], off offset:160
	global_load_dword v40, v[20:21], off offset:192
	global_load_dword v41, v[20:21], off offset:224
	v_mad_i64_i32 v[20:21], s[16:17], v22, s33, v[18:19]
	v_mad_i64_i32 v[22:23], s[16:17], v23, s33, v[18:19]
	v_mad_i64_i32 v[24:25], s[16:17], v24, s33, v[18:19]
	v_mad_i64_i32 v[26:27], s[16:17], v26, s33, v[18:19]
	v_mad_i64_i32 v[28:29], s[16:17], v28, s33, v[18:19]
	v_mad_i64_i32 v[30:31], s[16:17], v30, s33, v[18:19]
	v_mad_i64_i32 v[18:19], s[16:17], v32, s33, v[18:19]
	global_load_dword v42, v[16:17], off
	global_load_dword v43, v[20:21], off
	global_load_dword v44, v[22:23], off
	global_load_dword v45, v[24:25], off
	global_load_dword v46, v[26:27], off
	global_load_dword v47, v[28:29], off
	global_load_dword v48, v[30:31], off
	global_load_dword v49, v[18:19], off
	v_add_u32_e32 v16, s11, v5
	v_add_u32_e32 v18, s11, v8
	v_add_u32_e32 v20, s11, v9
	v_add_u32_e32 v22, s11, v10
	v_add_u32_e32 v24, s11, v11
	v_add_u32_e32 v26, s11, v12
	v_add_u32_e32 v28, s11, v13
	v_add_u32_e32 v30, s11, v14
	s_ashr_i32 s9, s8, 31
	v_ashrrev_i32_e32 v17, 31, v16
	v_ashrrev_i32_e32 v19, 31, v18
	v_ashrrev_i32_e32 v21, 31, v20
	v_ashrrev_i32_e32 v23, 31, v22
	v_ashrrev_i32_e32 v25, 31, v24
	v_ashrrev_i32_e32 v27, 31, v26
	v_ashrrev_i32_e32 v29, 31, v28
	v_ashrrev_i32_e32 v31, 31, v30
	v_lshl_add_u64 v[32:33], s[8:9], 1, v[2:3]
	v_lshlrev_b64 v[16:17], 11, v[16:17]
	v_lshlrev_b64 v[18:19], 11, v[18:19]
	v_lshlrev_b64 v[20:21], 11, v[20:21]
	v_lshlrev_b64 v[22:23], 11, v[22:23]
	v_lshlrev_b64 v[24:25], 11, v[24:25]
	v_lshlrev_b64 v[26:27], 11, v[26:27]
	v_lshlrev_b64 v[28:29], 11, v[28:29]
	v_lshlrev_b64 v[30:31], 11, v[30:31]
	v_lshl_add_u64 v[16:17], v[32:33], 0, v[16:17]
	v_lshl_add_u64 v[18:19], v[32:33], 0, v[18:19]
	v_lshl_add_u64 v[20:21], v[32:33], 0, v[20:21]
	v_lshl_add_u64 v[22:23], v[32:33], 0, v[22:23]
	v_lshl_add_u64 v[24:25], v[32:33], 0, v[24:25]
	v_lshl_add_u64 v[26:27], v[32:33], 0, v[26:27]
	v_lshl_add_u64 v[28:29], v[32:33], 0, v[28:29]
	v_lshl_add_u64 v[30:31], v[32:33], 0, v[30:31]
	s_add_i32 s98, s10, s5
	s_cmp_lt_i32 s98, 0x580
	s_cbranch_scc0 .Lcv334_p1skip
; __device__ __forceinline__ bf16_t f2bf(float f) { unsigned u = __float_as_uint(f); u += 0x7FFFu + ((u >> 16) & 1u); return (bf16_t)(u >> 16); }
;     ...
;     for (int t_ = first; t_ < ntile * ((REP & 1) + 1); t_ += gridDim.x) { const int t = t_ % ntile;
;         const int r0 = (t / nkt) * 64, k0 = (t % nkt) * 64;
;         __syncthreads();
; #pragma unroll
;         for (int i = 0; i < 8; ++i) { const int kk = i * 8 + w; tile[kk * 65 + lane] = src(k0 + kk, r0 + lane); }
;         __syncthreads();
; #pragma unroll
;         for (int i = 0; i < 8; ++i) { const int j = i * 8 + w; Bt[(size_t)(r0 + j) * ld + k0 + lane] = f2bf(tile[lane * 65 + j]); }
;     }
; __device__ void convert_phase(unsigned char* smem, const Params& p, int l) {
;     ...
;       conv_tiles(tile, wt + W_UP2, 5632, 1024, 53, [=](int k, int r) { const int col = (r >> 5) * 16 + (r & 15); return gn[k] * (((r >> 4) & 1) ? wu[(size_t)k * DFF + col] : wg[(size_t)k * DFF + col]); }); }
	s_lshr_b32 s99, s98, 8
	s_and_b32 s100, s98, 0xff
	s_mul_i32 s101, s100, 6
	s_sub_i32 s98, s100, 128
	s_mul_i32 s98, s98, 5
	s_add_i32 s98, s98, 768
	s_cmp_lt_u32 s100, 128
	s_cselect_b32 s98, s101, s98
	s_add_i32 s98, s98, s99
	s_mul_hi_u32 s99, s98, 0x2e8ba2f
	s_mul_i32 s100, s99, 88
	s_sub_i32 s98, s98, s100
	s_mul_i32 s98, s98, 16
	s_add_i32 s98, s98, s99
	s_mul_hi_i32 s8, s98, 0x2e8ba2e9
	s_lshr_b32 s9, s8, 31
	s_ashr_i32 s8, s8, 8
	s_add_i32 s8, s8, s9
	s_mulk_i32 s8, 0x580
	s_sub_i32 s8, s98, s8
	s_sext_i32_i16 s9, s8
	s_bfe_u32 s9, s9, 0x4001b
	s_add_i32 s9, s8, s9
	s_sext_i32_i16 s11, s9
	s_lshl_b32 s11, s11, 2
	s_and_b32 s9, s9, 0xfff0
	s_andn2_b32 s11, s11, 63
	s_sub_i32 s8, s8, s9
	v_or_b32_e32 v56, s11, v4
	s_sext_i32_i16 s8, s8
	v_ashrrev_i32_e32 v57, 1, v56
	s_lshl_b32 s8, s8, 6
	v_and_or_b32 v58, v57, -16, v6
	v_add_u32_e32 v56, s8, v5
	v_ashrrev_i32_e32 v59, 31, v58
	v_ashrrev_i32_e32 v57, 31, v56
	v_lshl_add_u64 v[58:59], v[58:59], 2, v[0:1]
	v_add_u32_e32 v62, s8, v8
	v_add_u32_e32 v63, s8, v9
	v_add_u32_e32 v64, s8, v10
	v_add_u32_e32 v66, s8, v11
	v_add_u32_e32 v68, s8, v12
	v_add_u32_e32 v70, s8, v13
	v_add_u32_e32 v72, s8, v14
	v_lshl_add_u64 v[60:61], v[56:57], 2, s[6:7]
	v_mad_i64_i32 v[56:57], s[16:17], v56, s33, v[58:59]
	global_load_dword v74, v[60:61], off
	global_load_dword v75, v[60:61], off offset:32
	global_load_dword v76, v[60:61], off offset:64
	global_load_dword v77, v[60:61], off offset:96
	global_load_dword v78, v[60:61], off offset:128
	global_load_dword v79, v[60:61], off offset:160
	global_load_dword v80, v[60:61], off offset:192
	global_load_dword v81, v[60:61], off offset:224
	v_mad_i64_i32 v[60:61], s[16:17], v62, s33, v[58:59]
	v_mad_i64_i32 v[62:63], s[16:17], v63, s33, v[58:59]
	v_mad_i64_i32 v[64:65], s[16:17], v64, s33, v[58:59]
	v_mad_i64_i32 v[66:67], s[16:17], v66, s33, v[58:59]
	v_mad_i64_i32 v[68:69], s[16:17], v68, s33, v[58:59]
	v_mad_i64_i32 v[70:71], s[16:17], v70, s33, v[58:59]
	v_mad_i64_i32 v[58:59], s[16:17], v72, s33, v[58:59]
	global_load_dword v82, v[56:57], off
	global_load_dword v83, v[60:61], off
	global_load_dword v84, v[62:63], off
	global_load_dword v85, v[64:65], off
	global_load_dword v86, v[66:67], off
	global_load_dword v87, v[68:69], off
	global_load_dword v88, v[70:71], off
	global_load_dword v89, v[58:59], off
	v_add_u32_e32 v56, s11, v5
	v_add_u32_e32 v58, s11, v8
	v_add_u32_e32 v60, s11, v9
	v_add_u32_e32 v62, s11, v10
	v_add_u32_e32 v64, s11, v11
	v_add_u32_e32 v66, s11, v12
	v_add_u32_e32 v68, s11, v13
	v_add_u32_e32 v70, s11, v14
	s_ashr_i32 s9, s8, 31
	v_ashrrev_i32_e32 v57, 31, v56
	v_ashrrev_i32_e32 v59, 31, v58
	v_ashrrev_i32_e32 v61, 31, v60
	v_ashrrev_i32_e32 v63, 31, v62
	v_ashrrev_i32_e32 v65, 31, v64
	v_ashrrev_i32_e32 v67, 31, v66
	v_ashrrev_i32_e32 v69, 31, v68
	v_ashrrev_i32_e32 v71, 31, v70
	v_lshl_add_u64 v[72:73], s[8:9], 1, v[2:3]
	v_lshlrev_b64 v[56:57], 11, v[56:57]
	v_lshlrev_b64 v[58:59], 11, v[58:59]
	v_lshlrev_b64 v[60:61], 11, v[60:61]
	v_lshlrev_b64 v[62:63], 11, v[62:63]
	v_lshlrev_b64 v[64:65], 11, v[64:65]
	v_lshlrev_b64 v[66:67], 11, v[66:67]
	v_lshlrev_b64 v[68:69], 11, v[68:69]
	v_lshlrev_b64 v[70:71], 11, v[70:71]
	v_lshl_add_u64 v[56:57], v[72:73], 0, v[56:57]
	v_lshl_add_u64 v[58:59], v[72:73], 0, v[58:59]
	v_lshl_add_u64 v[60:61], v[72:73], 0, v[60:61]
	v_lshl_add_u64 v[62:63], v[72:73], 0, v[62:63]
	v_lshl_add_u64 v[64:65], v[72:73], 0, v[64:65]
	v_lshl_add_u64 v[66:67], v[72:73], 0, v[66:67]
	v_lshl_add_u64 v[68:69], v[72:73], 0, v[68:69]
	v_lshl_add_u64 v[70:71], v[72:73], 0, v[70:71]
	s_waitcnt vmcnt(16)
	s_branch .Lcv334_pj

; __device__ __forceinline__ bf16_t f2bf(float f) { unsigned u = __float_as_uint(f); u += 0x7FFFu + ((u >> 16) & 1u); return (bf16_t)(u >> 16); }
;     ...
;     for (int t_ = first; t_ < ntile * ((REP & 1) + 1); t_ += gridDim.x) { const int t = t_ % ntile;
;         const int r0 = (t / nkt) * 64, k0 = (t % nkt) * 64;
;         __syncthreads();
; #pragma unroll
;         for (int i = 0; i < 8; ++i) { const int kk = i * 8 + w; tile[kk * 65 + lane] = src(k0 + kk, r0 + lane); }
;         __syncthreads();
; #pragma unroll
;         for (int i = 0; i < 8; ++i) { const int j = i * 8 + w; Bt[(size_t)(r0 + j) * ld + k0 + lane] = f2bf(tile[lane * 65 + j]); }
;     }
; __device__ void convert_phase(unsigned char* smem, const Params& p, int l) {
;     ...
;       conv_tiles(tile, wt + W_UP2, 5632, 1024, 53, [=](int k, int r) { const int col = (r >> 5) * 16 + (r & 15); return gn[k] * (((r >> 4) & 1) ? wu[(size_t)k * DFF + col] : wg[(size_t)k * DFF + col]); }); }
.Lcv334_top:
	s_waitcnt vmcnt(31)
	v_mul_f32_e32 v32, v34, v42
	s_waitcnt vmcnt(30)
	v_mul_f32_e32 v33, v35, v43
	s_waitcnt vmcnt(29)
	v_mul_f32_e32 v34, v36, v44
	s_waitcnt vmcnt(28)
	v_mul_f32_e32 v35, v37, v45
	s_waitcnt vmcnt(27)
	v_mul_f32_e32 v36, v38, v46
	s_waitcnt vmcnt(26)
	v_mul_f32_e32 v37, v39, v47
	s_waitcnt vmcnt(25)
	v_mul_f32_e32 v38, v40, v48
	s_waitcnt vmcnt(24)
	v_mul_f32_e32 v39, v41, v49
	ds_write_b32 v15, v32
	ds_write_b32 v15, v33 offset:2080
	ds_write_b32 v15, v34 offset:4160
	ds_write_b32 v15, v35 offset:6240
	ds_write_b32 v15, v36 offset:8320
	ds_write_b32 v15, v37 offset:10400
	ds_write_b32 v15, v38 offset:12480
	ds_write_b32 v15, v39 offset:14560
	s_waitcnt lgkmcnt(0)
	s_barrier
	ds_read2_b32 v[32:33], v7 offset1:8
	ds_read2_b32 v[34:35], v7 offset0:16 offset1:24
	ds_read2_b32 v[36:37], v7 offset0:32 offset1:40
	ds_read2_b32 v[38:39], v7 offset0:48 offset1:56
	s_waitcnt lgkmcnt(3)
	v_bfe_u32 v40, v32, 16, 1
	v_bfe_u32 v41, v33, 16, 1
	s_waitcnt lgkmcnt(2)
	v_bfe_u32 v42, v34, 16, 1
	v_bfe_u32 v43, v35, 16, 1
	s_waitcnt lgkmcnt(1)
	v_bfe_u32 v44, v36, 16, 1
	v_bfe_u32 v45, v37, 16, 1
	s_waitcnt lgkmcnt(0)
	v_bfe_u32 v46, v38, 16, 1
	v_bfe_u32 v47, v39, 16, 1
	v_add3_u32 v32, v32, v40, s88
	v_add3_u32 v33, v33, v41, s88
	v_add3_u32 v34, v34, v42, s88
	v_add3_u32 v35, v35, v43, s88
	v_add3_u32 v36, v36, v44, s88
	v_add3_u32 v37, v37, v45, s88
	v_add3_u32 v38, v38, v46, s88
	v_add3_u32 v39, v39, v47, s88
	global_store_short_d16_hi v[16:17], v32, off
	global_store_short_d16_hi v[18:19], v33, off
	global_store_short_d16_hi v[20:21], v34, off
	global_store_short_d16_hi v[22:23], v35, off
	global_store_short_d16_hi v[24:25], v36, off
	global_store_short_d16_hi v[26:27], v37, off
	global_store_short_d16_hi v[28:29], v38, off
	global_store_short_d16_hi v[30:31], v39, off
	s_lshl_b32 s98, s5, 1
	s_add_i32 s98, s98, s10
	s_cmp_lt_i32 s98, 0x580
	s_cbranch_scc0 .Lcv334_s0
	s_lshr_b32 s99, s98, 8
	s_and_b32 s100, s98, 0xff
	s_mul_i32 s101, s100, 6
	s_sub_i32 s98, s100, 128
	s_mul_i32 s98, s98, 5
	s_add_i32 s98, s98, 768
	s_cmp_lt_u32 s100, 128
	s_cselect_b32 s98, s101, s98
	s_add_i32 s98, s98, s99
	s_mul_hi_u32 s99, s98, 0x2e8ba2f
	s_mul_i32 s100, s99, 88
	s_sub_i32 s98, s98, s100
	s_mul_i32 s98, s98, 16
	s_add_i32 s98, s98, s99
	s_mul_hi_i32 s8, s98, 0x2e8ba2e9
	s_lshr_b32 s9, s8, 31
	s_ashr_i32 s8, s8, 8
	s_add_i32 s8, s8, s9
	s_mulk_i32 s8, 0x580
	s_sub_i32 s8, s98, s8
	s_sext_i32_i16 s9, s8
	s_bfe_u32 s9, s9, 0x4001b
	s_add_i32 s9, s8, s9
	s_sext_i32_i16 s11, s9
	s_lshl_b32 s11, s11, 2
	s_and_b32 s9, s9, 0xfff0
	s_andn2_b32 s11, s11, 63
	s_sub_i32 s8, s8, s9
	v_or_b32_e32 v16, s11, v4
	s_sext_i32_i16 s8, s8
	v_ashrrev_i32_e32 v17, 1, v16
	s_lshl_b32 s8, s8, 6
	v_and_or_b32 v18, v17, -16, v6
	v_add_u32_e32 v16, s8, v5
	v_ashrrev_i32_e32 v19, 31, v18
	v_ashrrev_i32_e32 v17, 31, v16
	v_lshl_add_u64 v[18:19], v[18:19], 2, v[0:1]
	v_add_u32_e32 v22, s8, v8
	v_add_u32_e32 v23, s8, v9
	v_add_u32_e32 v24, s8, v10
	v_add_u32_e32 v26, s8, v11
	v_add_u32_e32 v28, s8, v12
	v_add_u32_e32 v30, s8, v13
	v_add_u32_e32 v32, s8, v14
	v_lshl_add_u64 v[20:21], v[16:17], 2, s[6:7]
	v_mad_i64_i32 v[16:17], s[16:17], v16, s33, v[18:19]
	global_load_dword v34, v[20:21], off
	global_load_dword v35, v[20:21], off offset:32
	global_load_dword v36, v[20:21], off offset:64
	global_load_dword v37, v[20:21], off offset:96
	global_load_dword v38, v[20:21], off offset:128
	global_load_dword v39, v[20:21], off offset:160
	global_load_dword v40, v[20:21], off offset:192
	global_load_dword v41, v[20:21], off offset:224
	v_mad_i64_i32 v[20:21], s[16:17], v22, s33, v[18:19]
	v_mad_i64_i32 v[22:23], s[16:17], v23, s33, v[18:19]
	v_mad_i64_i32 v[24:25], s[16:17], v24, s33, v[18:19]
	v_mad_i64_i32 v[26:27], s[16:17], v26, s33, v[18:19]
	v_mad_i64_i32 v[28:29], s[16:17], v28, s33, v[18:19]
	v_mad_i64_i32 v[30:31], s[16:17], v30, s33, v[18:19]
	v_mad_i64_i32 v[18:19], s[16:17], v32, s33, v[18:19]
	global_load_dword v42, v[16:17], off
	global_load_dword v43, v[20:21], off
	global_load_dword v44, v[22:23], off
	global_load_dword v45, v[24:25], off
	global_load_dword v46, v[26:27], off
	global_load_dword v47, v[28:29], off
	global_load_dword v48, v[30:31], off
	global_load_dword v49, v[18:19], off
	v_add_u32_e32 v16, s11, v5
	v_add_u32_e32 v18, s11, v8
	v_add_u32_e32 v20, s11, v9
	v_add_u32_e32 v22, s11, v10
	v_add_u32_e32 v24, s11, v11
	v_add_u32_e32 v26, s11, v12
	v_add_u32_e32 v28, s11, v13
	v_add_u32_e32 v30, s11, v14
	s_ashr_i32 s9, s8, 31
	v_ashrrev_i32_e32 v17, 31, v16
	v_ashrrev_i32_e32 v19, 31, v18
	v_ashrrev_i32_e32 v21, 31, v20
	v_ashrrev_i32_e32 v23, 31, v22
	v_ashrrev_i32_e32 v25, 31, v24
	v_ashrrev_i32_e32 v27, 31, v26
	v_ashrrev_i32_e32 v29, 31, v28
	v_ashrrev_i32_e32 v31, 31, v30
	v_lshl_add_u64 v[32:33], s[8:9], 1, v[2:3]
	v_lshlrev_b64 v[16:17], 11, v[16:17]
	v_lshlrev_b64 v[18:19], 11, v[18:19]
	v_lshlrev_b64 v[20:21], 11, v[20:21]
	v_lshlrev_b64 v[22:23], 11, v[22:23]
	v_lshlrev_b64 v[24:25], 11, v[24:25]
	v_lshlrev_b64 v[26:27], 11, v[26:27]
	v_lshlrev_b64 v[28:29], 11, v[28:29]
	v_lshlrev_b64 v[30:31], 11, v[30:31]
	v_lshl_add_u64 v[16:17], v[32:33], 0, v[16:17]
	v_lshl_add_u64 v[18:19], v[32:33], 0, v[18:19]
	v_lshl_add_u64 v[20:21], v[32:33], 0, v[20:21]
	v_lshl_add_u64 v[22:23], v[32:33], 0, v[22:23]
	v_lshl_add_u64 v[24:25], v[32:33], 0, v[24:25]
	v_lshl_add_u64 v[26:27], v[32:33], 0, v[26:27]
	v_lshl_add_u64 v[28:29], v[32:33], 0, v[28:29]
	v_lshl_add_u64 v[30:31], v[32:33], 0, v[30:31]
	s_branch .Lcv334_n0

; __device__ __forceinline__ bf16_t f2bf(float f) { unsigned u = __float_as_uint(f); u += 0x7FFFu + ((u >> 16) & 1u); return (bf16_t)(u >> 16); }
;     ...
;     for (int t_ = first; t_ < ntile * ((REP & 1) + 1); t_ += gridDim.x) { const int t = t_ % ntile;
;         const int r0 = (t / nkt) * 64, k0 = (t % nkt) * 64;
;         __syncthreads();
; #pragma unroll
;         for (int i = 0; i < 8; ++i) { const int kk = i * 8 + w; tile[kk * 65 + lane] = src(k0 + kk, r0 + lane); }
;         __syncthreads();
; #pragma unroll
;         for (int i = 0; i < 8; ++i) { const int j = i * 8 + w; Bt[(size_t)(r0 + j) * ld + k0 + lane] = f2bf(tile[lane * 65 + j]); }
;     }
; __device__ void convert_phase(unsigned char* smem, const Params& p, int l) {
;     ...
;       conv_tiles(tile, wt + W_UP2, 5632, 1024, 53, [=](int k, int r) { const int col = (r >> 5) * 16 + (r & 15); return gn[k] * (((r >> 4) & 1) ? wu[(size_t)k * DFF + col] : wg[(size_t)k * DFF + col]); }); }
.Lcv334_n0:
	s_add_i32 s10, s10, s5
	s_cmp_lt_i32 s10, 0x580
	s_cbranch_scc0 .LBB0_335
	s_waitcnt vmcnt(31)
	v_mul_f32_e32 v72, v74, v82
	s_waitcnt vmcnt(30)
	v_mul_f32_e32 v73, v75, v83
	s_waitcnt vmcnt(29)
	v_mul_f32_e32 v74, v76, v84
	s_waitcnt vmcnt(28)
	v_mul_f32_e32 v75, v77, v85
	s_waitcnt vmcnt(27)
	v_mul_f32_e32 v76, v78, v86
	s_waitcnt vmcnt(26)
	v_mul_f32_e32 v77, v79, v87
	s_waitcnt vmcnt(25)
	v_mul_f32_e32 v78, v80, v88
	s_waitcnt vmcnt(24)
	v_mul_f32_e32 v79, v81, v89
	ds_write_b32 v15, v72 offset:17408
	ds_write_b32 v15, v73 offset:19488
	ds_write_b32 v15, v74 offset:21568
	ds_write_b32 v15, v75 offset:23648
	ds_write_b32 v15, v76 offset:25728
	ds_write_b32 v15, v77 offset:27808
	ds_write_b32 v15, v78 offset:29888
	ds_write_b32 v15, v79 offset:31968
	s_waitcnt lgkmcnt(0)
	s_barrier
	ds_read2_b32 v[72:73], v95 offset1:8
	ds_read2_b32 v[74:75], v95 offset0:16 offset1:24
	ds_read2_b32 v[76:77], v95 offset0:32 offset1:40
	ds_read2_b32 v[78:79], v95 offset0:48 offset1:56
	s_waitcnt lgkmcnt(3)
	v_bfe_u32 v80, v72, 16, 1
	v_bfe_u32 v81, v73, 16, 1
	s_waitcnt lgkmcnt(2)
	v_bfe_u32 v82, v74, 16, 1
	v_bfe_u32 v83, v75, 16, 1
	s_waitcnt lgkmcnt(1)
	v_bfe_u32 v84, v76, 16, 1
	v_bfe_u32 v85, v77, 16, 1
	s_waitcnt lgkmcnt(0)
	v_bfe_u32 v86, v78, 16, 1
	v_bfe_u32 v87, v79, 16, 1
	v_add3_u32 v72, v72, v80, s88
	v_add3_u32 v73, v73, v81, s88
	v_add3_u32 v74, v74, v82, s88
	v_add3_u32 v75, v75, v83, s88
	v_add3_u32 v76, v76, v84, s88
	v_add3_u32 v77, v77, v85, s88
	v_add3_u32 v78, v78, v86, s88
	v_add3_u32 v79, v79, v87, s88
	global_store_short_d16_hi v[56:57], v72, off
	global_store_short_d16_hi v[58:59], v73, off
	global_store_short_d16_hi v[60:61], v74, off
	global_store_short_d16_hi v[62:63], v75, off
	global_store_short_d16_hi v[64:65], v76, off
	global_store_short_d16_hi v[66:67], v77, off
	global_store_short_d16_hi v[68:69], v78, off
	global_store_short_d16_hi v[70:71], v79, off
	s_lshl_b32 s98, s5, 1
	s_add_i32 s98, s98, s10
	s_cmp_lt_i32 s98, 0x580
	s_cbranch_scc0 .Lcv334_s1
	s_lshr_b32 s99, s98, 8
	s_and_b32 s100, s98, 0xff
	s_mul_i32 s101, s100, 6
	s_sub_i32 s98, s100, 128
	s_mul_i32 s98, s98, 5
	s_add_i32 s98, s98, 768
	s_cmp_lt_u32 s100, 128
	s_cselect_b32 s98, s101, s98
	s_add_i32 s98, s98, s99
	s_mul_hi_u32 s99, s98, 0x2e8ba2f
	s_mul_i32 s100, s99, 88
	s_sub_i32 s98, s98, s100
	s_mul_i32 s98, s98, 16
	s_add_i32 s98, s98, s99
	s_mul_hi_i32 s8, s98, 0x2e8ba2e9
	s_lshr_b32 s9, s8, 31
	s_ashr_i32 s8, s8, 8
	s_add_i32 s8, s8, s9
	s_mulk_i32 s8, 0x580
	s_sub_i32 s8, s98, s8
	s_sext_i32_i16 s9, s8
	s_bfe_u32 s9, s9, 0x4001b
	s_add_i32 s9, s8, s9
	s_sext_i32_i16 s11, s9
	s_lshl_b32 s11, s11, 2
	s_and_b32 s9, s9, 0xfff0
	s_andn2_b32 s11, s11, 63
	s_sub_i32 s8, s8, s9
	v_or_b32_e32 v56, s11, v4
	s_sext_i32_i16 s8, s8
	v_ashrrev_i32_e32 v57, 1, v56
	s_lshl_b32 s8, s8, 6
	v_and_or_b32 v58, v57, -16, v6
	v_add_u32_e32 v56, s8, v5
	v_ashrrev_i32_e32 v59, 31, v58
	v_ashrrev_i32_e32 v57, 31, v56
	v_lshl_add_u64 v[58:59], v[58:59], 2, v[0:1]
	v_add_u32_e32 v62, s8, v8
	v_add_u32_e32 v63, s8, v9
	v_add_u32_e32 v64, s8, v10
	v_add_u32_e32 v66, s8, v11
	v_add_u32_e32 v68, s8, v12
	v_add_u32_e32 v70, s8, v13
	v_add_u32_e32 v72, s8, v14
	v_lshl_add_u64 v[60:61], v[56:57], 2, s[6:7]
	v_mad_i64_i32 v[56:57], s[16:17], v56, s33, v[58:59]
	global_load_dword v74, v[60:61], off
	global_load_dword v75, v[60:61], off offset:32
	global_load_dword v76, v[60:61], off offset:64
	global_load_dword v77, v[60:61], off offset:96
	global_load_dword v78, v[60:61], off offset:128
	global_load_dword v79, v[60:61], off offset:160
	global_load_dword v80, v[60:61], off offset:192
	global_load_dword v81, v[60:61], off offset:224
	v_mad_i64_i32 v[60:61], s[16:17], v62, s33, v[58:59]
	v_mad_i64_i32 v[62:63], s[16:17], v63, s33, v[58:59]
	v_mad_i64_i32 v[64:65], s[16:17], v64, s33, v[58:59]
	v_mad_i64_i32 v[66:67], s[16:17], v66, s33, v[58:59]
	v_mad_i64_i32 v[68:69], s[16:17], v68, s33, v[58:59]
	v_mad_i64_i32 v[70:71], s[16:17], v70, s33, v[58:59]
	v_mad_i64_i32 v[58:59], s[16:17], v72, s33, v[58:59]
	global_load_dword v82, v[56:57], off
	global_load_dword v83, v[60:61], off
	global_load_dword v84, v[62:63], off
	global_load_dword v85, v[64:65], off
	global_load_dword v86, v[66:67], off
	global_load_dword v87, v[68:69], off
	global_load_dword v88, v[70:71], off
	global_load_dword v89, v[58:59], off
	v_add_u32_e32 v56, s11, v5
	v_add_u32_e32 v58, s11, v8
	v_add_u32_e32 v60, s11, v9
	v_add_u32_e32 v62, s11, v10
	v_add_u32_e32 v64, s11, v11
	v_add_u32_e32 v66, s11, v12
	v_add_u32_e32 v68, s11, v13
	v_add_u32_e32 v70, s11, v14
	s_ashr_i32 s9, s8, 31
	v_ashrrev_i32_e32 v57, 31, v56
	v_ashrrev_i32_e32 v59, 31, v58
	v_ashrrev_i32_e32 v61, 31, v60
	v_ashrrev_i32_e32 v63, 31, v62
	v_ashrrev_i32_e32 v65, 31, v64
	v_ashrrev_i32_e32 v67, 31, v66
	v_ashrrev_i32_e32 v69, 31, v68
	v_ashrrev_i32_e32 v71, 31, v70
	v_lshl_add_u64 v[72:73], s[8:9], 1, v[2:3]
	v_lshlrev_b64 v[56:57], 11, v[56:57]
	v_lshlrev_b64 v[58:59], 11, v[58:59]
	v_lshlrev_b64 v[60:61], 11, v[60:61]
	v_lshlrev_b64 v[62:63], 11, v[62:63]
	v_lshlrev_b64 v[64:65], 11, v[64:65]
	v_lshlrev_b64 v[66:67], 11, v[66:67]
	v_lshlrev_b64 v[68:69], 11, v[68:69]
	v_lshlrev_b64 v[70:71], 11, v[70:71]
	v_lshl_add_u64 v[56:57], v[72:73], 0, v[56:57]
	v_lshl_add_u64 v[58:59], v[72:73], 0, v[58:59]
	v_lshl_add_u64 v[60:61], v[72:73], 0, v[60:61]
	v_lshl_add_u64 v[62:63], v[72:73], 0, v[62:63]
	v_lshl_add_u64 v[64:65], v[72:73], 0, v[64:65]
	v_lshl_add_u64 v[66:67], v[72:73], 0, v[66:67]
	v_lshl_add_u64 v[68:69], v[72:73], 0, v[68:69]
	v_lshl_add_u64 v[70:71], v[72:73], 0, v[70:71]
	s_branch .Lcv334_n1

; __device__ __forceinline__ bf16_t f2bf(float f) { unsigned u = __float_as_uint(f); u += 0x7FFFu + ((u >> 16) & 1u); return (bf16_t)(u >> 16); }
;     ...
;     for (int t_ = first; t_ < ntile * ((REP & 1) + 1); t_ += gridDim.x) { const int t = t_ % ntile;
;         const int r0 = (t / nkt) * 64, k0 = (t % nkt) * 64;
;         __syncthreads();
; #pragma unroll
;         for (int i = 0; i < 8; ++i) { const int kk = i * 8 + w; tile[kk * 65 + lane] = src(k0 + kk, r0 + lane); }
;         __syncthreads();
; #pragma unroll
;         for (int i = 0; i < 8; ++i) { const int j = i * 8 + w; Bt[(size_t)(r0 + j) * ld + k0 + lane] = f2bf(tile[lane * 65 + j]); }
;     }
; __device__ void convert_phase(unsigned char* smem, const Params& p, int l) {
;     ...
;     { const float* wd = ((const float*)ldp(35)) + uo; conv_tiles(tile, wt + W_DN2, 1024, 2816, 97, [=](int k, int r) { return wd[(size_t)k * DM + r]; }); }
.LBB0_337:
	s_mov_b32 s98, s10
	s_lshr_b32 s99, s98, 8
	s_and_b32 s100, s98, 0xff
	s_mul_i32 s101, s100, 3
	s_sub_i32 s98, s100, 192
	s_mul_i32 s98, s98, 2
	s_add_i32 s98, s98, 576
	s_cmp_lt_u32 s100, 192
	s_cselect_b32 s98, s101, s98
	s_add_i32 s98, s98, s99
	s_mul_hi_u32 s99, s98, 0x10000001
	s_mul_i32 s100, s99, 16
	s_sub_i32 s98, s98, s100
	s_mul_i32 s98, s98, 44
	s_add_i32 s98, s98, s99
	s_mul_hi_i32 s8, s98, 0x2e8ba2e9
	s_lshr_b32 s9, s8, 31
	s_ashr_i32 s8, s8, 7
	s_add_i32 s8, s8, s9
	s_mulk_i32 s8, 0x2c0
	s_sub_i32 s8, s98, s8
	s_sext_i32_i16 s9, s8
	s_mulk_i32 s9, 0xba3
	s_lshr_b32 s11, s9, 31
	s_ashr_i32 s9, s9, 17
	s_add_i32 s9, s9, s11
	s_sext_i32_i16 s11, s9
	s_mul_i32 s9, s9, 44
	s_sub_i32 s8, s8, s9
	s_sext_i32_i16 s8, s8
	s_lshl_b32 s11, s11, 6
	s_lshl_b32 s8, s8, 6
	v_or_b32_e32 v14, s11, v2
	v_add_u32_e32 v16, s8, v3
	v_ashrrev_i32_e32 v15, 31, v14
	v_add_u32_e32 v18, s8, v5
	v_add_u32_e32 v20, s8, v6
	v_add_u32_e32 v22, s8, v7
	v_add_u32_e32 v24, s8, v8
	v_add_u32_e32 v26, s8, v9
	v_add_u32_e32 v28, s8, v10
	v_add_u32_e32 v30, s8, v11
	v_ashrrev_i32_e32 v17, 31, v16
	v_lshl_add_u64 v[14:15], v[14:15], 2, s[6:7]
	v_ashrrev_i32_e32 v19, 31, v18
	v_ashrrev_i32_e32 v21, 31, v20
	v_ashrrev_i32_e32 v23, 31, v22
	v_ashrrev_i32_e32 v25, 31, v24
	v_ashrrev_i32_e32 v27, 31, v26
	v_ashrrev_i32_e32 v29, 31, v28
	v_ashrrev_i32_e32 v31, 31, v30
	v_lshlrev_b64 v[16:17], 12, v[16:17]
	v_lshlrev_b64 v[18:19], 12, v[18:19]
	v_lshlrev_b64 v[20:21], 12, v[20:21]
	v_lshlrev_b64 v[22:23], 12, v[22:23]
	v_lshlrev_b64 v[24:25], 12, v[24:25]
	v_lshlrev_b64 v[26:27], 12, v[26:27]
	v_lshlrev_b64 v[28:29], 12, v[28:29]
	v_lshlrev_b64 v[30:31], 12, v[30:31]
	v_lshl_add_u64 v[16:17], v[14:15], 0, v[16:17]
	v_lshl_add_u64 v[18:19], v[14:15], 0, v[18:19]
	v_lshl_add_u64 v[20:21], v[14:15], 0, v[20:21]
	v_lshl_add_u64 v[22:23], v[14:15], 0, v[22:23]
	v_lshl_add_u64 v[24:25], v[14:15], 0, v[24:25]
	v_lshl_add_u64 v[26:27], v[14:15], 0, v[26:27]
	v_lshl_add_u64 v[28:29], v[14:15], 0, v[28:29]
	v_lshl_add_u64 v[14:15], v[14:15], 0, v[30:31]
	global_load_dword v13, v[16:17], off
	global_load_dword v30, v[18:19], off
	global_load_dword v31, v[20:21], off
	global_load_dword v32, v[22:23], off
	global_load_dword v33, v[24:25], off
	global_load_dword v34, v[26:27], off
	global_load_dword v35, v[28:29], off
	global_load_dword v36, v[14:15], off
	s_ashr_i32 s9, s8, 31
	v_add_u32_e32 v16, s11, v3
	v_add_u32_e32 v18, s11, v5
	v_add_u32_e32 v20, s11, v6
	v_add_u32_e32 v22, s11, v7
	v_add_u32_e32 v24, s11, v8
	v_add_u32_e32 v26, s11, v9
	v_add_u32_e32 v28, s11, v10
	v_add_u32_e32 v37, s11, v11
	v_lshl_add_u64 v[14:15], s[8:9], 1, v[0:1]
	v_mad_i64_i32 v[16:17], s[8:9], v16, s54, v[14:15]
	v_mad_i64_i32 v[18:19], s[8:9], v18, s54, v[14:15]
	v_mad_i64_i32 v[20:21], s[8:9], v20, s54, v[14:15]
	v_mad_i64_i32 v[22:23], s[8:9], v22, s54, v[14:15]
	v_mad_i64_i32 v[24:25], s[8:9], v24, s54, v[14:15]
	v_mad_i64_i32 v[26:27], s[8:9], v26, s54, v[14:15]
	v_mad_i64_i32 v[28:29], s[8:9], v28, s54, v[14:15]
	v_mad_i64_i32 v[14:15], s[8:9], v37, s54, v[14:15]
	s_add_i32 s98, s10, s5
	s_cmp_lt_i32 s98, 0x2c0
	s_cbranch_scc0 .Lcv337_p1skip
	s_lshr_b32 s99, s98, 8
	s_and_b32 s100, s98, 0xff
	s_mul_i32 s101, s100, 3
	s_sub_i32 s98, s100, 192
	s_mul_i32 s98, s98, 2
	s_add_i32 s98, s98, 576
	s_cmp_lt_u32 s100, 192
	s_cselect_b32 s98, s101, s98
	s_add_i32 s98, s98, s99
	s_mul_hi_u32 s99, s98, 0x10000001
	s_mul_i32 s100, s99, 16
	s_sub_i32 s98, s98, s100
	s_mul_i32 s98, s98, 44
	s_add_i32 s98, s98, s99
	s_mul_hi_i32 s8, s98, 0x2e8ba2e9
	s_lshr_b32 s9, s8, 31
	s_ashr_i32 s8, s8, 7
	s_add_i32 s8, s8, s9
	s_mulk_i32 s8, 0x2c0
	s_sub_i32 s8, s98, s8
	s_sext_i32_i16 s9, s8
	s_mulk_i32 s9, 0xba3
	s_lshr_b32 s11, s9, 31
	s_ashr_i32 s9, s9, 17
	s_add_i32 s9, s9, s11
	s_sext_i32_i16 s11, s9
	s_mul_i32 s9, s9, 44
	s_sub_i32 s8, s8, s9
	s_sext_i32_i16 s8, s8
	s_lshl_b32 s11, s11, 6
	s_lshl_b32 s8, s8, 6
	v_or_b32_e32 v54, s11, v2
	v_add_u32_e32 v56, s8, v3
	v_ashrrev_i32_e32 v55, 31, v54
	v_add_u32_e32 v58, s8, v5
	v_add_u32_e32 v60, s8, v6
	v_add_u32_e32 v62, s8, v7
	v_add_u32_e32 v64, s8, v8
	v_add_u32_e32 v66, s8, v9
	v_add_u32_e32 v68, s8, v10
	v_add_u32_e32 v70, s8, v11
	v_ashrrev_i32_e32 v57, 31, v56
	v_lshl_add_u64 v[54:55], v[54:55], 2, s[6:7]
	v_ashrrev_i32_e32 v59, 31, v58
	v_ashrrev_i32_e32 v61, 31, v60
	v_ashrrev_i32_e32 v63, 31, v62
	v_ashrrev_i32_e32 v65, 31, v64
	v_ashrrev_i32_e32 v67, 31, v66
	v_ashrrev_i32_e32 v69, 31, v68
	v_ashrrev_i32_e32 v71, 31, v70
	v_lshlrev_b64 v[56:57], 12, v[56:57]
	v_lshlrev_b64 v[58:59], 12, v[58:59]
	v_lshlrev_b64 v[60:61], 12, v[60:61]
	v_lshlrev_b64 v[62:63], 12, v[62:63]
	v_lshlrev_b64 v[64:65], 12, v[64:65]
	v_lshlrev_b64 v[66:67], 12, v[66:67]
	v_lshlrev_b64 v[68:69], 12, v[68:69]
	v_lshlrev_b64 v[70:71], 12, v[70:71]
	v_lshl_add_u64 v[56:57], v[54:55], 0, v[56:57]
	v_lshl_add_u64 v[58:59], v[54:55], 0, v[58:59]
	v_lshl_add_u64 v[60:61], v[54:55], 0, v[60:61]
	v_lshl_add_u64 v[62:63], v[54:55], 0, v[62:63]
	v_lshl_add_u64 v[64:65], v[54:55], 0, v[64:65]
	v_lshl_add_u64 v[66:67], v[54:55], 0, v[66:67]
	v_lshl_add_u64 v[68:69], v[54:55], 0, v[68:69]
	v_lshl_add_u64 v[54:55], v[54:55], 0, v[70:71]
	global_load_dword v53, v[56:57], off
	global_load_dword v70, v[58:59], off
	global_load_dword v71, v[60:61], off
	global_load_dword v72, v[62:63], off
	global_load_dword v73, v[64:65], off
	global_load_dword v74, v[66:67], off
	global_load_dword v75, v[68:69], off
	global_load_dword v76, v[54:55], off
	s_ashr_i32 s9, s8, 31
	v_add_u32_e32 v56, s11, v3
	v_add_u32_e32 v58, s11, v5
	v_add_u32_e32 v60, s11, v6
	v_add_u32_e32 v62, s11, v7
	v_add_u32_e32 v64, s11, v8
	v_add_u32_e32 v66, s11, v9
	v_add_u32_e32 v68, s11, v10
	v_add_u32_e32 v77, s11, v11
	v_lshl_add_u64 v[54:55], s[8:9], 1, v[0:1]
	v_mad_i64_i32 v[56:57], s[8:9], v56, s54, v[54:55]
	v_mad_i64_i32 v[58:59], s[8:9], v58, s54, v[54:55]
	v_mad_i64_i32 v[60:61], s[8:9], v60, s54, v[54:55]
	v_mad_i64_i32 v[62:63], s[8:9], v62, s54, v[54:55]
	v_mad_i64_i32 v[64:65], s[8:9], v64, s54, v[54:55]
	v_mad_i64_i32 v[66:67], s[8:9], v66, s54, v[54:55]
	v_mad_i64_i32 v[68:69], s[8:9], v68, s54, v[54:55]
	v_mad_i64_i32 v[54:55], s[8:9], v77, s54, v[54:55]
	s_waitcnt vmcnt(8)
	s_branch .Lcv337_pj

; __device__ __forceinline__ bf16_t f2bf(float f) { unsigned u = __float_as_uint(f); u += 0x7FFFu + ((u >> 16) & 1u); return (bf16_t)(u >> 16); }
;     ...
;     for (int t_ = first; t_ < ntile * ((REP & 1) + 1); t_ += gridDim.x) { const int t = t_ % ntile;
;         const int r0 = (t / nkt) * 64, k0 = (t % nkt) * 64;
;         __syncthreads();
; #pragma unroll
;         for (int i = 0; i < 8; ++i) { const int kk = i * 8 + w; tile[kk * 65 + lane] = src(k0 + kk, r0 + lane); }
;         __syncthreads();
; #pragma unroll
;         for (int i = 0; i < 8; ++i) { const int j = i * 8 + w; Bt[(size_t)(r0 + j) * ld + k0 + lane] = f2bf(tile[lane * 65 + j]); }
;     }
; __device__ void convert_phase(unsigned char* smem, const Params& p, int l) {
;     ...
;     { const float* wd = ((const float*)ldp(35)) + uo; conv_tiles(tile, wt + W_DN2, 1024, 2816, 97, [=](int k, int r) { return wd[(size_t)k * DM + r]; }); }
.Lcv337_top:
	s_waitcnt vmcnt(23)
	ds_write_b32 v12, v13
	s_waitcnt vmcnt(22)
	ds_write_b32 v12, v30 offset:2080
	s_waitcnt vmcnt(21)
	ds_write_b32 v12, v31 offset:4160
	s_waitcnt vmcnt(20)
	ds_write_b32 v12, v32 offset:6240
	s_waitcnt vmcnt(19)
	ds_write_b32 v12, v33 offset:8320
	s_waitcnt vmcnt(18)
	ds_write_b32 v12, v34 offset:10400
	s_waitcnt vmcnt(17)
	ds_write_b32 v12, v35 offset:12480
	s_waitcnt vmcnt(16)
	ds_write_b32 v12, v36 offset:14560
	s_waitcnt lgkmcnt(0)
	s_barrier
	ds_read2_b32 v[30:31], v4 offset1:8
	ds_read2_b32 v[32:33], v4 offset0:16 offset1:24
	ds_read2_b32 v[34:35], v4 offset0:32 offset1:40
	ds_read2_b32 v[36:37], v4 offset0:48 offset1:56
	s_waitcnt lgkmcnt(3)
	v_bfe_u32 v13, v30, 16, 1
	v_bfe_u32 v38, v31, 16, 1
	s_waitcnt lgkmcnt(2)
	v_bfe_u32 v39, v32, 16, 1
	v_bfe_u32 v40, v33, 16, 1
	s_waitcnt lgkmcnt(1)
	v_bfe_u32 v41, v34, 16, 1
	v_bfe_u32 v42, v35, 16, 1
	s_waitcnt lgkmcnt(0)
	v_bfe_u32 v43, v36, 16, 1
	v_bfe_u32 v44, v37, 16, 1
	v_add3_u32 v13, v30, v13, s88
	v_add3_u32 v30, v31, v38, s88
	v_add3_u32 v31, v32, v39, s88
	v_add3_u32 v32, v33, v40, s88
	v_add3_u32 v33, v34, v41, s88
	v_add3_u32 v34, v35, v42, s88
	v_add3_u32 v35, v36, v43, s88
	v_add3_u32 v36, v37, v44, s88
	global_store_short_d16_hi v[16:17], v13, off
	global_store_short_d16_hi v[18:19], v30, off
	global_store_short_d16_hi v[20:21], v31, off
	global_store_short_d16_hi v[22:23], v32, off
	global_store_short_d16_hi v[24:25], v33, off
	global_store_short_d16_hi v[26:27], v34, off
	global_store_short_d16_hi v[28:29], v35, off
	global_store_short_d16_hi v[14:15], v36, off
	s_lshl_b32 s98, s5, 1
	s_add_i32 s98, s98, s10
	s_cmp_lt_i32 s98, 0x2c0
	s_cbranch_scc0 .Lcv337_s0
	s_lshr_b32 s99, s98, 8
	s_and_b32 s100, s98, 0xff
	s_mul_i32 s101, s100, 3
	s_sub_i32 s98, s100, 192
	s_mul_i32 s98, s98, 2
	s_add_i32 s98, s98, 576
	s_cmp_lt_u32 s100, 192
	s_cselect_b32 s98, s101, s98
	s_add_i32 s98, s98, s99
	s_mul_hi_u32 s99, s98, 0x10000001
	s_mul_i32 s100, s99, 16
	s_sub_i32 s98, s98, s100
	s_mul_i32 s98, s98, 44
	s_add_i32 s98, s98, s99
	s_mul_hi_i32 s8, s98, 0x2e8ba2e9
	s_lshr_b32 s9, s8, 31
	s_ashr_i32 s8, s8, 7
	s_add_i32 s8, s8, s9
	s_mulk_i32 s8, 0x2c0
	s_sub_i32 s8, s98, s8
	s_sext_i32_i16 s9, s8
	s_mulk_i32 s9, 0xba3
	s_lshr_b32 s11, s9, 31
	s_ashr_i32 s9, s9, 17
	s_add_i32 s9, s9, s11
	s_sext_i32_i16 s11, s9
	s_mul_i32 s9, s9, 44
	s_sub_i32 s8, s8, s9
	s_sext_i32_i16 s8, s8
	s_lshl_b32 s11, s11, 6
	s_lshl_b32 s8, s8, 6
	v_or_b32_e32 v14, s11, v2
	v_add_u32_e32 v16, s8, v3
	v_ashrrev_i32_e32 v15, 31, v14
	v_add_u32_e32 v18, s8, v5
	v_add_u32_e32 v20, s8, v6
	v_add_u32_e32 v22, s8, v7
	v_add_u32_e32 v24, s8, v8
	v_add_u32_e32 v26, s8, v9
	v_add_u32_e32 v28, s8, v10
	v_add_u32_e32 v30, s8, v11
	v_ashrrev_i32_e32 v17, 31, v16
	v_lshl_add_u64 v[14:15], v[14:15], 2, s[6:7]
	v_ashrrev_i32_e32 v19, 31, v18
	v_ashrrev_i32_e32 v21, 31, v20
	v_ashrrev_i32_e32 v23, 31, v22
	v_ashrrev_i32_e32 v25, 31, v24
	v_ashrrev_i32_e32 v27, 31, v26
	v_ashrrev_i32_e32 v29, 31, v28
	v_ashrrev_i32_e32 v31, 31, v30
	v_lshlrev_b64 v[16:17], 12, v[16:17]
	v_lshlrev_b64 v[18:19], 12, v[18:19]
	v_lshlrev_b64 v[20:21], 12, v[20:21]
	v_lshlrev_b64 v[22:23], 12, v[22:23]
	v_lshlrev_b64 v[24:25], 12, v[24:25]
	v_lshlrev_b64 v[26:27], 12, v[26:27]
	v_lshlrev_b64 v[28:29], 12, v[28:29]
	v_lshlrev_b64 v[30:31], 12, v[30:31]
	v_lshl_add_u64 v[16:17], v[14:15], 0, v[16:17]
	v_lshl_add_u64 v[18:19], v[14:15], 0, v[18:19]
	v_lshl_add_u64 v[20:21], v[14:15], 0, v[20:21]
	v_lshl_add_u64 v[22:23], v[14:15], 0, v[22:23]
	v_lshl_add_u64 v[24:25], v[14:15], 0, v[24:25]
	v_lshl_add_u64 v[26:27], v[14:15], 0, v[26:27]
	v_lshl_add_u64 v[28:29], v[14:15], 0, v[28:29]
	v_lshl_add_u64 v[14:15], v[14:15], 0, v[30:31]
	global_load_dword v13, v[16:17], off
	global_load_dword v30, v[18:19], off
	global_load_dword v31, v[20:21], off
	global_load_dword v32, v[22:23], off
	global_load_dword v33, v[24:25], off
	global_load_dword v34, v[26:27], off
	global_load_dword v35, v[28:29], off
	global_load_dword v36, v[14:15], off
	s_ashr_i32 s9, s8, 31
	v_add_u32_e32 v16, s11, v3
	v_add_u32_e32 v18, s11, v5
	v_add_u32_e32 v20, s11, v6
	v_add_u32_e32 v22, s11, v7
	v_add_u32_e32 v24, s11, v8
	v_add_u32_e32 v26, s11, v9
	v_add_u32_e32 v28, s11, v10
	v_add_u32_e32 v37, s11, v11
	v_lshl_add_u64 v[14:15], s[8:9], 1, v[0:1]
	v_mad_i64_i32 v[16:17], s[8:9], v16, s54, v[14:15]
	v_mad_i64_i32 v[18:19], s[8:9], v18, s54, v[14:15]
	v_mad_i64_i32 v[20:21], s[8:9], v20, s54, v[14:15]
	v_mad_i64_i32 v[22:23], s[8:9], v22, s54, v[14:15]
	v_mad_i64_i32 v[24:25], s[8:9], v24, s54, v[14:15]
	v_mad_i64_i32 v[26:27], s[8:9], v26, s54, v[14:15]
	v_mad_i64_i32 v[28:29], s[8:9], v28, s54, v[14:15]
	v_mad_i64_i32 v[14:15], s[8:9], v37, s54, v[14:15]
	s_branch .Lcv337_n0

; __device__ __forceinline__ bf16_t f2bf(float f) { unsigned u = __float_as_uint(f); u += 0x7FFFu + ((u >> 16) & 1u); return (bf16_t)(u >> 16); }
;     ...
;     for (int t_ = first; t_ < ntile * ((REP & 1) + 1); t_ += gridDim.x) { const int t = t_ % ntile;
;         const int r0 = (t / nkt) * 64, k0 = (t % nkt) * 64;
;         __syncthreads();
; #pragma unroll
;         for (int i = 0; i < 8; ++i) { const int kk = i * 8 + w; tile[kk * 65 + lane] = src(k0 + kk, r0 + lane); }
;         __syncthreads();
; #pragma unroll
;         for (int i = 0; i < 8; ++i) { const int j = i * 8 + w; Bt[(size_t)(r0 + j) * ld + k0 + lane] = f2bf(tile[lane * 65 + j]); }
;     }
; __device__ void convert_phase(unsigned char* smem, const Params& p, int l) {
;     ...
;     { const float* wd = ((const float*)ldp(35)) + uo; conv_tiles(tile, wt + W_DN2, 1024, 2816, 97, [=](int k, int r) { return wd[(size_t)k * DM + r]; }); }
.Lcv337_n0:
	s_add_i32 s10, s10, s5
	s_cmp_lt_i32 s10, 0x2c0
	s_cbranch_scc0 .LBB0_338
	s_waitcnt vmcnt(23)
	ds_write_b32 v12, v53 offset:17408
	s_waitcnt vmcnt(22)
	ds_write_b32 v12, v70 offset:19488
	s_waitcnt vmcnt(21)
	ds_write_b32 v12, v71 offset:21568
	s_waitcnt vmcnt(20)
	ds_write_b32 v12, v72 offset:23648
	s_waitcnt vmcnt(19)
	ds_write_b32 v12, v73 offset:25728
	s_waitcnt vmcnt(18)
	ds_write_b32 v12, v74 offset:27808
	s_waitcnt vmcnt(17)
	ds_write_b32 v12, v75 offset:29888
	s_waitcnt vmcnt(16)
	ds_write_b32 v12, v76 offset:31968
	s_waitcnt lgkmcnt(0)
	s_barrier
	ds_read2_b32 v[70:71], v95 offset1:8
	ds_read2_b32 v[72:73], v95 offset0:16 offset1:24
	ds_read2_b32 v[74:75], v95 offset0:32 offset1:40
	ds_read2_b32 v[76:77], v95 offset0:48 offset1:56
	s_waitcnt lgkmcnt(3)
	v_bfe_u32 v53, v70, 16, 1
	v_bfe_u32 v78, v71, 16, 1
	s_waitcnt lgkmcnt(2)
	v_bfe_u32 v79, v72, 16, 1
	v_bfe_u32 v80, v73, 16, 1
	s_waitcnt lgkmcnt(1)
	v_bfe_u32 v81, v74, 16, 1
	v_bfe_u32 v82, v75, 16, 1
	s_waitcnt lgkmcnt(0)
	v_bfe_u32 v83, v76, 16, 1
	v_bfe_u32 v84, v77, 16, 1
	v_add3_u32 v53, v70, v53, s88
	v_add3_u32 v70, v71, v78, s88
	v_add3_u32 v71, v72, v79, s88
	v_add3_u32 v72, v73, v80, s88
	v_add3_u32 v73, v74, v81, s88
	v_add3_u32 v74, v75, v82, s88
	v_add3_u32 v75, v76, v83, s88
	v_add3_u32 v76, v77, v84, s88
	global_store_short_d16_hi v[56:57], v53, off
	global_store_short_d16_hi v[58:59], v70, off
	global_store_short_d16_hi v[60:61], v71, off
	global_store_short_d16_hi v[62:63], v72, off
	global_store_short_d16_hi v[64:65], v73, off
	global_store_short_d16_hi v[66:67], v74, off
	global_store_short_d16_hi v[68:69], v75, off
	global_store_short_d16_hi v[54:55], v76, off
	s_lshl_b32 s98, s5, 1
	s_add_i32 s98, s98, s10
	s_cmp_lt_i32 s98, 0x2c0
	s_cbranch_scc0 .Lcv337_s1
	s_lshr_b32 s99, s98, 8
	s_and_b32 s100, s98, 0xff
	s_mul_i32 s101, s100, 3
	s_sub_i32 s98, s100, 192
	s_mul_i32 s98, s98, 2
	s_add_i32 s98, s98, 576
	s_cmp_lt_u32 s100, 192
	s_cselect_b32 s98, s101, s98
	s_add_i32 s98, s98, s99
	s_mul_hi_u32 s99, s98, 0x10000001
	s_mul_i32 s100, s99, 16
	s_sub_i32 s98, s98, s100
	s_mul_i32 s98, s98, 44
	s_add_i32 s98, s98, s99
	s_mul_hi_i32 s8, s98, 0x2e8ba2e9
	s_lshr_b32 s9, s8, 31
	s_ashr_i32 s8, s8, 7
	s_add_i32 s8, s8, s9
	s_mulk_i32 s8, 0x2c0
	s_sub_i32 s8, s98, s8
	s_sext_i32_i16 s9, s8
	s_mulk_i32 s9, 0xba3
	s_lshr_b32 s11, s9, 31
	s_ashr_i32 s9, s9, 17
	s_add_i32 s9, s9, s11
	s_sext_i32_i16 s11, s9
	s_mul_i32 s9, s9, 44
	s_sub_i32 s8, s8, s9
	s_sext_i32_i16 s8, s8
	s_lshl_b32 s11, s11, 6
	s_lshl_b32 s8, s8, 6
	v_or_b32_e32 v54, s11, v2
	v_add_u32_e32 v56, s8, v3
	v_ashrrev_i32_e32 v55, 31, v54
	v_add_u32_e32 v58, s8, v5
	v_add_u32_e32 v60, s8, v6
	v_add_u32_e32 v62, s8, v7
	v_add_u32_e32 v64, s8, v8
	v_add_u32_e32 v66, s8, v9
	v_add_u32_e32 v68, s8, v10
	v_add_u32_e32 v70, s8, v11
	v_ashrrev_i32_e32 v57, 31, v56
	v_lshl_add_u64 v[54:55], v[54:55], 2, s[6:7]
	v_ashrrev_i32_e32 v59, 31, v58
	v_ashrrev_i32_e32 v61, 31, v60
	v_ashrrev_i32_e32 v63, 31, v62
	v_ashrrev_i32_e32 v65, 31, v64
	v_ashrrev_i32_e32 v67, 31, v66
	v_ashrrev_i32_e32 v69, 31, v68
	v_ashrrev_i32_e32 v71, 31, v70
	v_lshlrev_b64 v[56:57], 12, v[56:57]
	v_lshlrev_b64 v[58:59], 12, v[58:59]
	v_lshlrev_b64 v[60:61], 12, v[60:61]
	v_lshlrev_b64 v[62:63], 12, v[62:63]
	v_lshlrev_b64 v[64:65], 12, v[64:65]
	v_lshlrev_b64 v[66:67], 12, v[66:67]
	v_lshlrev_b64 v[68:69], 12, v[68:69]
	v_lshlrev_b64 v[70:71], 12, v[70:71]
	v_lshl_add_u64 v[56:57], v[54:55], 0, v[56:57]
	v_lshl_add_u64 v[58:59], v[54:55], 0, v[58:59]
	v_lshl_add_u64 v[60:61], v[54:55], 0, v[60:61]
	v_lshl_add_u64 v[62:63], v[54:55], 0, v[62:63]
	v_lshl_add_u64 v[64:65], v[54:55], 0, v[64:65]
	v_lshl_add_u64 v[66:67], v[54:55], 0, v[66:67]
	v_lshl_add_u64 v[68:69], v[54:55], 0, v[68:69]
	v_lshl_add_u64 v[54:55], v[54:55], 0, v[70:71]
	global_load_dword v53, v[56:57], off
	global_load_dword v70, v[58:59], off
	global_load_dword v71, v[60:61], off
	global_load_dword v72, v[62:63], off
	global_load_dword v73, v[64:65], off
	global_load_dword v74, v[66:67], off
	global_load_dword v75, v[68:69], off
	global_load_dword v76, v[54:55], off
	s_ashr_i32 s9, s8, 31
	v_add_u32_e32 v56, s11, v3
	v_add_u32_e32 v58, s11, v5
	v_add_u32_e32 v60, s11, v6
	v_add_u32_e32 v62, s11, v7
	v_add_u32_e32 v64, s11, v8
	v_add_u32_e32 v66, s11, v9
	v_add_u32_e32 v68, s11, v10
	v_add_u32_e32 v77, s11, v11
	v_lshl_add_u64 v[54:55], s[8:9], 1, v[0:1]
	v_mad_i64_i32 v[56:57], s[8:9], v56, s54, v[54:55]
	v_mad_i64_i32 v[58:59], s[8:9], v58, s54, v[54:55]
	v_mad_i64_i32 v[60:61], s[8:9], v60, s54, v[54:55]
	v_mad_i64_i32 v[62:63], s[8:9], v62, s54, v[54:55]
	v_mad_i64_i32 v[64:65], s[8:9], v64, s54, v[54:55]
	v_mad_i64_i32 v[66:67], s[8:9], v66, s54, v[54:55]
	v_mad_i64_i32 v[68:69], s[8:9], v68, s54, v[54:55]
	v_mad_i64_i32 v[54:55], s[8:9], v77, s54, v[54:55]
	s_branch .Lcv337_n1
